# stack of small edits: drain-skip in residual GEMMs, hoisted B-fragment LDS addresses, counted P.V waits, Q.K^T chains
# speedup vs baseline: 1.0047x; 1.0003x over previous
.LBB0_296:
	s_ashr_i32 s23, s22, 31
	s_lshl_b64 s[56:57], s[22:23], 21
	s_add_u32 s72, s2, s56
	s_addc_u32 s73, s3, s57
	s_and_b64 s[56:57], s[4:5], exec
	s_cselect_b32 s23, s73, s81
	s_cselect_b32 s56, s72, s80
	s_ashr_i32 s21, s20, 31
	s_lshl_b64 s[60:61], s[20:21], 20
	s_add_u32 s74, s14, s60
	s_addc_u32 s75, s15, s61
	s_and_b64 s[60:61], s[4:5], exec
	s_cselect_b32 s21, s75, s83
	s_cselect_b32 s57, s74, s82
	s_add_u32 s80, s80, 0x100080
	s_addc_u32 s81, s81, 0
	s_add_u32 s60, s82, 0x100
	s_addc_u32 s61, s83, 0
	s_mov_b32 s68, -2
	v_add_u32_e32 v145, 0x10000, v168
	s_add_u32 s67, s80, 0xfff00080
	s_addc_u32 s69, s81, -1
	s_add_i32 s70, 0, 0x10000
	s_cmp_eq_u32 s68, 28
	s_cselect_b32 s85, s23, s69
	s_cselect_b32 s84, s56, s67
	s_cselect_b32 s83, s21, s61
	s_cselect_b32 s82, s57, s60
	s_add_i32 s67, 0, 0x14000
	ds_read_b128 v[80:83], v145
	ds_read_b128 v[116:119], v145 offset:1024
	ds_read_b128 v[136:139], v145 offset:2048
	ds_read_b128 v[140:143], v145 offset:3072
	ds_read_b128 v[158:161], v145 offset:16384
	ds_read_b128 v[162:165], v145 offset:17408
	ds_read_b128 v[170:173], v145 offset:18432
	ds_read_b128 v[174:177], v145 offset:19456
	s_add_i32 m0, s26, 0xc000
	ds_read_b128 v[178:181], v169
	ds_read_b128 v[182:185], v169 offset:1024
	ds_read_b128 v[186:189], v169 offset:2048
	ds_read_b128 v[190:193], v169 offset:3072
	ds_read_b128 v[194:197], v169 offset:4096
	ds_read_b128 v[198:201], v169 offset:5120
	ds_read_b128 v[202:205], v169 offset:6144
	ds_read_b128 v[206:209], v169 offset:7168
	global_load_lds_dwordx4 v154, s[80:81]
	s_add_i32 m0, s26, 0xe000
	s_nop 0
	global_load_lds_dwordx4 v156, s[80:81]
	s_waitcnt vmcnt(8)
	s_waitcnt lgkmcnt(0)
	s_barrier
	s_waitcnt lgkmcnt(0)
	v_mfma_f32_16x16x32_bf16 v[132:135], v[80:83], v[178:181], 0
	v_mfma_f32_16x16x32_bf16 v[132:135], v[116:119], v[182:185], v[132:135]
	v_mfma_f32_16x16x32_bf16 v[124:127], v[158:161], v[178:181], 0
	v_mfma_f32_16x16x32_bf16 v[124:127], v[162:165], v[182:185], v[124:127]
	v_mfma_f32_16x16x32_bf16 v[128:131], v[136:139], v[178:181], 0
	v_mfma_f32_16x16x32_bf16 v[128:131], v[140:143], v[182:185], v[128:131]
	v_mfma_f32_16x16x32_bf16 v[120:123], v[170:173], v[178:181], 0
	v_mfma_f32_16x16x32_bf16 v[120:123], v[174:177], v[182:185], v[120:123]
	v_mfma_f32_16x16x32_bf16 v[112:115], v[80:83], v[186:189], 0
	v_mfma_f32_16x16x32_bf16 v[112:115], v[116:119], v[190:193], v[112:115]
	v_mfma_f32_16x16x32_bf16 v[104:107], v[158:161], v[186:189], 0
	v_mfma_f32_16x16x32_bf16 v[104:107], v[162:165], v[190:193], v[104:107]
	v_mfma_f32_16x16x32_bf16 v[108:111], v[136:139], v[186:189], 0
	v_mfma_f32_16x16x32_bf16 v[108:111], v[140:143], v[190:193], v[108:111]
	v_mfma_f32_16x16x32_bf16 v[100:103], v[170:173], v[186:189], 0
	v_mfma_f32_16x16x32_bf16 v[100:103], v[174:177], v[190:193], v[100:103]
	v_mfma_f32_16x16x32_bf16 v[96:99], v[80:83], v[194:197], 0
	v_mfma_f32_16x16x32_bf16 v[96:99], v[116:119], v[198:201], v[96:99]
	v_mfma_f32_16x16x32_bf16 v[88:91], v[158:161], v[194:197], 0
	v_mfma_f32_16x16x32_bf16 v[88:91], v[162:165], v[198:201], v[88:91]
	v_mfma_f32_16x16x32_bf16 v[92:95], v[136:139], v[194:197], 0
	v_mfma_f32_16x16x32_bf16 v[92:95], v[140:143], v[198:201], v[92:95]
	v_mfma_f32_16x16x32_bf16 v[84:87], v[170:173], v[194:197], 0
	v_mfma_f32_16x16x32_bf16 v[84:87], v[174:177], v[198:201], v[84:87]
	v_mfma_f32_16x16x32_bf16 v[76:79], v[80:83], v[202:205], 0
	v_mfma_f32_16x16x32_bf16 v[76:79], v[116:119], v[206:209], v[76:79]
	v_mfma_f32_16x16x32_bf16 v[68:71], v[158:161], v[202:205], 0
	v_mfma_f32_16x16x32_bf16 v[68:71], v[162:165], v[206:209], v[68:71]
	v_mfma_f32_16x16x32_bf16 v[72:75], v[136:139], v[202:205], 0
	v_mfma_f32_16x16x32_bf16 v[72:75], v[140:143], v[206:209], v[72:75]
	v_mfma_f32_16x16x32_bf16 v[64:67], v[170:173], v[202:205], 0
	v_mfma_f32_16x16x32_bf16 v[64:67], v[174:177], v[206:209], v[64:67]
	s_barrier
	s_add_i32 s69, s70, s24
	s_mov_b32 m0, s69
	ds_read_b128 v[178:181], v169 offset:16384
	ds_read_b128 v[182:185], v169 offset:17408
	ds_read_b128 v[186:189], v169 offset:18432
	ds_read_b128 v[190:193], v169 offset:19456
	ds_read_b128 v[194:197], v169 offset:20480
	ds_read_b128 v[198:201], v169 offset:21504
	ds_read_b128 v[202:205], v169 offset:22528
	ds_read_b128 v[206:209], v169 offset:23552
	global_load_lds_dwordx4 v146, s[82:83]
	s_add_i32 m0, s69, 0x2000
	s_add_u32 s70, s82, 0x80000
	s_addc_u32 s71, s83, 0
	s_add_i32 s67, s67, s24
	global_load_lds_dwordx4 v150, s[82:83]
	s_mov_b32 m0, s67
	s_nop 0
	global_load_lds_dwordx4 v146, s[70:71]
	s_add_i32 m0, s67, 0x2000
	s_nop 0
	global_load_lds_dwordx4 v150, s[70:71]
	s_mov_b32 m0, s26
	s_nop 0
	global_load_lds_dwordx4 v144, s[84:85]
	s_mov_b32 m0, s28
	s_nop 0
	global_load_lds_dwordx4 v148, s[84:85]
	s_waitcnt vmcnt(8)
	s_waitcnt lgkmcnt(0)
	s_barrier
	s_waitcnt lgkmcnt(0)
	v_mfma_f32_16x16x32_bf16 v[60:63], v[80:83], v[178:181], 0
	v_mfma_f32_16x16x32_bf16 v[60:63], v[116:119], v[182:185], v[60:63]
	v_mfma_f32_16x16x32_bf16 v[52:55], v[158:161], v[178:181], 0
	v_mfma_f32_16x16x32_bf16 v[52:55], v[162:165], v[182:185], v[52:55]
	v_mfma_f32_16x16x32_bf16 v[56:59], v[136:139], v[178:181], 0
	v_mfma_f32_16x16x32_bf16 v[56:59], v[140:143], v[182:185], v[56:59]
	v_mfma_f32_16x16x32_bf16 v[48:51], v[170:173], v[178:181], 0
	v_mfma_f32_16x16x32_bf16 v[48:51], v[174:177], v[182:185], v[48:51]
	v_mfma_f32_16x16x32_bf16 v[44:47], v[80:83], v[186:189], 0
	v_mfma_f32_16x16x32_bf16 v[44:47], v[116:119], v[190:193], v[44:47]
	v_mfma_f32_16x16x32_bf16 v[36:39], v[158:161], v[186:189], 0
	v_mfma_f32_16x16x32_bf16 v[36:39], v[162:165], v[190:193], v[36:39]
	v_mfma_f32_16x16x32_bf16 v[40:43], v[136:139], v[186:189], 0
	v_mfma_f32_16x16x32_bf16 v[40:43], v[140:143], v[190:193], v[40:43]
	v_mfma_f32_16x16x32_bf16 v[32:35], v[170:173], v[186:189], 0
	v_mfma_f32_16x16x32_bf16 v[32:35], v[174:177], v[190:193], v[32:35]
	v_mfma_f32_16x16x32_bf16 v[28:31], v[80:83], v[194:197], 0
	v_mfma_f32_16x16x32_bf16 v[28:31], v[116:119], v[198:201], v[28:31]
	v_mfma_f32_16x16x32_bf16 v[20:23], v[158:161], v[194:197], 0
	v_mfma_f32_16x16x32_bf16 v[20:23], v[162:165], v[198:201], v[20:23]
	v_mfma_f32_16x16x32_bf16 v[24:27], v[136:139], v[194:197], 0
	v_mfma_f32_16x16x32_bf16 v[24:27], v[140:143], v[198:201], v[24:27]
	v_mfma_f32_16x16x32_bf16 v[16:19], v[170:173], v[194:197], 0
	v_mfma_f32_16x16x32_bf16 v[16:19], v[174:177], v[198:201], v[16:19]
	v_mfma_f32_16x16x32_bf16 v[12:15], v[80:83], v[202:205], 0
	v_mfma_f32_16x16x32_bf16 v[12:15], v[116:119], v[206:209], v[12:15]
	v_mfma_f32_16x16x32_bf16 v[4:7], v[158:161], v[202:205], 0
	v_mfma_f32_16x16x32_bf16 v[4:7], v[162:165], v[206:209], v[4:7]
	v_mfma_f32_16x16x32_bf16 v[8:11], v[136:139], v[202:205], 0
	v_mfma_f32_16x16x32_bf16 v[8:11], v[140:143], v[206:209], v[8:11]
	v_mfma_f32_16x16x32_bf16 v[0:3], v[170:173], v[202:205], 0
	v_mfma_f32_16x16x32_bf16 v[0:3], v[174:177], v[206:209], v[0:3]
	s_barrier
	s_add_i32 s67, 0, 0x18000
	s_add_i32 s69, 0, 0x1c000
	ds_read_b128 v[80:83], v145 offset:32768
	ds_read_b128 v[116:119], v145 offset:33792
	ds_read_b128 v[136:139], v145 offset:34816
	ds_read_b128 v[140:143], v145 offset:35840
	ds_read_b128 v[158:161], v145 offset:49152
	ds_read_b128 v[162:165], v145 offset:50176
	ds_read_b128 v[170:173], v145 offset:51200
	ds_read_b128 v[174:177], v145 offset:52224
	s_add_u32 s70, s84, 0x100000
	s_addc_u32 s71, s85, 0
	s_mov_b32 m0, s29
	ds_read_b128 v[178:181], v169 offset:32768
	ds_read_b128 v[182:185], v169 offset:33792
	ds_read_b128 v[186:189], v169 offset:34816
	ds_read_b128 v[190:193], v169 offset:35840
	ds_read_b128 v[194:197], v169 offset:36864
	ds_read_b128 v[198:201], v169 offset:37888
	ds_read_b128 v[202:205], v169 offset:38912
	ds_read_b128 v[206:209], v169 offset:39936
	global_load_lds_dwordx4 v144, s[70:71]
	s_mov_b32 m0, s34
	s_nop 0
	global_load_lds_dwordx4 v148, s[70:71]
	s_waitcnt vmcnt(8)
	s_waitcnt lgkmcnt(0)
	s_barrier
	s_waitcnt lgkmcnt(0)
	v_mfma_f32_16x16x32_bf16 v[132:135], v[80:83], v[178:181], v[132:135]
	v_mfma_f32_16x16x32_bf16 v[132:135], v[116:119], v[182:185], v[132:135]
	v_mfma_f32_16x16x32_bf16 v[124:127], v[158:161], v[178:181], v[124:127]
	v_mfma_f32_16x16x32_bf16 v[124:127], v[162:165], v[182:185], v[124:127]
	v_mfma_f32_16x16x32_bf16 v[128:131], v[136:139], v[178:181], v[128:131]
	v_mfma_f32_16x16x32_bf16 v[128:131], v[140:143], v[182:185], v[128:131]
	v_mfma_f32_16x16x32_bf16 v[120:123], v[170:173], v[178:181], v[120:123]
	v_mfma_f32_16x16x32_bf16 v[120:123], v[174:177], v[182:185], v[120:123]
	v_mfma_f32_16x16x32_bf16 v[112:115], v[80:83], v[186:189], v[112:115]
	v_mfma_f32_16x16x32_bf16 v[112:115], v[116:119], v[190:193], v[112:115]
	v_mfma_f32_16x16x32_bf16 v[104:107], v[158:161], v[186:189], v[104:107]
	v_mfma_f32_16x16x32_bf16 v[104:107], v[162:165], v[190:193], v[104:107]
	v_mfma_f32_16x16x32_bf16 v[108:111], v[136:139], v[186:189], v[108:111]
	v_mfma_f32_16x16x32_bf16 v[108:111], v[140:143], v[190:193], v[108:111]
	v_mfma_f32_16x16x32_bf16 v[100:103], v[170:173], v[186:189], v[100:103]
	v_mfma_f32_16x16x32_bf16 v[100:103], v[174:177], v[190:193], v[100:103]
	v_mfma_f32_16x16x32_bf16 v[96:99], v[80:83], v[194:197], v[96:99]
	v_mfma_f32_16x16x32_bf16 v[96:99], v[116:119], v[198:201], v[96:99]
	v_mfma_f32_16x16x32_bf16 v[88:91], v[158:161], v[194:197], v[88:91]
	v_mfma_f32_16x16x32_bf16 v[88:91], v[162:165], v[198:201], v[88:91]
	v_mfma_f32_16x16x32_bf16 v[92:95], v[136:139], v[194:197], v[92:95]
	v_mfma_f32_16x16x32_bf16 v[92:95], v[140:143], v[198:201], v[92:95]
	v_mfma_f32_16x16x32_bf16 v[84:87], v[170:173], v[194:197], v[84:87]
	v_mfma_f32_16x16x32_bf16 v[84:87], v[174:177], v[198:201], v[84:87]
	v_mfma_f32_16x16x32_bf16 v[76:79], v[80:83], v[202:205], v[76:79]
	v_mfma_f32_16x16x32_bf16 v[76:79], v[116:119], v[206:209], v[76:79]
	v_mfma_f32_16x16x32_bf16 v[68:71], v[158:161], v[202:205], v[68:71]
	v_mfma_f32_16x16x32_bf16 v[68:71], v[162:165], v[206:209], v[68:71]
	v_mfma_f32_16x16x32_bf16 v[72:75], v[136:139], v[202:205], v[72:75]
	v_mfma_f32_16x16x32_bf16 v[72:75], v[140:143], v[206:209], v[72:75]
	v_mfma_f32_16x16x32_bf16 v[64:67], v[170:173], v[202:205], v[64:67]
	v_mfma_f32_16x16x32_bf16 v[64:67], v[174:177], v[206:209], v[64:67]
	s_barrier
	s_add_i32 s67, s67, s24
	s_add_u32 s98, s82, 0x80
	s_addc_u32 s99, s83, 0
	s_mov_b32 m0, s67
	ds_read_b128 v[178:181], v169 offset:49152
	ds_read_b128 v[182:185], v169 offset:50176
	ds_read_b128 v[186:189], v169 offset:51200
	ds_read_b128 v[190:193], v169 offset:52224
	ds_read_b128 v[194:197], v169 offset:53248
	ds_read_b128 v[198:201], v169 offset:54272
	ds_read_b128 v[202:205], v169 offset:55296
	ds_read_b128 v[206:209], v169 offset:56320
	global_load_lds_dwordx4 v146, s[98:99]
	s_add_i32 m0, s67, 0x2000
	s_add_u32 s70, s82, 0x80080
	s_addc_u32 s71, s83, 0
	s_add_i32 s67, s69, s24
	global_load_lds_dwordx4 v150, s[98:99]
	s_mov_b32 m0, s67
	s_nop 0
	global_load_lds_dwordx4 v146, s[70:71]
	s_add_i32 m0, s67, 0x2000
	s_nop 0
	global_load_lds_dwordx4 v150, s[70:71]
	s_add_u32 s98, s84, 0x80
	s_addc_u32 s99, s85, 0
	s_mov_b32 m0, s39
	s_nop 0
	global_load_lds_dwordx4 v144, s[98:99]
	s_mov_b32 m0, s40
	s_nop 0
	global_load_lds_dwordx4 v148, s[98:99]
	s_waitcnt vmcnt(8)
	s_waitcnt lgkmcnt(0)
	s_barrier
	s_waitcnt lgkmcnt(0)
	v_mfma_f32_16x16x32_bf16 v[60:63], v[80:83], v[178:181], v[60:63]
	v_mfma_f32_16x16x32_bf16 v[60:63], v[116:119], v[182:185], v[60:63]
	v_mfma_f32_16x16x32_bf16 v[52:55], v[158:161], v[178:181], v[52:55]
	v_mfma_f32_16x16x32_bf16 v[52:55], v[162:165], v[182:185], v[52:55]
	v_mfma_f32_16x16x32_bf16 v[56:59], v[136:139], v[178:181], v[56:59]
	v_mfma_f32_16x16x32_bf16 v[56:59], v[140:143], v[182:185], v[56:59]
	v_mfma_f32_16x16x32_bf16 v[48:51], v[170:173], v[178:181], v[48:51]
	v_mfma_f32_16x16x32_bf16 v[48:51], v[174:177], v[182:185], v[48:51]
	v_mfma_f32_16x16x32_bf16 v[44:47], v[80:83], v[186:189], v[44:47]
	v_mfma_f32_16x16x32_bf16 v[44:47], v[116:119], v[190:193], v[44:47]
	v_mfma_f32_16x16x32_bf16 v[36:39], v[158:161], v[186:189], v[36:39]
	v_mfma_f32_16x16x32_bf16 v[36:39], v[162:165], v[190:193], v[36:39]
	v_mfma_f32_16x16x32_bf16 v[40:43], v[136:139], v[186:189], v[40:43]
	v_mfma_f32_16x16x32_bf16 v[40:43], v[140:143], v[190:193], v[40:43]
	v_mfma_f32_16x16x32_bf16 v[32:35], v[170:173], v[186:189], v[32:35]
	v_mfma_f32_16x16x32_bf16 v[32:35], v[174:177], v[190:193], v[32:35]
	v_mfma_f32_16x16x32_bf16 v[28:31], v[80:83], v[194:197], v[28:31]
	v_mfma_f32_16x16x32_bf16 v[28:31], v[116:119], v[198:201], v[28:31]
	v_mfma_f32_16x16x32_bf16 v[20:23], v[158:161], v[194:197], v[20:23]
	v_mfma_f32_16x16x32_bf16 v[20:23], v[162:165], v[198:201], v[20:23]
	v_mfma_f32_16x16x32_bf16 v[24:27], v[136:139], v[194:197], v[24:27]
	v_mfma_f32_16x16x32_bf16 v[24:27], v[140:143], v[198:201], v[24:27]
	v_mfma_f32_16x16x32_bf16 v[16:19], v[170:173], v[194:197], v[16:19]
	v_mfma_f32_16x16x32_bf16 v[16:19], v[174:177], v[198:201], v[16:19]
	v_mfma_f32_16x16x32_bf16 v[12:15], v[80:83], v[202:205], v[12:15]
	v_mfma_f32_16x16x32_bf16 v[12:15], v[116:119], v[206:209], v[12:15]
	v_mfma_f32_16x16x32_bf16 v[4:7], v[158:161], v[202:205], v[4:7]
	v_mfma_f32_16x16x32_bf16 v[4:7], v[162:165], v[206:209], v[4:7]
	v_mfma_f32_16x16x32_bf16 v[8:11], v[136:139], v[202:205], v[8:11]
	v_mfma_f32_16x16x32_bf16 v[8:11], v[140:143], v[206:209], v[8:11]
	v_mfma_f32_16x16x32_bf16 v[0:3], v[170:173], v[202:205], v[0:3]
	v_mfma_f32_16x16x32_bf16 v[0:3], v[174:177], v[206:209], v[0:3]
	s_barrier
	s_add_i32 s68, s68, 2
	s_add_u32 s80, s80, 0x100
	s_addc_u32 s81, s81, 0
	s_add_u32 s60, s60, 0x100
	s_addc_u32 s61, s61, 0
.LBB0_297:
	s_add_u32 s67, s80, 0xfff00080
	s_addc_u32 s69, s81, -1
	s_add_i32 s70, 0, 0x10000
	s_cmp_eq_u32 s68, 28
	s_cselect_b32 s85, s23, s69
	s_cselect_b32 s84, s56, s67
	s_cselect_b32 s83, s21, s61
	s_cselect_b32 s82, s57, s60
	s_add_i32 s67, 0, 0x14000
	ds_read_b128 v[80:83], v145
	ds_read_b128 v[116:119], v145 offset:1024
	ds_read_b128 v[136:139], v145 offset:2048
	ds_read_b128 v[140:143], v145 offset:3072
	ds_read_b128 v[158:161], v145 offset:16384
	ds_read_b128 v[162:165], v145 offset:17408
	ds_read_b128 v[170:173], v145 offset:18432
	ds_read_b128 v[174:177], v145 offset:19456
	s_add_i32 m0, s26, 0xc000
	ds_read_b128 v[178:181], v169
	ds_read_b128 v[182:185], v169 offset:1024
	ds_read_b128 v[186:189], v169 offset:2048
	ds_read_b128 v[190:193], v169 offset:3072
	ds_read_b128 v[194:197], v169 offset:4096
	ds_read_b128 v[198:201], v169 offset:5120
	ds_read_b128 v[202:205], v169 offset:6144
	ds_read_b128 v[206:209], v169 offset:7168
	global_load_lds_dwordx4 v154, s[80:81]
	s_add_i32 m0, s26, 0xe000
	s_nop 0
	global_load_lds_dwordx4 v156, s[80:81]
	s_waitcnt vmcnt(8)
	s_waitcnt lgkmcnt(0)
	s_barrier
	s_waitcnt lgkmcnt(0)
	v_mfma_f32_16x16x32_bf16 v[132:135], v[80:83], v[178:181], v[132:135]
	v_mfma_f32_16x16x32_bf16 v[132:135], v[116:119], v[182:185], v[132:135]
	v_mfma_f32_16x16x32_bf16 v[124:127], v[158:161], v[178:181], v[124:127]
	v_mfma_f32_16x16x32_bf16 v[124:127], v[162:165], v[182:185], v[124:127]
	v_mfma_f32_16x16x32_bf16 v[128:131], v[136:139], v[178:181], v[128:131]
	v_mfma_f32_16x16x32_bf16 v[128:131], v[140:143], v[182:185], v[128:131]
	v_mfma_f32_16x16x32_bf16 v[120:123], v[170:173], v[178:181], v[120:123]
	v_mfma_f32_16x16x32_bf16 v[120:123], v[174:177], v[182:185], v[120:123]
	v_mfma_f32_16x16x32_bf16 v[112:115], v[80:83], v[186:189], v[112:115]
	v_mfma_f32_16x16x32_bf16 v[112:115], v[116:119], v[190:193], v[112:115]
	v_mfma_f32_16x16x32_bf16 v[104:107], v[158:161], v[186:189], v[104:107]
	v_mfma_f32_16x16x32_bf16 v[104:107], v[162:165], v[190:193], v[104:107]
	v_mfma_f32_16x16x32_bf16 v[108:111], v[136:139], v[186:189], v[108:111]
	v_mfma_f32_16x16x32_bf16 v[108:111], v[140:143], v[190:193], v[108:111]
	v_mfma_f32_16x16x32_bf16 v[100:103], v[170:173], v[186:189], v[100:103]
	v_mfma_f32_16x16x32_bf16 v[100:103], v[174:177], v[190:193], v[100:103]
	v_mfma_f32_16x16x32_bf16 v[96:99], v[80:83], v[194:197], v[96:99]
	v_mfma_f32_16x16x32_bf16 v[96:99], v[116:119], v[198:201], v[96:99]
	v_mfma_f32_16x16x32_bf16 v[88:91], v[158:161], v[194:197], v[88:91]
	v_mfma_f32_16x16x32_bf16 v[88:91], v[162:165], v[198:201], v[88:91]
	v_mfma_f32_16x16x32_bf16 v[92:95], v[136:139], v[194:197], v[92:95]
	v_mfma_f32_16x16x32_bf16 v[92:95], v[140:143], v[198:201], v[92:95]
	v_mfma_f32_16x16x32_bf16 v[84:87], v[170:173], v[194:197], v[84:87]
	v_mfma_f32_16x16x32_bf16 v[84:87], v[174:177], v[198:201], v[84:87]
	v_mfma_f32_16x16x32_bf16 v[76:79], v[80:83], v[202:205], v[76:79]
	v_mfma_f32_16x16x32_bf16 v[76:79], v[116:119], v[206:209], v[76:79]
	v_mfma_f32_16x16x32_bf16 v[68:71], v[158:161], v[202:205], v[68:71]
	v_mfma_f32_16x16x32_bf16 v[68:71], v[162:165], v[206:209], v[68:71]
	v_mfma_f32_16x16x32_bf16 v[72:75], v[136:139], v[202:205], v[72:75]
	v_mfma_f32_16x16x32_bf16 v[72:75], v[140:143], v[206:209], v[72:75]
	v_mfma_f32_16x16x32_bf16 v[64:67], v[170:173], v[202:205], v[64:67]
	v_mfma_f32_16x16x32_bf16 v[64:67], v[174:177], v[206:209], v[64:67]
	s_barrier
	s_add_i32 s69, s70, s24
	s_mov_b32 m0, s69
	ds_read_b128 v[178:181], v169 offset:16384
	ds_read_b128 v[182:185], v169 offset:17408
	ds_read_b128 v[186:189], v169 offset:18432
	ds_read_b128 v[190:193], v169 offset:19456
	ds_read_b128 v[194:197], v169 offset:20480
	ds_read_b128 v[198:201], v169 offset:21504
	ds_read_b128 v[202:205], v169 offset:22528
	ds_read_b128 v[206:209], v169 offset:23552
	global_load_lds_dwordx4 v146, s[82:83]
	s_add_i32 m0, s69, 0x2000
	s_add_u32 s70, s82, 0x80000
	s_addc_u32 s71, s83, 0
	s_add_i32 s67, s67, s24
	global_load_lds_dwordx4 v150, s[82:83]
	s_mov_b32 m0, s67
	s_nop 0
	global_load_lds_dwordx4 v146, s[70:71]
	s_add_i32 m0, s67, 0x2000
	s_nop 0
	global_load_lds_dwordx4 v150, s[70:71]
	s_mov_b32 m0, s26
	s_nop 0
	global_load_lds_dwordx4 v144, s[84:85]
	s_mov_b32 m0, s28
	s_nop 0
	global_load_lds_dwordx4 v148, s[84:85]
	s_waitcnt vmcnt(8)
	s_waitcnt lgkmcnt(0)
	s_barrier
	s_waitcnt lgkmcnt(0)
	v_mfma_f32_16x16x32_bf16 v[60:63], v[80:83], v[178:181], v[60:63]
	v_mfma_f32_16x16x32_bf16 v[60:63], v[116:119], v[182:185], v[60:63]
	v_mfma_f32_16x16x32_bf16 v[52:55], v[158:161], v[178:181], v[52:55]
	v_mfma_f32_16x16x32_bf16 v[52:55], v[162:165], v[182:185], v[52:55]
	v_mfma_f32_16x16x32_bf16 v[56:59], v[136:139], v[178:181], v[56:59]
	v_mfma_f32_16x16x32_bf16 v[56:59], v[140:143], v[182:185], v[56:59]
	v_mfma_f32_16x16x32_bf16 v[48:51], v[170:173], v[178:181], v[48:51]
	v_mfma_f32_16x16x32_bf16 v[48:51], v[174:177], v[182:185], v[48:51]
	v_mfma_f32_16x16x32_bf16 v[44:47], v[80:83], v[186:189], v[44:47]
	v_mfma_f32_16x16x32_bf16 v[44:47], v[116:119], v[190:193], v[44:47]
	v_mfma_f32_16x16x32_bf16 v[36:39], v[158:161], v[186:189], v[36:39]
	v_mfma_f32_16x16x32_bf16 v[36:39], v[162:165], v[190:193], v[36:39]
	v_mfma_f32_16x16x32_bf16 v[40:43], v[136:139], v[186:189], v[40:43]
	v_mfma_f32_16x16x32_bf16 v[40:43], v[140:143], v[190:193], v[40:43]
	v_mfma_f32_16x16x32_bf16 v[32:35], v[170:173], v[186:189], v[32:35]
	v_mfma_f32_16x16x32_bf16 v[32:35], v[174:177], v[190:193], v[32:35]
	v_mfma_f32_16x16x32_bf16 v[28:31], v[80:83], v[194:197], v[28:31]
	v_mfma_f32_16x16x32_bf16 v[28:31], v[116:119], v[198:201], v[28:31]
	v_mfma_f32_16x16x32_bf16 v[20:23], v[158:161], v[194:197], v[20:23]
	v_mfma_f32_16x16x32_bf16 v[20:23], v[162:165], v[198:201], v[20:23]
	v_mfma_f32_16x16x32_bf16 v[24:27], v[136:139], v[194:197], v[24:27]
	v_mfma_f32_16x16x32_bf16 v[24:27], v[140:143], v[198:201], v[24:27]
	v_mfma_f32_16x16x32_bf16 v[16:19], v[170:173], v[194:197], v[16:19]
	v_mfma_f32_16x16x32_bf16 v[16:19], v[174:177], v[198:201], v[16:19]
	v_mfma_f32_16x16x32_bf16 v[12:15], v[80:83], v[202:205], v[12:15]
	v_mfma_f32_16x16x32_bf16 v[12:15], v[116:119], v[206:209], v[12:15]
	v_mfma_f32_16x16x32_bf16 v[4:7], v[158:161], v[202:205], v[4:7]
	v_mfma_f32_16x16x32_bf16 v[4:7], v[162:165], v[206:209], v[4:7]
	v_mfma_f32_16x16x32_bf16 v[8:11], v[136:139], v[202:205], v[8:11]
	v_mfma_f32_16x16x32_bf16 v[8:11], v[140:143], v[206:209], v[8:11]
	v_mfma_f32_16x16x32_bf16 v[0:3], v[170:173], v[202:205], v[0:3]
	v_mfma_f32_16x16x32_bf16 v[0:3], v[174:177], v[206:209], v[0:3]
	s_barrier
	s_add_i32 s67, 0, 0x18000
	s_add_i32 s69, 0, 0x1c000
	ds_read_b128 v[80:83], v145 offset:32768
	ds_read_b128 v[116:119], v145 offset:33792
	ds_read_b128 v[136:139], v145 offset:34816
	ds_read_b128 v[140:143], v145 offset:35840
	ds_read_b128 v[158:161], v145 offset:49152
	ds_read_b128 v[162:165], v145 offset:50176
	ds_read_b128 v[170:173], v145 offset:51200
	ds_read_b128 v[174:177], v145 offset:52224
	s_add_u32 s70, s84, 0x100000
	s_addc_u32 s71, s85, 0
	s_mov_b32 m0, s29
	ds_read_b128 v[178:181], v169 offset:32768
	ds_read_b128 v[182:185], v169 offset:33792
	ds_read_b128 v[186:189], v169 offset:34816
	ds_read_b128 v[190:193], v169 offset:35840
	ds_read_b128 v[194:197], v169 offset:36864
	ds_read_b128 v[198:201], v169 offset:37888
	ds_read_b128 v[202:205], v169 offset:38912
	ds_read_b128 v[206:209], v169 offset:39936
	global_load_lds_dwordx4 v144, s[70:71]
	s_mov_b32 m0, s34
	s_nop 0
	global_load_lds_dwordx4 v148, s[70:71]
	s_waitcnt vmcnt(8)
	s_waitcnt lgkmcnt(0)
	s_barrier
	s_waitcnt lgkmcnt(0)
	v_mfma_f32_16x16x32_bf16 v[132:135], v[80:83], v[178:181], v[132:135]
	v_mfma_f32_16x16x32_bf16 v[132:135], v[116:119], v[182:185], v[132:135]
	v_mfma_f32_16x16x32_bf16 v[124:127], v[158:161], v[178:181], v[124:127]
	v_mfma_f32_16x16x32_bf16 v[124:127], v[162:165], v[182:185], v[124:127]
	v_mfma_f32_16x16x32_bf16 v[128:131], v[136:139], v[178:181], v[128:131]
	v_mfma_f32_16x16x32_bf16 v[128:131], v[140:143], v[182:185], v[128:131]
	v_mfma_f32_16x16x32_bf16 v[120:123], v[170:173], v[178:181], v[120:123]
	v_mfma_f32_16x16x32_bf16 v[120:123], v[174:177], v[182:185], v[120:123]
	v_mfma_f32_16x16x32_bf16 v[112:115], v[80:83], v[186:189], v[112:115]
	v_mfma_f32_16x16x32_bf16 v[112:115], v[116:119], v[190:193], v[112:115]
	v_mfma_f32_16x16x32_bf16 v[104:107], v[158:161], v[186:189], v[104:107]
	v_mfma_f32_16x16x32_bf16 v[104:107], v[162:165], v[190:193], v[104:107]
	v_mfma_f32_16x16x32_bf16 v[108:111], v[136:139], v[186:189], v[108:111]
	v_mfma_f32_16x16x32_bf16 v[108:111], v[140:143], v[190:193], v[108:111]
	v_mfma_f32_16x16x32_bf16 v[100:103], v[170:173], v[186:189], v[100:103]
	v_mfma_f32_16x16x32_bf16 v[100:103], v[174:177], v[190:193], v[100:103]
	v_mfma_f32_16x16x32_bf16 v[96:99], v[80:83], v[194:197], v[96:99]
	v_mfma_f32_16x16x32_bf16 v[96:99], v[116:119], v[198:201], v[96:99]
	v_mfma_f32_16x16x32_bf16 v[88:91], v[158:161], v[194:197], v[88:91]
	v_mfma_f32_16x16x32_bf16 v[88:91], v[162:165], v[198:201], v[88:91]
	v_mfma_f32_16x16x32_bf16 v[92:95], v[136:139], v[194:197], v[92:95]
	v_mfma_f32_16x16x32_bf16 v[92:95], v[140:143], v[198:201], v[92:95]
	v_mfma_f32_16x16x32_bf16 v[84:87], v[170:173], v[194:197], v[84:87]
	v_mfma_f32_16x16x32_bf16 v[84:87], v[174:177], v[198:201], v[84:87]
	v_mfma_f32_16x16x32_bf16 v[76:79], v[80:83], v[202:205], v[76:79]
	v_mfma_f32_16x16x32_bf16 v[76:79], v[116:119], v[206:209], v[76:79]
	v_mfma_f32_16x16x32_bf16 v[68:71], v[158:161], v[202:205], v[68:71]
	v_mfma_f32_16x16x32_bf16 v[68:71], v[162:165], v[206:209], v[68:71]
	v_mfma_f32_16x16x32_bf16 v[72:75], v[136:139], v[202:205], v[72:75]
	v_mfma_f32_16x16x32_bf16 v[72:75], v[140:143], v[206:209], v[72:75]
	v_mfma_f32_16x16x32_bf16 v[64:67], v[170:173], v[202:205], v[64:67]
	v_mfma_f32_16x16x32_bf16 v[64:67], v[174:177], v[206:209], v[64:67]
	s_barrier
	s_add_i32 s67, s67, s24
	s_add_u32 s98, s82, 0x80
	s_addc_u32 s99, s83, 0
	s_mov_b32 m0, s67
	ds_read_b128 v[178:181], v169 offset:49152
	ds_read_b128 v[182:185], v169 offset:50176
	ds_read_b128 v[186:189], v169 offset:51200
	ds_read_b128 v[190:193], v169 offset:52224
	ds_read_b128 v[194:197], v169 offset:53248
	ds_read_b128 v[198:201], v169 offset:54272
	ds_read_b128 v[202:205], v169 offset:55296
	ds_read_b128 v[206:209], v169 offset:56320
	global_load_lds_dwordx4 v146, s[98:99]
	s_add_i32 m0, s67, 0x2000
	s_add_u32 s70, s82, 0x80080
	s_addc_u32 s71, s83, 0
	s_add_i32 s67, s69, s24
	global_load_lds_dwordx4 v150, s[98:99]
	s_mov_b32 m0, s67
	s_nop 0
	global_load_lds_dwordx4 v146, s[70:71]
	s_add_i32 m0, s67, 0x2000
	s_nop 0
	global_load_lds_dwordx4 v150, s[70:71]
	s_add_u32 s98, s84, 0x80
	s_addc_u32 s99, s85, 0
	s_mov_b32 m0, s39
	s_nop 0
	global_load_lds_dwordx4 v144, s[98:99]
	s_mov_b32 m0, s40
	s_nop 0
	global_load_lds_dwordx4 v148, s[98:99]
	s_waitcnt vmcnt(8)
	s_waitcnt lgkmcnt(0)
	s_barrier
	s_waitcnt lgkmcnt(0)
	v_mfma_f32_16x16x32_bf16 v[60:63], v[80:83], v[178:181], v[60:63]
	v_mfma_f32_16x16x32_bf16 v[60:63], v[116:119], v[182:185], v[60:63]
	v_mfma_f32_16x16x32_bf16 v[52:55], v[158:161], v[178:181], v[52:55]
	v_mfma_f32_16x16x32_bf16 v[52:55], v[162:165], v[182:185], v[52:55]
	v_mfma_f32_16x16x32_bf16 v[56:59], v[136:139], v[178:181], v[56:59]
	v_mfma_f32_16x16x32_bf16 v[56:59], v[140:143], v[182:185], v[56:59]
	v_mfma_f32_16x16x32_bf16 v[48:51], v[170:173], v[178:181], v[48:51]
	v_mfma_f32_16x16x32_bf16 v[48:51], v[174:177], v[182:185], v[48:51]
	v_mfma_f32_16x16x32_bf16 v[44:47], v[80:83], v[186:189], v[44:47]
	v_mfma_f32_16x16x32_bf16 v[44:47], v[116:119], v[190:193], v[44:47]
	v_mfma_f32_16x16x32_bf16 v[36:39], v[158:161], v[186:189], v[36:39]
	v_mfma_f32_16x16x32_bf16 v[36:39], v[162:165], v[190:193], v[36:39]
	v_mfma_f32_16x16x32_bf16 v[40:43], v[136:139], v[186:189], v[40:43]
	v_mfma_f32_16x16x32_bf16 v[40:43], v[140:143], v[190:193], v[40:43]
	v_mfma_f32_16x16x32_bf16 v[32:35], v[170:173], v[186:189], v[32:35]
	v_mfma_f32_16x16x32_bf16 v[32:35], v[174:177], v[190:193], v[32:35]
	v_mfma_f32_16x16x32_bf16 v[28:31], v[80:83], v[194:197], v[28:31]
	v_mfma_f32_16x16x32_bf16 v[28:31], v[116:119], v[198:201], v[28:31]
	v_mfma_f32_16x16x32_bf16 v[20:23], v[158:161], v[194:197], v[20:23]
	v_mfma_f32_16x16x32_bf16 v[20:23], v[162:165], v[198:201], v[20:23]
	v_mfma_f32_16x16x32_bf16 v[24:27], v[136:139], v[194:197], v[24:27]
	v_mfma_f32_16x16x32_bf16 v[24:27], v[140:143], v[198:201], v[24:27]
	v_mfma_f32_16x16x32_bf16 v[16:19], v[170:173], v[194:197], v[16:19]
	v_mfma_f32_16x16x32_bf16 v[16:19], v[174:177], v[198:201], v[16:19]
	v_mfma_f32_16x16x32_bf16 v[12:15], v[80:83], v[202:205], v[12:15]
	v_mfma_f32_16x16x32_bf16 v[12:15], v[116:119], v[206:209], v[12:15]
	v_mfma_f32_16x16x32_bf16 v[4:7], v[158:161], v[202:205], v[4:7]
	v_mfma_f32_16x16x32_bf16 v[4:7], v[162:165], v[206:209], v[4:7]
	v_mfma_f32_16x16x32_bf16 v[8:11], v[136:139], v[202:205], v[8:11]
	v_mfma_f32_16x16x32_bf16 v[8:11], v[140:143], v[206:209], v[8:11]
	v_mfma_f32_16x16x32_bf16 v[0:3], v[170:173], v[202:205], v[0:3]
	v_mfma_f32_16x16x32_bf16 v[0:3], v[174:177], v[206:209], v[0:3]
	s_barrier
	s_add_i32 s68, s68, 2
	s_add_u32 s80, s80, 0x100
	s_addc_u32 s81, s81, 0
	s_add_u32 s60, s60, 0x100
	s_addc_u32 s61, s61, 0
	s_cmp_gt_u32 s68, 29
	s_cbranch_scc0 .LBB0_297
	s_and_b64 vcc, exec, s[18:19]
	s_cbranch_vccz .LBB0_300
	s_barrier

.LBB0_384:
	s_ashr_i32 s73, s72, 31
	s_lshl_b64 s[74:75], s[72:73], 20
	s_add_u32 s74, s2, s74
	s_addc_u32 s75, s3, s75
	s_and_b64 s[76:77], s[4:5], exec
	s_cselect_b32 s73, s75, s81
	s_cselect_b32 s79, s74, s80
	s_ashr_i32 s23, s22, 31
	s_lshl_b64 s[76:77], s[22:23], 20
	s_add_u32 s76, s14, s76
	s_addc_u32 s77, s15, s77
	s_and_b64 s[84:85], s[4:5], exec
	s_cselect_b32 s23, s77, s83
	s_cselect_b32 s86, s76, s82
	s_add_u32 s80, s80, 0x80080
	s_addc_u32 s81, s81, 0
	s_add_u32 s87, s82, 0x100
	s_addc_u32 s88, s83, 0
	s_mov_b32 s89, -2
	v_add_u32_e32 v169, 0x10000, v186
	s_add_u32 s67, s80, 0xfff80080
	s_addc_u32 s82, s81, -1
	s_add_i32 s90, 0, 0x10000
	s_cmp_eq_u32 s89, 28
	s_cselect_b32 s85, s73, s82
	s_cselect_b32 s84, s79, s67
	s_cselect_b32 s83, s23, s88
	s_cselect_b32 s82, s86, s87
	s_add_i32 s67, 0, 0x14000
	ds_read_b128 v[128:131], v169
	ds_read_b128 v[132:135], v169 offset:1024
	ds_read_b128 v[136:139], v169 offset:2048
	ds_read_b128 v[140:143], v169 offset:3072
	ds_read_b128 v[144:147], v169 offset:16384
	ds_read_b128 v[148:151], v169 offset:17408
	ds_read_b128 v[152:155], v169 offset:18432
	ds_read_b128 v[156:159], v169 offset:19456
	s_add_i32 m0, s29, 0xc000
	ds_read_b128 v[160:163], v187
	ds_read_b128 v[164:167], v187 offset:1024
	ds_read_b128 v[182:185], v187 offset:2048
	ds_read_b128 v[188:191], v187 offset:3072
	ds_read_b128 v[192:195], v187 offset:4096
	ds_read_b128 v[196:199], v187 offset:5120
	ds_read_b128 v[200:203], v187 offset:6144
	ds_read_b128 v[204:207], v187 offset:7168
	global_load_lds_dwordx4 v178, s[80:81]
	s_add_i32 m0, s29, 0xe000
	s_nop 0
	global_load_lds_dwordx4 v180, s[80:81]
	s_waitcnt vmcnt(8)
	s_waitcnt lgkmcnt(0)
	s_barrier
	s_waitcnt lgkmcnt(0)
	v_mfma_f32_16x16x32_bf16 v[124:127], v[128:131], v[160:163], 0
	v_mfma_f32_16x16x32_bf16 v[124:127], v[132:135], v[164:167], v[124:127]
	v_mfma_f32_16x16x32_bf16 v[116:119], v[144:147], v[160:163], 0
	v_mfma_f32_16x16x32_bf16 v[116:119], v[148:151], v[164:167], v[116:119]
	v_mfma_f32_16x16x32_bf16 v[120:123], v[136:139], v[160:163], 0
	v_mfma_f32_16x16x32_bf16 v[120:123], v[140:143], v[164:167], v[120:123]
	v_mfma_f32_16x16x32_bf16 v[112:115], v[152:155], v[160:163], 0
	v_mfma_f32_16x16x32_bf16 v[112:115], v[156:159], v[164:167], v[112:115]
	v_mfma_f32_16x16x32_bf16 v[108:111], v[128:131], v[182:185], 0
	v_mfma_f32_16x16x32_bf16 v[108:111], v[132:135], v[188:191], v[108:111]
	v_mfma_f32_16x16x32_bf16 v[100:103], v[144:147], v[182:185], 0
	v_mfma_f32_16x16x32_bf16 v[100:103], v[148:151], v[188:191], v[100:103]
	v_mfma_f32_16x16x32_bf16 v[104:107], v[136:139], v[182:185], 0
	v_mfma_f32_16x16x32_bf16 v[104:107], v[140:143], v[188:191], v[104:107]
	v_mfma_f32_16x16x32_bf16 v[96:99], v[152:155], v[182:185], 0
	v_mfma_f32_16x16x32_bf16 v[96:99], v[156:159], v[188:191], v[96:99]
	v_mfma_f32_16x16x32_bf16 v[92:95], v[128:131], v[192:195], 0
	v_mfma_f32_16x16x32_bf16 v[92:95], v[132:135], v[196:199], v[92:95]
	v_mfma_f32_16x16x32_bf16 v[84:87], v[144:147], v[192:195], 0
	v_mfma_f32_16x16x32_bf16 v[84:87], v[148:151], v[196:199], v[84:87]
	v_mfma_f32_16x16x32_bf16 v[88:91], v[136:139], v[192:195], 0
	v_mfma_f32_16x16x32_bf16 v[88:91], v[140:143], v[196:199], v[88:91]
	v_mfma_f32_16x16x32_bf16 v[80:83], v[152:155], v[192:195], 0
	v_mfma_f32_16x16x32_bf16 v[80:83], v[156:159], v[196:199], v[80:83]
	v_mfma_f32_16x16x32_bf16 v[76:79], v[128:131], v[200:203], 0
	v_mfma_f32_16x16x32_bf16 v[76:79], v[132:135], v[204:207], v[76:79]
	v_mfma_f32_16x16x32_bf16 v[68:71], v[144:147], v[200:203], 0
	v_mfma_f32_16x16x32_bf16 v[68:71], v[148:151], v[204:207], v[68:71]
	v_mfma_f32_16x16x32_bf16 v[72:75], v[136:139], v[200:203], 0
	v_mfma_f32_16x16x32_bf16 v[72:75], v[140:143], v[204:207], v[72:75]
	v_mfma_f32_16x16x32_bf16 v[64:67], v[152:155], v[200:203], 0
	v_mfma_f32_16x16x32_bf16 v[64:67], v[156:159], v[204:207], v[64:67]
	s_barrier
	s_add_i32 s90, s90, s24
	s_mov_b32 m0, s90
	ds_read_b128 v[160:163], v187 offset:16384
	ds_read_b128 v[164:167], v187 offset:17408
	ds_read_b128 v[182:185], v187 offset:18432
	ds_read_b128 v[188:191], v187 offset:19456
	ds_read_b128 v[192:195], v187 offset:20480
	ds_read_b128 v[196:199], v187 offset:21504
	ds_read_b128 v[200:203], v187 offset:22528
	ds_read_b128 v[204:207], v187 offset:23552
	global_load_lds_dwordx4 v172, s[82:83]
	s_add_i32 m0, s90, 0x2000
	s_add_u32 s90, s82, 0x80000
	s_addc_u32 s91, s83, 0
	s_add_i32 s67, s67, s24
	global_load_lds_dwordx4 v168, s[82:83]
	s_mov_b32 m0, s67
	s_nop 0
	global_load_lds_dwordx4 v172, s[90:91]
	s_add_i32 m0, s67, 0x2000
	s_nop 0
	global_load_lds_dwordx4 v168, s[90:91]
	s_mov_b32 m0, s29
	s_nop 0
	global_load_lds_dwordx4 v174, s[84:85]
	s_mov_b32 m0, s34
	s_nop 0
	global_load_lds_dwordx4 v170, s[84:85]
	s_waitcnt vmcnt(8)
	s_waitcnt lgkmcnt(0)
	s_barrier
	s_waitcnt lgkmcnt(0)
	v_mfma_f32_16x16x32_bf16 v[60:63], v[128:131], v[160:163], 0
	v_mfma_f32_16x16x32_bf16 v[60:63], v[132:135], v[164:167], v[60:63]
	v_mfma_f32_16x16x32_bf16 v[52:55], v[144:147], v[160:163], 0
	v_mfma_f32_16x16x32_bf16 v[52:55], v[148:151], v[164:167], v[52:55]
	v_mfma_f32_16x16x32_bf16 v[56:59], v[136:139], v[160:163], 0
	v_mfma_f32_16x16x32_bf16 v[56:59], v[140:143], v[164:167], v[56:59]
	v_mfma_f32_16x16x32_bf16 v[48:51], v[152:155], v[160:163], 0
	v_mfma_f32_16x16x32_bf16 v[48:51], v[156:159], v[164:167], v[48:51]
	v_mfma_f32_16x16x32_bf16 v[44:47], v[128:131], v[182:185], 0
	v_mfma_f32_16x16x32_bf16 v[44:47], v[132:135], v[188:191], v[44:47]
	v_mfma_f32_16x16x32_bf16 v[36:39], v[144:147], v[182:185], 0
	v_mfma_f32_16x16x32_bf16 v[36:39], v[148:151], v[188:191], v[36:39]
	v_mfma_f32_16x16x32_bf16 v[40:43], v[136:139], v[182:185], 0
	v_mfma_f32_16x16x32_bf16 v[40:43], v[140:143], v[188:191], v[40:43]
	v_mfma_f32_16x16x32_bf16 v[32:35], v[152:155], v[182:185], 0
	v_mfma_f32_16x16x32_bf16 v[32:35], v[156:159], v[188:191], v[32:35]
	v_mfma_f32_16x16x32_bf16 v[28:31], v[128:131], v[192:195], 0
	v_mfma_f32_16x16x32_bf16 v[28:31], v[132:135], v[196:199], v[28:31]
	v_mfma_f32_16x16x32_bf16 v[20:23], v[144:147], v[192:195], 0
	v_mfma_f32_16x16x32_bf16 v[20:23], v[148:151], v[196:199], v[20:23]
	v_mfma_f32_16x16x32_bf16 v[24:27], v[136:139], v[192:195], 0
	v_mfma_f32_16x16x32_bf16 v[24:27], v[140:143], v[196:199], v[24:27]
	v_mfma_f32_16x16x32_bf16 v[16:19], v[152:155], v[192:195], 0
	v_mfma_f32_16x16x32_bf16 v[16:19], v[156:159], v[196:199], v[16:19]
	v_mfma_f32_16x16x32_bf16 v[12:15], v[128:131], v[200:203], 0
	v_mfma_f32_16x16x32_bf16 v[12:15], v[132:135], v[204:207], v[12:15]
	v_mfma_f32_16x16x32_bf16 v[4:7], v[144:147], v[200:203], 0
	v_mfma_f32_16x16x32_bf16 v[4:7], v[148:151], v[204:207], v[4:7]
	v_mfma_f32_16x16x32_bf16 v[8:11], v[136:139], v[200:203], 0
	v_mfma_f32_16x16x32_bf16 v[8:11], v[140:143], v[204:207], v[8:11]
	v_mfma_f32_16x16x32_bf16 v[0:3], v[152:155], v[200:203], 0
	v_mfma_f32_16x16x32_bf16 v[0:3], v[156:159], v[204:207], v[0:3]
	s_barrier
	s_add_i32 s67, 0, 0x18000
	s_add_i32 s90, 0, 0x1c000
	ds_read_b128 v[128:131], v169 offset:32768
	ds_read_b128 v[132:135], v169 offset:33792
	ds_read_b128 v[136:139], v169 offset:34816
	ds_read_b128 v[140:143], v169 offset:35840
	ds_read_b128 v[144:147], v169 offset:49152
	ds_read_b128 v[148:151], v169 offset:50176
	ds_read_b128 v[152:155], v169 offset:51200
	ds_read_b128 v[156:159], v169 offset:52224
	s_add_u32 s84, s84, 0x80000
	s_addc_u32 s85, s85, 0
	s_mov_b32 m0, s35
	ds_read_b128 v[160:163], v187 offset:32768
	ds_read_b128 v[164:167], v187 offset:33792
	ds_read_b128 v[182:185], v187 offset:34816
	ds_read_b128 v[188:191], v187 offset:35840
	ds_read_b128 v[192:195], v187 offset:36864
	ds_read_b128 v[196:199], v187 offset:37888
	ds_read_b128 v[200:203], v187 offset:38912
	ds_read_b128 v[204:207], v187 offset:39936
	global_load_lds_dwordx4 v174, s[84:85]
	s_mov_b32 m0, s38
	s_nop 0
	global_load_lds_dwordx4 v170, s[84:85]
	s_waitcnt vmcnt(8)
	s_waitcnt lgkmcnt(0)
	s_barrier
	s_waitcnt lgkmcnt(0)
	v_mfma_f32_16x16x32_bf16 v[124:127], v[128:131], v[160:163], v[124:127]
	v_mfma_f32_16x16x32_bf16 v[124:127], v[132:135], v[164:167], v[124:127]
	v_mfma_f32_16x16x32_bf16 v[116:119], v[144:147], v[160:163], v[116:119]
	v_mfma_f32_16x16x32_bf16 v[116:119], v[148:151], v[164:167], v[116:119]
	v_mfma_f32_16x16x32_bf16 v[120:123], v[136:139], v[160:163], v[120:123]
	v_mfma_f32_16x16x32_bf16 v[120:123], v[140:143], v[164:167], v[120:123]
	v_mfma_f32_16x16x32_bf16 v[112:115], v[152:155], v[160:163], v[112:115]
	v_mfma_f32_16x16x32_bf16 v[112:115], v[156:159], v[164:167], v[112:115]
	v_mfma_f32_16x16x32_bf16 v[108:111], v[128:131], v[182:185], v[108:111]
	v_mfma_f32_16x16x32_bf16 v[108:111], v[132:135], v[188:191], v[108:111]
	v_mfma_f32_16x16x32_bf16 v[100:103], v[144:147], v[182:185], v[100:103]
	v_mfma_f32_16x16x32_bf16 v[100:103], v[148:151], v[188:191], v[100:103]
	v_mfma_f32_16x16x32_bf16 v[104:107], v[136:139], v[182:185], v[104:107]
	v_mfma_f32_16x16x32_bf16 v[104:107], v[140:143], v[188:191], v[104:107]
	v_mfma_f32_16x16x32_bf16 v[96:99], v[152:155], v[182:185], v[96:99]
	v_mfma_f32_16x16x32_bf16 v[96:99], v[156:159], v[188:191], v[96:99]
	v_mfma_f32_16x16x32_bf16 v[92:95], v[128:131], v[192:195], v[92:95]
	v_mfma_f32_16x16x32_bf16 v[92:95], v[132:135], v[196:199], v[92:95]
	v_mfma_f32_16x16x32_bf16 v[84:87], v[144:147], v[192:195], v[84:87]
	v_mfma_f32_16x16x32_bf16 v[84:87], v[148:151], v[196:199], v[84:87]
	v_mfma_f32_16x16x32_bf16 v[88:91], v[136:139], v[192:195], v[88:91]
	v_mfma_f32_16x16x32_bf16 v[88:91], v[140:143], v[196:199], v[88:91]
	v_mfma_f32_16x16x32_bf16 v[80:83], v[152:155], v[192:195], v[80:83]
	v_mfma_f32_16x16x32_bf16 v[80:83], v[156:159], v[196:199], v[80:83]
	v_mfma_f32_16x16x32_bf16 v[76:79], v[128:131], v[200:203], v[76:79]
	v_mfma_f32_16x16x32_bf16 v[76:79], v[132:135], v[204:207], v[76:79]
	v_mfma_f32_16x16x32_bf16 v[68:71], v[144:147], v[200:203], v[68:71]
	v_mfma_f32_16x16x32_bf16 v[68:71], v[148:151], v[204:207], v[68:71]
	v_mfma_f32_16x16x32_bf16 v[72:75], v[136:139], v[200:203], v[72:75]
	v_mfma_f32_16x16x32_bf16 v[72:75], v[140:143], v[204:207], v[72:75]
	v_mfma_f32_16x16x32_bf16 v[64:67], v[152:155], v[200:203], v[64:67]
	v_mfma_f32_16x16x32_bf16 v[64:67], v[156:159], v[204:207], v[64:67]
	s_barrier
	s_add_i32 s67, s67, s24
	s_add_u32 s98, s82, 0x80
	s_addc_u32 s99, s83, 0
	s_mov_b32 m0, s67
	ds_read_b128 v[160:163], v187 offset:49152
	ds_read_b128 v[164:167], v187 offset:50176
	ds_read_b128 v[182:185], v187 offset:51200
	ds_read_b128 v[188:191], v187 offset:52224
	ds_read_b128 v[192:195], v187 offset:53248
	ds_read_b128 v[196:199], v187 offset:54272
	ds_read_b128 v[200:203], v187 offset:55296
	ds_read_b128 v[204:207], v187 offset:56320
	global_load_lds_dwordx4 v172, s[98:99]
	s_add_i32 m0, s67, 0x2000
	s_add_u32 s82, s82, 0x80080
	s_addc_u32 s83, s83, 0
	s_add_i32 s67, s90, s24
	global_load_lds_dwordx4 v168, s[98:99]
	s_mov_b32 m0, s67
	s_nop 0
	global_load_lds_dwordx4 v172, s[82:83]
	s_add_i32 m0, s67, 0x2000
	s_nop 0
	global_load_lds_dwordx4 v168, s[82:83]
	s_add_u32 s98, s84, 0xfff80080
	s_addc_u32 s99, s85, -1
	s_mov_b32 m0, s54
	s_nop 0
	global_load_lds_dwordx4 v174, s[98:99]
	s_mov_b32 m0, s55
	s_nop 0
	global_load_lds_dwordx4 v170, s[98:99]
	s_waitcnt vmcnt(8)
	s_waitcnt lgkmcnt(0)
	s_barrier
	s_waitcnt lgkmcnt(0)
	v_mfma_f32_16x16x32_bf16 v[60:63], v[128:131], v[160:163], v[60:63]
	v_mfma_f32_16x16x32_bf16 v[60:63], v[132:135], v[164:167], v[60:63]
	v_mfma_f32_16x16x32_bf16 v[52:55], v[144:147], v[160:163], v[52:55]
	v_mfma_f32_16x16x32_bf16 v[52:55], v[148:151], v[164:167], v[52:55]
	v_mfma_f32_16x16x32_bf16 v[56:59], v[136:139], v[160:163], v[56:59]
	v_mfma_f32_16x16x32_bf16 v[56:59], v[140:143], v[164:167], v[56:59]
	v_mfma_f32_16x16x32_bf16 v[48:51], v[152:155], v[160:163], v[48:51]
	v_mfma_f32_16x16x32_bf16 v[48:51], v[156:159], v[164:167], v[48:51]
	v_mfma_f32_16x16x32_bf16 v[44:47], v[128:131], v[182:185], v[44:47]
	v_mfma_f32_16x16x32_bf16 v[44:47], v[132:135], v[188:191], v[44:47]
	v_mfma_f32_16x16x32_bf16 v[36:39], v[144:147], v[182:185], v[36:39]
	v_mfma_f32_16x16x32_bf16 v[36:39], v[148:151], v[188:191], v[36:39]
	v_mfma_f32_16x16x32_bf16 v[40:43], v[136:139], v[182:185], v[40:43]
	v_mfma_f32_16x16x32_bf16 v[40:43], v[140:143], v[188:191], v[40:43]
	v_mfma_f32_16x16x32_bf16 v[32:35], v[152:155], v[182:185], v[32:35]
	v_mfma_f32_16x16x32_bf16 v[32:35], v[156:159], v[188:191], v[32:35]
	v_mfma_f32_16x16x32_bf16 v[28:31], v[128:131], v[192:195], v[28:31]
	v_mfma_f32_16x16x32_bf16 v[28:31], v[132:135], v[196:199], v[28:31]
	v_mfma_f32_16x16x32_bf16 v[20:23], v[144:147], v[192:195], v[20:23]
	v_mfma_f32_16x16x32_bf16 v[20:23], v[148:151], v[196:199], v[20:23]
	v_mfma_f32_16x16x32_bf16 v[24:27], v[136:139], v[192:195], v[24:27]
	v_mfma_f32_16x16x32_bf16 v[24:27], v[140:143], v[196:199], v[24:27]
	v_mfma_f32_16x16x32_bf16 v[16:19], v[152:155], v[192:195], v[16:19]
	v_mfma_f32_16x16x32_bf16 v[16:19], v[156:159], v[196:199], v[16:19]
	v_mfma_f32_16x16x32_bf16 v[12:15], v[128:131], v[200:203], v[12:15]
	v_mfma_f32_16x16x32_bf16 v[12:15], v[132:135], v[204:207], v[12:15]
	v_mfma_f32_16x16x32_bf16 v[4:7], v[144:147], v[200:203], v[4:7]
	v_mfma_f32_16x16x32_bf16 v[4:7], v[148:151], v[204:207], v[4:7]
	v_mfma_f32_16x16x32_bf16 v[8:11], v[136:139], v[200:203], v[8:11]
	v_mfma_f32_16x16x32_bf16 v[8:11], v[140:143], v[204:207], v[8:11]
	v_mfma_f32_16x16x32_bf16 v[0:3], v[152:155], v[200:203], v[0:3]
	v_mfma_f32_16x16x32_bf16 v[0:3], v[156:159], v[204:207], v[0:3]
	s_barrier
	s_add_i32 s89, s89, 2
	s_add_u32 s80, s80, 0x100
	s_addc_u32 s81, s81, 0
	s_add_u32 s87, s87, 0x100
	s_addc_u32 s88, s88, 0
.LBB0_385:
	s_add_u32 s67, s80, 0xfff80080
	s_addc_u32 s82, s81, -1
	s_add_i32 s90, 0, 0x10000
	s_cmp_eq_u32 s89, 28
	s_cselect_b32 s85, s73, s82
	s_cselect_b32 s84, s79, s67
	s_cselect_b32 s83, s23, s88
	s_cselect_b32 s82, s86, s87
	s_add_i32 s67, 0, 0x14000
	ds_read_b128 v[128:131], v169
	ds_read_b128 v[132:135], v169 offset:1024
	ds_read_b128 v[136:139], v169 offset:2048
	ds_read_b128 v[140:143], v169 offset:3072
	ds_read_b128 v[144:147], v169 offset:16384
	ds_read_b128 v[148:151], v169 offset:17408
	ds_read_b128 v[152:155], v169 offset:18432
	ds_read_b128 v[156:159], v169 offset:19456
	s_add_i32 m0, s29, 0xc000
	ds_read_b128 v[160:163], v187
	ds_read_b128 v[164:167], v187 offset:1024
	ds_read_b128 v[182:185], v187 offset:2048
	ds_read_b128 v[188:191], v187 offset:3072
	ds_read_b128 v[192:195], v187 offset:4096
	ds_read_b128 v[196:199], v187 offset:5120
	ds_read_b128 v[200:203], v187 offset:6144
	ds_read_b128 v[204:207], v187 offset:7168
	global_load_lds_dwordx4 v178, s[80:81]
	s_add_i32 m0, s29, 0xe000
	s_nop 0
	global_load_lds_dwordx4 v180, s[80:81]
	s_waitcnt vmcnt(8)
	s_waitcnt lgkmcnt(0)
	s_barrier
	s_waitcnt lgkmcnt(0)
	v_mfma_f32_16x16x32_bf16 v[124:127], v[128:131], v[160:163], v[124:127]
	v_mfma_f32_16x16x32_bf16 v[124:127], v[132:135], v[164:167], v[124:127]
	v_mfma_f32_16x16x32_bf16 v[116:119], v[144:147], v[160:163], v[116:119]
	v_mfma_f32_16x16x32_bf16 v[116:119], v[148:151], v[164:167], v[116:119]
	v_mfma_f32_16x16x32_bf16 v[120:123], v[136:139], v[160:163], v[120:123]
	v_mfma_f32_16x16x32_bf16 v[120:123], v[140:143], v[164:167], v[120:123]
	v_mfma_f32_16x16x32_bf16 v[112:115], v[152:155], v[160:163], v[112:115]
	v_mfma_f32_16x16x32_bf16 v[112:115], v[156:159], v[164:167], v[112:115]
	v_mfma_f32_16x16x32_bf16 v[108:111], v[128:131], v[182:185], v[108:111]
	v_mfma_f32_16x16x32_bf16 v[108:111], v[132:135], v[188:191], v[108:111]
	v_mfma_f32_16x16x32_bf16 v[100:103], v[144:147], v[182:185], v[100:103]
	v_mfma_f32_16x16x32_bf16 v[100:103], v[148:151], v[188:191], v[100:103]
	v_mfma_f32_16x16x32_bf16 v[104:107], v[136:139], v[182:185], v[104:107]
	v_mfma_f32_16x16x32_bf16 v[104:107], v[140:143], v[188:191], v[104:107]
	v_mfma_f32_16x16x32_bf16 v[96:99], v[152:155], v[182:185], v[96:99]
	v_mfma_f32_16x16x32_bf16 v[96:99], v[156:159], v[188:191], v[96:99]
	v_mfma_f32_16x16x32_bf16 v[92:95], v[128:131], v[192:195], v[92:95]
	v_mfma_f32_16x16x32_bf16 v[92:95], v[132:135], v[196:199], v[92:95]
	v_mfma_f32_16x16x32_bf16 v[84:87], v[144:147], v[192:195], v[84:87]
	v_mfma_f32_16x16x32_bf16 v[84:87], v[148:151], v[196:199], v[84:87]
	v_mfma_f32_16x16x32_bf16 v[88:91], v[136:139], v[192:195], v[88:91]
	v_mfma_f32_16x16x32_bf16 v[88:91], v[140:143], v[196:199], v[88:91]
	v_mfma_f32_16x16x32_bf16 v[80:83], v[152:155], v[192:195], v[80:83]
	v_mfma_f32_16x16x32_bf16 v[80:83], v[156:159], v[196:199], v[80:83]
	v_mfma_f32_16x16x32_bf16 v[76:79], v[128:131], v[200:203], v[76:79]
	v_mfma_f32_16x16x32_bf16 v[76:79], v[132:135], v[204:207], v[76:79]
	v_mfma_f32_16x16x32_bf16 v[68:71], v[144:147], v[200:203], v[68:71]
	v_mfma_f32_16x16x32_bf16 v[68:71], v[148:151], v[204:207], v[68:71]
	v_mfma_f32_16x16x32_bf16 v[72:75], v[136:139], v[200:203], v[72:75]
	v_mfma_f32_16x16x32_bf16 v[72:75], v[140:143], v[204:207], v[72:75]
	v_mfma_f32_16x16x32_bf16 v[64:67], v[152:155], v[200:203], v[64:67]
	v_mfma_f32_16x16x32_bf16 v[64:67], v[156:159], v[204:207], v[64:67]
	s_barrier
	s_add_i32 s90, s90, s24
	s_mov_b32 m0, s90
	ds_read_b128 v[160:163], v187 offset:16384
	ds_read_b128 v[164:167], v187 offset:17408
	ds_read_b128 v[182:185], v187 offset:18432
	ds_read_b128 v[188:191], v187 offset:19456
	ds_read_b128 v[192:195], v187 offset:20480
	ds_read_b128 v[196:199], v187 offset:21504
	ds_read_b128 v[200:203], v187 offset:22528
	ds_read_b128 v[204:207], v187 offset:23552
	global_load_lds_dwordx4 v172, s[82:83]
	s_add_i32 m0, s90, 0x2000
	s_add_u32 s90, s82, 0x80000
	s_addc_u32 s91, s83, 0
	s_add_i32 s67, s67, s24
	global_load_lds_dwordx4 v168, s[82:83]
	s_mov_b32 m0, s67
	s_nop 0
	global_load_lds_dwordx4 v172, s[90:91]
	s_add_i32 m0, s67, 0x2000
	s_nop 0
	global_load_lds_dwordx4 v168, s[90:91]
	s_mov_b32 m0, s29
	s_nop 0
	global_load_lds_dwordx4 v174, s[84:85]
	s_mov_b32 m0, s34
	s_nop 0
	global_load_lds_dwordx4 v170, s[84:85]
	s_waitcnt vmcnt(8)
	s_waitcnt lgkmcnt(0)
	s_barrier
	s_waitcnt lgkmcnt(0)
	v_mfma_f32_16x16x32_bf16 v[60:63], v[128:131], v[160:163], v[60:63]
	v_mfma_f32_16x16x32_bf16 v[60:63], v[132:135], v[164:167], v[60:63]
	v_mfma_f32_16x16x32_bf16 v[52:55], v[144:147], v[160:163], v[52:55]
	v_mfma_f32_16x16x32_bf16 v[52:55], v[148:151], v[164:167], v[52:55]
	v_mfma_f32_16x16x32_bf16 v[56:59], v[136:139], v[160:163], v[56:59]
	v_mfma_f32_16x16x32_bf16 v[56:59], v[140:143], v[164:167], v[56:59]
	v_mfma_f32_16x16x32_bf16 v[48:51], v[152:155], v[160:163], v[48:51]
	v_mfma_f32_16x16x32_bf16 v[48:51], v[156:159], v[164:167], v[48:51]
	v_mfma_f32_16x16x32_bf16 v[44:47], v[128:131], v[182:185], v[44:47]
	v_mfma_f32_16x16x32_bf16 v[44:47], v[132:135], v[188:191], v[44:47]
	v_mfma_f32_16x16x32_bf16 v[36:39], v[144:147], v[182:185], v[36:39]
	v_mfma_f32_16x16x32_bf16 v[36:39], v[148:151], v[188:191], v[36:39]
	v_mfma_f32_16x16x32_bf16 v[40:43], v[136:139], v[182:185], v[40:43]
	v_mfma_f32_16x16x32_bf16 v[40:43], v[140:143], v[188:191], v[40:43]
	v_mfma_f32_16x16x32_bf16 v[32:35], v[152:155], v[182:185], v[32:35]
	v_mfma_f32_16x16x32_bf16 v[32:35], v[156:159], v[188:191], v[32:35]
	v_mfma_f32_16x16x32_bf16 v[28:31], v[128:131], v[192:195], v[28:31]
	v_mfma_f32_16x16x32_bf16 v[28:31], v[132:135], v[196:199], v[28:31]
	v_mfma_f32_16x16x32_bf16 v[20:23], v[144:147], v[192:195], v[20:23]
	v_mfma_f32_16x16x32_bf16 v[20:23], v[148:151], v[196:199], v[20:23]
	v_mfma_f32_16x16x32_bf16 v[24:27], v[136:139], v[192:195], v[24:27]
	v_mfma_f32_16x16x32_bf16 v[24:27], v[140:143], v[196:199], v[24:27]
	v_mfma_f32_16x16x32_bf16 v[16:19], v[152:155], v[192:195], v[16:19]
	v_mfma_f32_16x16x32_bf16 v[16:19], v[156:159], v[196:199], v[16:19]
	v_mfma_f32_16x16x32_bf16 v[12:15], v[128:131], v[200:203], v[12:15]
	v_mfma_f32_16x16x32_bf16 v[12:15], v[132:135], v[204:207], v[12:15]
	v_mfma_f32_16x16x32_bf16 v[4:7], v[144:147], v[200:203], v[4:7]
	v_mfma_f32_16x16x32_bf16 v[4:7], v[148:151], v[204:207], v[4:7]
	v_mfma_f32_16x16x32_bf16 v[8:11], v[136:139], v[200:203], v[8:11]
	v_mfma_f32_16x16x32_bf16 v[8:11], v[140:143], v[204:207], v[8:11]
	v_mfma_f32_16x16x32_bf16 v[0:3], v[152:155], v[200:203], v[0:3]
	v_mfma_f32_16x16x32_bf16 v[0:3], v[156:159], v[204:207], v[0:3]
	s_barrier
	s_add_i32 s67, 0, 0x18000
	s_add_i32 s90, 0, 0x1c000
	ds_read_b128 v[128:131], v169 offset:32768
	ds_read_b128 v[132:135], v169 offset:33792
	ds_read_b128 v[136:139], v169 offset:34816
	ds_read_b128 v[140:143], v169 offset:35840
	ds_read_b128 v[144:147], v169 offset:49152
	ds_read_b128 v[148:151], v169 offset:50176
	ds_read_b128 v[152:155], v169 offset:51200
	ds_read_b128 v[156:159], v169 offset:52224
	s_add_u32 s84, s84, 0x80000
	s_addc_u32 s85, s85, 0
	s_mov_b32 m0, s35
	ds_read_b128 v[160:163], v187 offset:32768
	ds_read_b128 v[164:167], v187 offset:33792
	ds_read_b128 v[182:185], v187 offset:34816
	ds_read_b128 v[188:191], v187 offset:35840
	ds_read_b128 v[192:195], v187 offset:36864
	ds_read_b128 v[196:199], v187 offset:37888
	ds_read_b128 v[200:203], v187 offset:38912
	ds_read_b128 v[204:207], v187 offset:39936
	global_load_lds_dwordx4 v174, s[84:85]
	s_mov_b32 m0, s38
	s_nop 0
	global_load_lds_dwordx4 v170, s[84:85]
	s_waitcnt vmcnt(8)
	s_waitcnt lgkmcnt(0)
	s_barrier
	s_waitcnt lgkmcnt(0)
	v_mfma_f32_16x16x32_bf16 v[124:127], v[128:131], v[160:163], v[124:127]
	v_mfma_f32_16x16x32_bf16 v[124:127], v[132:135], v[164:167], v[124:127]
	v_mfma_f32_16x16x32_bf16 v[116:119], v[144:147], v[160:163], v[116:119]
	v_mfma_f32_16x16x32_bf16 v[116:119], v[148:151], v[164:167], v[116:119]
	v_mfma_f32_16x16x32_bf16 v[120:123], v[136:139], v[160:163], v[120:123]
	v_mfma_f32_16x16x32_bf16 v[120:123], v[140:143], v[164:167], v[120:123]
	v_mfma_f32_16x16x32_bf16 v[112:115], v[152:155], v[160:163], v[112:115]
	v_mfma_f32_16x16x32_bf16 v[112:115], v[156:159], v[164:167], v[112:115]
	v_mfma_f32_16x16x32_bf16 v[108:111], v[128:131], v[182:185], v[108:111]
	v_mfma_f32_16x16x32_bf16 v[108:111], v[132:135], v[188:191], v[108:111]
	v_mfma_f32_16x16x32_bf16 v[100:103], v[144:147], v[182:185], v[100:103]
	v_mfma_f32_16x16x32_bf16 v[100:103], v[148:151], v[188:191], v[100:103]
	v_mfma_f32_16x16x32_bf16 v[104:107], v[136:139], v[182:185], v[104:107]
	v_mfma_f32_16x16x32_bf16 v[104:107], v[140:143], v[188:191], v[104:107]
	v_mfma_f32_16x16x32_bf16 v[96:99], v[152:155], v[182:185], v[96:99]
	v_mfma_f32_16x16x32_bf16 v[96:99], v[156:159], v[188:191], v[96:99]
	v_mfma_f32_16x16x32_bf16 v[92:95], v[128:131], v[192:195], v[92:95]
	v_mfma_f32_16x16x32_bf16 v[92:95], v[132:135], v[196:199], v[92:95]
	v_mfma_f32_16x16x32_bf16 v[84:87], v[144:147], v[192:195], v[84:87]
	v_mfma_f32_16x16x32_bf16 v[84:87], v[148:151], v[196:199], v[84:87]
	v_mfma_f32_16x16x32_bf16 v[88:91], v[136:139], v[192:195], v[88:91]
	v_mfma_f32_16x16x32_bf16 v[88:91], v[140:143], v[196:199], v[88:91]
	v_mfma_f32_16x16x32_bf16 v[80:83], v[152:155], v[192:195], v[80:83]
	v_mfma_f32_16x16x32_bf16 v[80:83], v[156:159], v[196:199], v[80:83]
	v_mfma_f32_16x16x32_bf16 v[76:79], v[128:131], v[200:203], v[76:79]
	v_mfma_f32_16x16x32_bf16 v[76:79], v[132:135], v[204:207], v[76:79]
	v_mfma_f32_16x16x32_bf16 v[68:71], v[144:147], v[200:203], v[68:71]
	v_mfma_f32_16x16x32_bf16 v[68:71], v[148:151], v[204:207], v[68:71]
	v_mfma_f32_16x16x32_bf16 v[72:75], v[136:139], v[200:203], v[72:75]
	v_mfma_f32_16x16x32_bf16 v[72:75], v[140:143], v[204:207], v[72:75]
	v_mfma_f32_16x16x32_bf16 v[64:67], v[152:155], v[200:203], v[64:67]
	v_mfma_f32_16x16x32_bf16 v[64:67], v[156:159], v[204:207], v[64:67]
	s_barrier
	s_add_i32 s67, s67, s24
	s_add_u32 s98, s82, 0x80
	s_addc_u32 s99, s83, 0
	s_mov_b32 m0, s67
	ds_read_b128 v[160:163], v187 offset:49152
	ds_read_b128 v[164:167], v187 offset:50176
	ds_read_b128 v[182:185], v187 offset:51200
	ds_read_b128 v[188:191], v187 offset:52224
	ds_read_b128 v[192:195], v187 offset:53248
	ds_read_b128 v[196:199], v187 offset:54272
	ds_read_b128 v[200:203], v187 offset:55296
	ds_read_b128 v[204:207], v187 offset:56320
	global_load_lds_dwordx4 v172, s[98:99]
	s_add_i32 m0, s67, 0x2000
	s_add_u32 s82, s82, 0x80080
	s_addc_u32 s83, s83, 0
	s_add_i32 s67, s90, s24
	global_load_lds_dwordx4 v168, s[98:99]
	s_mov_b32 m0, s67
	s_nop 0
	global_load_lds_dwordx4 v172, s[82:83]
	s_add_i32 m0, s67, 0x2000
	s_nop 0
	global_load_lds_dwordx4 v168, s[82:83]
	s_add_u32 s98, s84, 0xfff80080
	s_addc_u32 s99, s85, -1
	s_mov_b32 m0, s54
	s_nop 0
	global_load_lds_dwordx4 v174, s[98:99]
	s_mov_b32 m0, s55
	s_nop 0
	global_load_lds_dwordx4 v170, s[98:99]
	s_waitcnt vmcnt(8)
	s_waitcnt lgkmcnt(0)
	s_barrier
	s_waitcnt lgkmcnt(0)
	v_mfma_f32_16x16x32_bf16 v[60:63], v[128:131], v[160:163], v[60:63]
	v_mfma_f32_16x16x32_bf16 v[60:63], v[132:135], v[164:167], v[60:63]
	v_mfma_f32_16x16x32_bf16 v[52:55], v[144:147], v[160:163], v[52:55]
	v_mfma_f32_16x16x32_bf16 v[52:55], v[148:151], v[164:167], v[52:55]
	v_mfma_f32_16x16x32_bf16 v[56:59], v[136:139], v[160:163], v[56:59]
	v_mfma_f32_16x16x32_bf16 v[56:59], v[140:143], v[164:167], v[56:59]
	v_mfma_f32_16x16x32_bf16 v[48:51], v[152:155], v[160:163], v[48:51]
	v_mfma_f32_16x16x32_bf16 v[48:51], v[156:159], v[164:167], v[48:51]
	v_mfma_f32_16x16x32_bf16 v[44:47], v[128:131], v[182:185], v[44:47]
	v_mfma_f32_16x16x32_bf16 v[44:47], v[132:135], v[188:191], v[44:47]
	v_mfma_f32_16x16x32_bf16 v[36:39], v[144:147], v[182:185], v[36:39]
	v_mfma_f32_16x16x32_bf16 v[36:39], v[148:151], v[188:191], v[36:39]
	v_mfma_f32_16x16x32_bf16 v[40:43], v[136:139], v[182:185], v[40:43]
	v_mfma_f32_16x16x32_bf16 v[40:43], v[140:143], v[188:191], v[40:43]
	v_mfma_f32_16x16x32_bf16 v[32:35], v[152:155], v[182:185], v[32:35]
	v_mfma_f32_16x16x32_bf16 v[32:35], v[156:159], v[188:191], v[32:35]
	v_mfma_f32_16x16x32_bf16 v[28:31], v[128:131], v[192:195], v[28:31]
	v_mfma_f32_16x16x32_bf16 v[28:31], v[132:135], v[196:199], v[28:31]
	v_mfma_f32_16x16x32_bf16 v[20:23], v[144:147], v[192:195], v[20:23]
	v_mfma_f32_16x16x32_bf16 v[20:23], v[148:151], v[196:199], v[20:23]
	v_mfma_f32_16x16x32_bf16 v[24:27], v[136:139], v[192:195], v[24:27]
	v_mfma_f32_16x16x32_bf16 v[24:27], v[140:143], v[196:199], v[24:27]
	v_mfma_f32_16x16x32_bf16 v[16:19], v[152:155], v[192:195], v[16:19]
	v_mfma_f32_16x16x32_bf16 v[16:19], v[156:159], v[196:199], v[16:19]
	v_mfma_f32_16x16x32_bf16 v[12:15], v[128:131], v[200:203], v[12:15]
	v_mfma_f32_16x16x32_bf16 v[12:15], v[132:135], v[204:207], v[12:15]
	v_mfma_f32_16x16x32_bf16 v[4:7], v[144:147], v[200:203], v[4:7]
	v_mfma_f32_16x16x32_bf16 v[4:7], v[148:151], v[204:207], v[4:7]
	v_mfma_f32_16x16x32_bf16 v[8:11], v[136:139], v[200:203], v[8:11]
	v_mfma_f32_16x16x32_bf16 v[8:11], v[140:143], v[204:207], v[8:11]
	v_mfma_f32_16x16x32_bf16 v[0:3], v[152:155], v[200:203], v[0:3]
	v_mfma_f32_16x16x32_bf16 v[0:3], v[156:159], v[204:207], v[0:3]
	s_barrier
	s_add_i32 s89, s89, 2
	s_add_u32 s80, s80, 0x100
	s_addc_u32 s81, s81, 0
	s_add_u32 s87, s87, 0x100
	s_addc_u32 s88, s88, 0
	s_cmp_gt_u32 s89, 29
	s_cbranch_scc0 .LBB0_385
	s_and_b64 vcc, exec, s[18:19]
	s_cbranch_vccz .LBB0_388
	s_barrier

.LBB0_594:
	s_ashr_i32 s81, s80, 31
	s_lshl_b64 s[84:85], s[80:81], 20
	s_add_u32 s84, s29, s84
	s_addc_u32 s85, s34, s85
	s_and_b64 s[86:87], s[82:83], exec
	s_cselect_b32 s81, s85, s95
	s_cselect_b32 vcc_lo, s84, s94
	s_ashr_i32 s79, s78, 31
	s_lshl_b64 s[86:87], s[78:79], 20
	s_add_u32 s86, s35, s86
	s_addc_u32 s87, s38, s87
	s_and_b64 s[2:3], s[82:83], exec
	s_cselect_b32 s79, s87, s93
	s_cselect_b32 vcc_hi, s86, s92
	s_lshl_b32 s88, s88, 8
	s_ashr_i32 s89, s88, 31
	s_lshl_b64 s[2:3], s[88:89], 2
	s_add_u32 s2, s90, s2
	s_addc_u32 s3, s91, s3
	s_add_i32 m0, s14, s41
	s_add_u32 s90, s94, 0x80080
	global_load_lds_dwordx4 v239, s[2:3]
	s_addc_u32 s91, s95, 0
	s_add_u32 s89, s92, 0x100
	s_addc_u32 s14, s93, 0
	s_mov_b32 s20, -2
	s_waitcnt vmcnt(0)
	v_add_u32_e32 v192, 0x10000, v238
	s_add_u32 s2, s90, 0xfff80080
	s_addc_u32 s3, s91, -1
	s_add_i32 s67, 0, 0x10000
	s_cmp_eq_u32 s20, 28
	s_cselect_b32 s95, s81, s3
	s_cselect_b32 s94, vcc_lo, s2
	s_cselect_b32 s93, s79, s14
	s_cselect_b32 s92, vcc_hi, s89
	s_add_i32 s76, 0, 0x14000
	ds_read_b128 v[64:67], v192
	ds_read_b128 v[72:75], v192 offset:1024
	ds_read_b128 v[88:91], v192 offset:2048
	ds_read_b128 v[96:99], v192 offset:3072
	ds_read_b128 v[108:111], v192 offset:16384
	ds_read_b128 v[116:119], v192 offset:17408
	ds_read_b128 v[128:131], v192 offset:18432
	ds_read_b128 v[140:143], v192 offset:19456
	s_add_i32 m0, s39, 0xc000
	ds_read_b128 v[152:155], v240
	ds_read_b128 v[156:159], v240 offset:1024
	ds_read_b128 v[160:163], v240 offset:2048
	ds_read_b128 v[164:167], v240 offset:3072
	ds_read_b128 v[168:171], v240 offset:4096
	ds_read_b128 v[180:183], v240 offset:5120
	ds_read_b128 v[184:187], v240 offset:6144
	ds_read_b128 v[188:191], v240 offset:7168
	global_load_lds_dwordx4 v230, s[90:91]
	s_add_i32 m0, s39, 0xe000
	s_nop 0
	global_load_lds_dwordx4 v232, s[90:91]
	s_cmp_lg_u32 s54, 1
	s_cbranch_scc1 .Lds2_0
	s_waitcnt vmcnt(8)

.Lds2_1:
	s_waitcnt lgkmcnt(0)
	s_barrier
	s_waitcnt lgkmcnt(0)
	v_mfma_f32_16x16x32_bf16 v[60:63], v[64:67], v[152:155], 0
	v_mfma_f32_16x16x32_bf16 v[60:63], v[72:75], v[156:159], v[60:63]
	v_mfma_f32_16x16x32_bf16 v[52:55], v[108:111], v[152:155], 0
	v_mfma_f32_16x16x32_bf16 v[52:55], v[116:119], v[156:159], v[52:55]
	v_mfma_f32_16x16x32_bf16 v[56:59], v[88:91], v[152:155], 0
	v_mfma_f32_16x16x32_bf16 v[56:59], v[96:99], v[156:159], v[56:59]
	v_mfma_f32_16x16x32_bf16 v[48:51], v[128:131], v[152:155], 0
	v_mfma_f32_16x16x32_bf16 v[48:51], v[140:143], v[156:159], v[48:51]
	v_mfma_f32_16x16x32_bf16 v[44:47], v[64:67], v[160:163], 0
	v_mfma_f32_16x16x32_bf16 v[44:47], v[72:75], v[164:167], v[44:47]
	v_mfma_f32_16x16x32_bf16 v[36:39], v[108:111], v[160:163], 0
	v_mfma_f32_16x16x32_bf16 v[36:39], v[116:119], v[164:167], v[36:39]
	v_mfma_f32_16x16x32_bf16 v[40:43], v[88:91], v[160:163], 0
	v_mfma_f32_16x16x32_bf16 v[40:43], v[96:99], v[164:167], v[40:43]
	v_mfma_f32_16x16x32_bf16 v[32:35], v[128:131], v[160:163], 0
	v_mfma_f32_16x16x32_bf16 v[32:35], v[140:143], v[164:167], v[32:35]
	v_mfma_f32_16x16x32_bf16 v[28:31], v[64:67], v[168:171], 0
	v_mfma_f32_16x16x32_bf16 v[28:31], v[72:75], v[180:183], v[28:31]
	v_mfma_f32_16x16x32_bf16 v[20:23], v[108:111], v[168:171], 0
	v_mfma_f32_16x16x32_bf16 v[20:23], v[116:119], v[180:183], v[20:23]
	v_mfma_f32_16x16x32_bf16 v[24:27], v[88:91], v[168:171], 0
	v_mfma_f32_16x16x32_bf16 v[24:27], v[96:99], v[180:183], v[24:27]
	v_mfma_f32_16x16x32_bf16 v[16:19], v[128:131], v[168:171], 0
	v_mfma_f32_16x16x32_bf16 v[16:19], v[140:143], v[180:183], v[16:19]
	v_mfma_f32_16x16x32_bf16 v[12:15], v[64:67], v[184:187], 0
	v_mfma_f32_16x16x32_bf16 v[12:15], v[72:75], v[188:191], v[12:15]
	v_mfma_f32_16x16x32_bf16 v[4:7], v[108:111], v[184:187], 0
	v_mfma_f32_16x16x32_bf16 v[4:7], v[116:119], v[188:191], v[4:7]
	v_mfma_f32_16x16x32_bf16 v[8:11], v[88:91], v[184:187], 0
	v_mfma_f32_16x16x32_bf16 v[8:11], v[96:99], v[188:191], v[8:11]
	v_mfma_f32_16x16x32_bf16 v[0:3], v[128:131], v[184:187], 0
	v_mfma_f32_16x16x32_bf16 v[0:3], v[140:143], v[188:191], v[0:3]
	s_barrier
	s_add_i32 s67, 0, 0x18000
	s_add_i32 s76, 0, 0x1c000
	ds_read_b128 v[64:67], v192 offset:32768
	ds_read_b128 v[72:75], v192 offset:33792
	ds_read_b128 v[88:91], v192 offset:34816
	ds_read_b128 v[96:99], v192 offset:35840
	ds_read_b128 v[108:111], v192 offset:49152
	ds_read_b128 v[116:119], v192 offset:50176
	ds_read_b128 v[128:131], v192 offset:51200
	ds_read_b128 v[140:143], v192 offset:52224
	s_add_u32 s2, s94, 0x80000
	s_addc_u32 s3, s95, 0
	s_mov_b32 m0, s55
	ds_read_b128 v[152:155], v240 offset:32768
	ds_read_b128 v[156:159], v240 offset:33792
	ds_read_b128 v[160:163], v240 offset:34816
	ds_read_b128 v[164:167], v240 offset:35840
	ds_read_b128 v[168:171], v240 offset:36864
	ds_read_b128 v[180:183], v240 offset:37888
	ds_read_b128 v[184:187], v240 offset:38912
	ds_read_b128 v[188:191], v240 offset:39936
	global_load_lds_dwordx4 v224, s[2:3]
	s_mov_b32 m0, s56
	s_nop 0
	global_load_lds_dwordx4 v226, s[2:3]
	s_waitcnt vmcnt(8)
	s_waitcnt lgkmcnt(0)
	s_barrier
	s_waitcnt lgkmcnt(0)
	v_mfma_f32_16x16x32_bf16 v[176:179], v[64:67], v[152:155], v[176:179]
	v_mfma_f32_16x16x32_bf16 v[176:179], v[72:75], v[156:159], v[176:179]
	v_mfma_f32_16x16x32_bf16 v[148:151], v[108:111], v[152:155], v[148:151]
	v_mfma_f32_16x16x32_bf16 v[148:151], v[116:119], v[156:159], v[148:151]
	v_mfma_f32_16x16x32_bf16 v[172:175], v[88:91], v[152:155], v[172:175]
	v_mfma_f32_16x16x32_bf16 v[172:175], v[96:99], v[156:159], v[172:175]
	v_mfma_f32_16x16x32_bf16 v[144:147], v[128:131], v[152:155], v[144:147]
	v_mfma_f32_16x16x32_bf16 v[144:147], v[140:143], v[156:159], v[144:147]
	v_mfma_f32_16x16x32_bf16 v[136:139], v[64:67], v[160:163], v[136:139]
	v_mfma_f32_16x16x32_bf16 v[136:139], v[72:75], v[164:167], v[136:139]
	v_mfma_f32_16x16x32_bf16 v[124:127], v[108:111], v[160:163], v[124:127]
	v_mfma_f32_16x16x32_bf16 v[124:127], v[116:119], v[164:167], v[124:127]
	v_mfma_f32_16x16x32_bf16 v[132:135], v[88:91], v[160:163], v[132:135]
	v_mfma_f32_16x16x32_bf16 v[132:135], v[96:99], v[164:167], v[132:135]
	v_mfma_f32_16x16x32_bf16 v[120:123], v[128:131], v[160:163], v[120:123]
	v_mfma_f32_16x16x32_bf16 v[120:123], v[140:143], v[164:167], v[120:123]
	v_mfma_f32_16x16x32_bf16 v[112:115], v[64:67], v[168:171], v[112:115]
	v_mfma_f32_16x16x32_bf16 v[112:115], v[72:75], v[180:183], v[112:115]
	v_mfma_f32_16x16x32_bf16 v[100:103], v[108:111], v[168:171], v[100:103]
	v_mfma_f32_16x16x32_bf16 v[100:103], v[116:119], v[180:183], v[100:103]
	v_mfma_f32_16x16x32_bf16 v[104:107], v[88:91], v[168:171], v[104:107]
	v_mfma_f32_16x16x32_bf16 v[104:107], v[96:99], v[180:183], v[104:107]
	v_mfma_f32_16x16x32_bf16 v[92:95], v[128:131], v[168:171], v[92:95]
	v_mfma_f32_16x16x32_bf16 v[92:95], v[140:143], v[180:183], v[92:95]
	v_mfma_f32_16x16x32_bf16 v[84:87], v[64:67], v[184:187], v[84:87]
	v_mfma_f32_16x16x32_bf16 v[84:87], v[72:75], v[188:191], v[84:87]
	v_mfma_f32_16x16x32_bf16 v[76:79], v[108:111], v[184:187], v[76:79]
	v_mfma_f32_16x16x32_bf16 v[76:79], v[116:119], v[188:191], v[76:79]
	v_mfma_f32_16x16x32_bf16 v[80:83], v[88:91], v[184:187], v[80:83]
	v_mfma_f32_16x16x32_bf16 v[80:83], v[96:99], v[188:191], v[80:83]
	v_mfma_f32_16x16x32_bf16 v[68:71], v[128:131], v[184:187], v[68:71]
	v_mfma_f32_16x16x32_bf16 v[68:71], v[140:143], v[188:191], v[68:71]
	s_barrier
	s_add_i32 s2, s67, s28
	s_add_u32 s98, s92, 0x80
	s_addc_u32 s99, s93, 0
	s_mov_b32 m0, s2
	ds_read_b128 v[152:155], v240 offset:49152
	ds_read_b128 v[156:159], v240 offset:50176
	ds_read_b128 v[160:163], v240 offset:51200
	ds_read_b128 v[164:167], v240 offset:52224
	ds_read_b128 v[168:171], v240 offset:53248
	ds_read_b128 v[180:183], v240 offset:54272
	ds_read_b128 v[184:187], v240 offset:55296
	ds_read_b128 v[188:191], v240 offset:56320
	global_load_lds_dwordx4 v216, s[98:99]
	s_add_i32 m0, s2, 0x2000
	s_add_u32 s2, s92, 0x80080
	s_addc_u32 s3, s93, 0
	s_add_i32 s67, s76, s28
	global_load_lds_dwordx4 v228, s[98:99]
	s_mov_b32 m0, s67
	s_nop 0
	global_load_lds_dwordx4 v216, s[2:3]
	s_add_i32 m0, s67, 0x2000
	s_nop 0
	global_load_lds_dwordx4 v228, s[2:3]
	s_add_u32 s98, s94, 0x80
	s_addc_u32 s99, s95, 0
	s_mov_b32 m0, s70
	s_nop 0
	global_load_lds_dwordx4 v224, s[98:99]
	s_mov_b32 m0, s71
	s_nop 0
	global_load_lds_dwordx4 v226, s[98:99]
	s_waitcnt vmcnt(8)
	s_waitcnt lgkmcnt(0)
	s_barrier
	s_waitcnt lgkmcnt(0)
	v_mfma_f32_16x16x32_bf16 v[60:63], v[64:67], v[152:155], v[60:63]
	v_mfma_f32_16x16x32_bf16 v[60:63], v[72:75], v[156:159], v[60:63]
	v_mfma_f32_16x16x32_bf16 v[52:55], v[108:111], v[152:155], v[52:55]
	v_mfma_f32_16x16x32_bf16 v[52:55], v[116:119], v[156:159], v[52:55]
	v_mfma_f32_16x16x32_bf16 v[56:59], v[88:91], v[152:155], v[56:59]
	v_mfma_f32_16x16x32_bf16 v[56:59], v[96:99], v[156:159], v[56:59]
	v_mfma_f32_16x16x32_bf16 v[48:51], v[128:131], v[152:155], v[48:51]
	v_mfma_f32_16x16x32_bf16 v[48:51], v[140:143], v[156:159], v[48:51]
	v_mfma_f32_16x16x32_bf16 v[44:47], v[64:67], v[160:163], v[44:47]
	v_mfma_f32_16x16x32_bf16 v[44:47], v[72:75], v[164:167], v[44:47]
	v_mfma_f32_16x16x32_bf16 v[36:39], v[108:111], v[160:163], v[36:39]
	v_mfma_f32_16x16x32_bf16 v[36:39], v[116:119], v[164:167], v[36:39]
	v_mfma_f32_16x16x32_bf16 v[40:43], v[88:91], v[160:163], v[40:43]
	v_mfma_f32_16x16x32_bf16 v[40:43], v[96:99], v[164:167], v[40:43]
	v_mfma_f32_16x16x32_bf16 v[32:35], v[128:131], v[160:163], v[32:35]
	v_mfma_f32_16x16x32_bf16 v[32:35], v[140:143], v[164:167], v[32:35]
	v_mfma_f32_16x16x32_bf16 v[28:31], v[64:67], v[168:171], v[28:31]
	v_mfma_f32_16x16x32_bf16 v[28:31], v[72:75], v[180:183], v[28:31]
	v_mfma_f32_16x16x32_bf16 v[20:23], v[108:111], v[168:171], v[20:23]
	v_mfma_f32_16x16x32_bf16 v[20:23], v[116:119], v[180:183], v[20:23]
	v_mfma_f32_16x16x32_bf16 v[24:27], v[88:91], v[168:171], v[24:27]
	v_mfma_f32_16x16x32_bf16 v[24:27], v[96:99], v[180:183], v[24:27]
	v_mfma_f32_16x16x32_bf16 v[16:19], v[128:131], v[168:171], v[16:19]
	v_mfma_f32_16x16x32_bf16 v[16:19], v[140:143], v[180:183], v[16:19]
	v_mfma_f32_16x16x32_bf16 v[12:15], v[64:67], v[184:187], v[12:15]
	v_mfma_f32_16x16x32_bf16 v[12:15], v[72:75], v[188:191], v[12:15]
	v_mfma_f32_16x16x32_bf16 v[4:7], v[108:111], v[184:187], v[4:7]
	v_mfma_f32_16x16x32_bf16 v[4:7], v[116:119], v[188:191], v[4:7]
	v_mfma_f32_16x16x32_bf16 v[8:11], v[88:91], v[184:187], v[8:11]
	v_mfma_f32_16x16x32_bf16 v[8:11], v[96:99], v[188:191], v[8:11]
	v_mfma_f32_16x16x32_bf16 v[0:3], v[128:131], v[184:187], v[0:3]
	v_mfma_f32_16x16x32_bf16 v[0:3], v[140:143], v[188:191], v[0:3]
	s_barrier
	s_add_i32 s20, s20, 2
	s_add_u32 s90, s90, 0x100
	s_addc_u32 s91, s91, 0
	s_add_u32 s89, s89, 0x100
	s_addc_u32 s14, s14, 0
.LBB0_595:
	s_add_u32 s2, s90, 0xfff80080
	s_addc_u32 s3, s91, -1
	s_add_i32 s67, 0, 0x10000
	s_cmp_eq_u32 s20, 28
	s_cselect_b32 s95, s81, s3
	s_cselect_b32 s94, vcc_lo, s2
	s_cselect_b32 s93, s79, s14
	s_cselect_b32 s92, vcc_hi, s89
	s_add_i32 s76, 0, 0x14000
	ds_read_b128 v[64:67], v192
	ds_read_b128 v[72:75], v192 offset:1024
	ds_read_b128 v[88:91], v192 offset:2048
	ds_read_b128 v[96:99], v192 offset:3072
	ds_read_b128 v[108:111], v192 offset:16384
	ds_read_b128 v[116:119], v192 offset:17408
	ds_read_b128 v[128:131], v192 offset:18432
	ds_read_b128 v[140:143], v192 offset:19456
	s_add_i32 m0, s39, 0xc000
	ds_read_b128 v[152:155], v240
	ds_read_b128 v[156:159], v240 offset:1024
	ds_read_b128 v[160:163], v240 offset:2048
	ds_read_b128 v[164:167], v240 offset:3072
	ds_read_b128 v[168:171], v240 offset:4096
	ds_read_b128 v[180:183], v240 offset:5120
	ds_read_b128 v[184:187], v240 offset:6144
	ds_read_b128 v[188:191], v240 offset:7168
	global_load_lds_dwordx4 v230, s[90:91]
	s_add_i32 m0, s39, 0xe000
	s_nop 0
	global_load_lds_dwordx4 v232, s[90:91]
	s_waitcnt vmcnt(8)
	s_waitcnt lgkmcnt(0)
	s_barrier
	s_waitcnt lgkmcnt(0)
	v_mfma_f32_16x16x32_bf16 v[176:179], v[64:67], v[152:155], v[176:179]
	v_mfma_f32_16x16x32_bf16 v[176:179], v[72:75], v[156:159], v[176:179]
	v_mfma_f32_16x16x32_bf16 v[148:151], v[108:111], v[152:155], v[148:151]
	v_mfma_f32_16x16x32_bf16 v[148:151], v[116:119], v[156:159], v[148:151]
	v_mfma_f32_16x16x32_bf16 v[172:175], v[88:91], v[152:155], v[172:175]
	v_mfma_f32_16x16x32_bf16 v[172:175], v[96:99], v[156:159], v[172:175]
	v_mfma_f32_16x16x32_bf16 v[144:147], v[128:131], v[152:155], v[144:147]
	v_mfma_f32_16x16x32_bf16 v[144:147], v[140:143], v[156:159], v[144:147]
	v_mfma_f32_16x16x32_bf16 v[136:139], v[64:67], v[160:163], v[136:139]
	v_mfma_f32_16x16x32_bf16 v[136:139], v[72:75], v[164:167], v[136:139]
	v_mfma_f32_16x16x32_bf16 v[124:127], v[108:111], v[160:163], v[124:127]
	v_mfma_f32_16x16x32_bf16 v[124:127], v[116:119], v[164:167], v[124:127]
	v_mfma_f32_16x16x32_bf16 v[132:135], v[88:91], v[160:163], v[132:135]
	v_mfma_f32_16x16x32_bf16 v[132:135], v[96:99], v[164:167], v[132:135]
	v_mfma_f32_16x16x32_bf16 v[120:123], v[128:131], v[160:163], v[120:123]
	v_mfma_f32_16x16x32_bf16 v[120:123], v[140:143], v[164:167], v[120:123]
	v_mfma_f32_16x16x32_bf16 v[112:115], v[64:67], v[168:171], v[112:115]
	v_mfma_f32_16x16x32_bf16 v[112:115], v[72:75], v[180:183], v[112:115]
	v_mfma_f32_16x16x32_bf16 v[100:103], v[108:111], v[168:171], v[100:103]
	v_mfma_f32_16x16x32_bf16 v[100:103], v[116:119], v[180:183], v[100:103]
	v_mfma_f32_16x16x32_bf16 v[104:107], v[88:91], v[168:171], v[104:107]
	v_mfma_f32_16x16x32_bf16 v[104:107], v[96:99], v[180:183], v[104:107]
	v_mfma_f32_16x16x32_bf16 v[92:95], v[128:131], v[168:171], v[92:95]
	v_mfma_f32_16x16x32_bf16 v[92:95], v[140:143], v[180:183], v[92:95]
	v_mfma_f32_16x16x32_bf16 v[84:87], v[64:67], v[184:187], v[84:87]
	v_mfma_f32_16x16x32_bf16 v[84:87], v[72:75], v[188:191], v[84:87]
	v_mfma_f32_16x16x32_bf16 v[76:79], v[108:111], v[184:187], v[76:79]
	v_mfma_f32_16x16x32_bf16 v[76:79], v[116:119], v[188:191], v[76:79]
	v_mfma_f32_16x16x32_bf16 v[80:83], v[88:91], v[184:187], v[80:83]
	v_mfma_f32_16x16x32_bf16 v[80:83], v[96:99], v[188:191], v[80:83]
	v_mfma_f32_16x16x32_bf16 v[68:71], v[128:131], v[184:187], v[68:71]
	v_mfma_f32_16x16x32_bf16 v[68:71], v[140:143], v[188:191], v[68:71]
	s_barrier
	s_add_i32 s2, s67, s28
	s_mov_b32 m0, s2
	ds_read_b128 v[152:155], v240 offset:16384
	ds_read_b128 v[156:159], v240 offset:17408
	ds_read_b128 v[160:163], v240 offset:18432
	ds_read_b128 v[164:167], v240 offset:19456
	ds_read_b128 v[168:171], v240 offset:20480
	ds_read_b128 v[180:183], v240 offset:21504
	ds_read_b128 v[184:187], v240 offset:22528
	ds_read_b128 v[188:191], v240 offset:23552
	global_load_lds_dwordx4 v216, s[92:93]
	s_add_i32 m0, s2, 0x2000
	s_add_u32 s2, s92, 0x80000
	s_addc_u32 s3, s93, 0
	s_add_i32 s67, s76, s28
	global_load_lds_dwordx4 v228, s[92:93]
	s_mov_b32 m0, s67
	s_nop 0
	global_load_lds_dwordx4 v216, s[2:3]
	s_add_i32 m0, s67, 0x2000
	s_nop 0
	global_load_lds_dwordx4 v228, s[2:3]
	s_mov_b32 m0, s39
	s_nop 0
	global_load_lds_dwordx4 v224, s[94:95]
	s_mov_b32 m0, s53
	s_nop 0
	global_load_lds_dwordx4 v226, s[94:95]
	s_waitcnt vmcnt(8)
	s_waitcnt lgkmcnt(0)
	s_barrier
	s_waitcnt lgkmcnt(0)
	v_mfma_f32_16x16x32_bf16 v[60:63], v[64:67], v[152:155], v[60:63]
	v_mfma_f32_16x16x32_bf16 v[60:63], v[72:75], v[156:159], v[60:63]
	v_mfma_f32_16x16x32_bf16 v[52:55], v[108:111], v[152:155], v[52:55]
	v_mfma_f32_16x16x32_bf16 v[52:55], v[116:119], v[156:159], v[52:55]
	v_mfma_f32_16x16x32_bf16 v[56:59], v[88:91], v[152:155], v[56:59]
	v_mfma_f32_16x16x32_bf16 v[56:59], v[96:99], v[156:159], v[56:59]
	v_mfma_f32_16x16x32_bf16 v[48:51], v[128:131], v[152:155], v[48:51]
	v_mfma_f32_16x16x32_bf16 v[48:51], v[140:143], v[156:159], v[48:51]
	v_mfma_f32_16x16x32_bf16 v[44:47], v[64:67], v[160:163], v[44:47]
	v_mfma_f32_16x16x32_bf16 v[44:47], v[72:75], v[164:167], v[44:47]
	v_mfma_f32_16x16x32_bf16 v[36:39], v[108:111], v[160:163], v[36:39]
	v_mfma_f32_16x16x32_bf16 v[36:39], v[116:119], v[164:167], v[36:39]
	v_mfma_f32_16x16x32_bf16 v[40:43], v[88:91], v[160:163], v[40:43]
	v_mfma_f32_16x16x32_bf16 v[40:43], v[96:99], v[164:167], v[40:43]
	v_mfma_f32_16x16x32_bf16 v[32:35], v[128:131], v[160:163], v[32:35]
	v_mfma_f32_16x16x32_bf16 v[32:35], v[140:143], v[164:167], v[32:35]
	v_mfma_f32_16x16x32_bf16 v[28:31], v[64:67], v[168:171], v[28:31]
	v_mfma_f32_16x16x32_bf16 v[28:31], v[72:75], v[180:183], v[28:31]
	v_mfma_f32_16x16x32_bf16 v[20:23], v[108:111], v[168:171], v[20:23]
	v_mfma_f32_16x16x32_bf16 v[20:23], v[116:119], v[180:183], v[20:23]
	v_mfma_f32_16x16x32_bf16 v[24:27], v[88:91], v[168:171], v[24:27]
	v_mfma_f32_16x16x32_bf16 v[24:27], v[96:99], v[180:183], v[24:27]
	v_mfma_f32_16x16x32_bf16 v[16:19], v[128:131], v[168:171], v[16:19]
	v_mfma_f32_16x16x32_bf16 v[16:19], v[140:143], v[180:183], v[16:19]
	v_mfma_f32_16x16x32_bf16 v[12:15], v[64:67], v[184:187], v[12:15]
	v_mfma_f32_16x16x32_bf16 v[12:15], v[72:75], v[188:191], v[12:15]
	v_mfma_f32_16x16x32_bf16 v[4:7], v[108:111], v[184:187], v[4:7]
	v_mfma_f32_16x16x32_bf16 v[4:7], v[116:119], v[188:191], v[4:7]
	v_mfma_f32_16x16x32_bf16 v[8:11], v[88:91], v[184:187], v[8:11]
	v_mfma_f32_16x16x32_bf16 v[8:11], v[96:99], v[188:191], v[8:11]
	v_mfma_f32_16x16x32_bf16 v[0:3], v[128:131], v[184:187], v[0:3]
	v_mfma_f32_16x16x32_bf16 v[0:3], v[140:143], v[188:191], v[0:3]
	s_barrier
	s_add_i32 s67, 0, 0x18000
	s_add_i32 s76, 0, 0x1c000
	ds_read_b128 v[64:67], v192 offset:32768
	ds_read_b128 v[72:75], v192 offset:33792
	ds_read_b128 v[88:91], v192 offset:34816
	ds_read_b128 v[96:99], v192 offset:35840
	ds_read_b128 v[108:111], v192 offset:49152
	ds_read_b128 v[116:119], v192 offset:50176
	ds_read_b128 v[128:131], v192 offset:51200
	ds_read_b128 v[140:143], v192 offset:52224
	s_add_u32 s2, s94, 0x80000
	s_addc_u32 s3, s95, 0
	s_mov_b32 m0, s55
	ds_read_b128 v[152:155], v240 offset:32768
	ds_read_b128 v[156:159], v240 offset:33792
	ds_read_b128 v[160:163], v240 offset:34816
	ds_read_b128 v[164:167], v240 offset:35840
	ds_read_b128 v[168:171], v240 offset:36864
	ds_read_b128 v[180:183], v240 offset:37888
	ds_read_b128 v[184:187], v240 offset:38912
	ds_read_b128 v[188:191], v240 offset:39936
	global_load_lds_dwordx4 v224, s[2:3]
	s_mov_b32 m0, s56
	s_nop 0
	global_load_lds_dwordx4 v226, s[2:3]
	s_waitcnt vmcnt(8)
	s_waitcnt lgkmcnt(0)
	s_barrier
	s_waitcnt lgkmcnt(0)
	v_mfma_f32_16x16x32_bf16 v[176:179], v[64:67], v[152:155], v[176:179]
	v_mfma_f32_16x16x32_bf16 v[176:179], v[72:75], v[156:159], v[176:179]
	v_mfma_f32_16x16x32_bf16 v[148:151], v[108:111], v[152:155], v[148:151]
	v_mfma_f32_16x16x32_bf16 v[148:151], v[116:119], v[156:159], v[148:151]
	v_mfma_f32_16x16x32_bf16 v[172:175], v[88:91], v[152:155], v[172:175]
	v_mfma_f32_16x16x32_bf16 v[172:175], v[96:99], v[156:159], v[172:175]
	v_mfma_f32_16x16x32_bf16 v[144:147], v[128:131], v[152:155], v[144:147]
	v_mfma_f32_16x16x32_bf16 v[144:147], v[140:143], v[156:159], v[144:147]
	v_mfma_f32_16x16x32_bf16 v[136:139], v[64:67], v[160:163], v[136:139]
	v_mfma_f32_16x16x32_bf16 v[136:139], v[72:75], v[164:167], v[136:139]
	v_mfma_f32_16x16x32_bf16 v[124:127], v[108:111], v[160:163], v[124:127]
	v_mfma_f32_16x16x32_bf16 v[124:127], v[116:119], v[164:167], v[124:127]
	v_mfma_f32_16x16x32_bf16 v[132:135], v[88:91], v[160:163], v[132:135]
	v_mfma_f32_16x16x32_bf16 v[132:135], v[96:99], v[164:167], v[132:135]
	v_mfma_f32_16x16x32_bf16 v[120:123], v[128:131], v[160:163], v[120:123]
	v_mfma_f32_16x16x32_bf16 v[120:123], v[140:143], v[164:167], v[120:123]
	v_mfma_f32_16x16x32_bf16 v[112:115], v[64:67], v[168:171], v[112:115]
	v_mfma_f32_16x16x32_bf16 v[112:115], v[72:75], v[180:183], v[112:115]
	v_mfma_f32_16x16x32_bf16 v[100:103], v[108:111], v[168:171], v[100:103]
	v_mfma_f32_16x16x32_bf16 v[100:103], v[116:119], v[180:183], v[100:103]
	v_mfma_f32_16x16x32_bf16 v[104:107], v[88:91], v[168:171], v[104:107]
	v_mfma_f32_16x16x32_bf16 v[104:107], v[96:99], v[180:183], v[104:107]
	v_mfma_f32_16x16x32_bf16 v[92:95], v[128:131], v[168:171], v[92:95]
	v_mfma_f32_16x16x32_bf16 v[92:95], v[140:143], v[180:183], v[92:95]
	v_mfma_f32_16x16x32_bf16 v[84:87], v[64:67], v[184:187], v[84:87]
	v_mfma_f32_16x16x32_bf16 v[84:87], v[72:75], v[188:191], v[84:87]
	v_mfma_f32_16x16x32_bf16 v[76:79], v[108:111], v[184:187], v[76:79]
	v_mfma_f32_16x16x32_bf16 v[76:79], v[116:119], v[188:191], v[76:79]
	v_mfma_f32_16x16x32_bf16 v[80:83], v[88:91], v[184:187], v[80:83]
	v_mfma_f32_16x16x32_bf16 v[80:83], v[96:99], v[188:191], v[80:83]
	v_mfma_f32_16x16x32_bf16 v[68:71], v[128:131], v[184:187], v[68:71]
	v_mfma_f32_16x16x32_bf16 v[68:71], v[140:143], v[188:191], v[68:71]
	s_barrier
	s_add_i32 s2, s67, s28
	s_add_u32 s98, s92, 0x80
	s_addc_u32 s99, s93, 0
	s_mov_b32 m0, s2
	ds_read_b128 v[152:155], v240 offset:49152
	ds_read_b128 v[156:159], v240 offset:50176
	ds_read_b128 v[160:163], v240 offset:51200
	ds_read_b128 v[164:167], v240 offset:52224
	ds_read_b128 v[168:171], v240 offset:53248
	ds_read_b128 v[180:183], v240 offset:54272
	ds_read_b128 v[184:187], v240 offset:55296
	ds_read_b128 v[188:191], v240 offset:56320
	global_load_lds_dwordx4 v216, s[98:99]
	s_add_i32 m0, s2, 0x2000
	s_add_u32 s2, s92, 0x80080
	s_addc_u32 s3, s93, 0
	s_add_i32 s67, s76, s28
	global_load_lds_dwordx4 v228, s[98:99]
	s_mov_b32 m0, s67
	s_nop 0
	global_load_lds_dwordx4 v216, s[2:3]
	s_add_i32 m0, s67, 0x2000
	s_nop 0
	global_load_lds_dwordx4 v228, s[2:3]
	s_add_u32 s98, s94, 0x80
	s_addc_u32 s99, s95, 0
	s_mov_b32 m0, s70
	s_nop 0
	global_load_lds_dwordx4 v224, s[98:99]
	s_mov_b32 m0, s71
	s_nop 0
	global_load_lds_dwordx4 v226, s[98:99]
	s_waitcnt vmcnt(8)
	s_waitcnt lgkmcnt(0)
	s_barrier
	s_waitcnt lgkmcnt(0)
	v_mfma_f32_16x16x32_bf16 v[60:63], v[64:67], v[152:155], v[60:63]
	v_mfma_f32_16x16x32_bf16 v[60:63], v[72:75], v[156:159], v[60:63]
	v_mfma_f32_16x16x32_bf16 v[52:55], v[108:111], v[152:155], v[52:55]
	v_mfma_f32_16x16x32_bf16 v[52:55], v[116:119], v[156:159], v[52:55]
	v_mfma_f32_16x16x32_bf16 v[56:59], v[88:91], v[152:155], v[56:59]
	v_mfma_f32_16x16x32_bf16 v[56:59], v[96:99], v[156:159], v[56:59]
	v_mfma_f32_16x16x32_bf16 v[48:51], v[128:131], v[152:155], v[48:51]
	v_mfma_f32_16x16x32_bf16 v[48:51], v[140:143], v[156:159], v[48:51]
	v_mfma_f32_16x16x32_bf16 v[44:47], v[64:67], v[160:163], v[44:47]
	v_mfma_f32_16x16x32_bf16 v[44:47], v[72:75], v[164:167], v[44:47]
	v_mfma_f32_16x16x32_bf16 v[36:39], v[108:111], v[160:163], v[36:39]
	v_mfma_f32_16x16x32_bf16 v[36:39], v[116:119], v[164:167], v[36:39]
	v_mfma_f32_16x16x32_bf16 v[40:43], v[88:91], v[160:163], v[40:43]
	v_mfma_f32_16x16x32_bf16 v[40:43], v[96:99], v[164:167], v[40:43]
	v_mfma_f32_16x16x32_bf16 v[32:35], v[128:131], v[160:163], v[32:35]
	v_mfma_f32_16x16x32_bf16 v[32:35], v[140:143], v[164:167], v[32:35]
	v_mfma_f32_16x16x32_bf16 v[28:31], v[64:67], v[168:171], v[28:31]
	v_mfma_f32_16x16x32_bf16 v[28:31], v[72:75], v[180:183], v[28:31]
	v_mfma_f32_16x16x32_bf16 v[20:23], v[108:111], v[168:171], v[20:23]
	v_mfma_f32_16x16x32_bf16 v[20:23], v[116:119], v[180:183], v[20:23]
	v_mfma_f32_16x16x32_bf16 v[24:27], v[88:91], v[168:171], v[24:27]
	v_mfma_f32_16x16x32_bf16 v[24:27], v[96:99], v[180:183], v[24:27]
	v_mfma_f32_16x16x32_bf16 v[16:19], v[128:131], v[168:171], v[16:19]
	v_mfma_f32_16x16x32_bf16 v[16:19], v[140:143], v[180:183], v[16:19]
	v_mfma_f32_16x16x32_bf16 v[12:15], v[64:67], v[184:187], v[12:15]
	v_mfma_f32_16x16x32_bf16 v[12:15], v[72:75], v[188:191], v[12:15]
	v_mfma_f32_16x16x32_bf16 v[4:7], v[108:111], v[184:187], v[4:7]
	v_mfma_f32_16x16x32_bf16 v[4:7], v[116:119], v[188:191], v[4:7]
	v_mfma_f32_16x16x32_bf16 v[8:11], v[88:91], v[184:187], v[8:11]
	v_mfma_f32_16x16x32_bf16 v[8:11], v[96:99], v[188:191], v[8:11]
	v_mfma_f32_16x16x32_bf16 v[0:3], v[128:131], v[184:187], v[0:3]
	v_mfma_f32_16x16x32_bf16 v[0:3], v[140:143], v[188:191], v[0:3]
	s_barrier
	s_add_i32 s20, s20, 2
	s_add_u32 s90, s90, 0x100
	s_addc_u32 s91, s91, 0
	s_add_u32 s89, s89, 0x100
	s_addc_u32 s14, s14, 0
	s_cmp_gt_u32 s20, 29
	s_cbranch_scc0 .LBB0_595
	s_and_b64 vcc, exec, s[74:75]
	s_cbranch_vccz .LBB0_598
	s_barrier

.LBB0_638:
	s_ashr_i32 s87, s86, 31
	s_lshl_b64 s[40:41], s[86:87], 20
	s_add_u32 s88, s14, s40
	s_addc_u32 s89, s15, s41
	s_and_b64 s[40:41], s[4:5], exec
	s_cselect_b32 s7, s89, s11
	s_cselect_b32 s9, s88, s10
	s_ashr_i32 s85, s84, 31
	s_lshl_b64 s[40:41], s[84:85], 20
	s_add_u32 s90, s24, s40
	s_addc_u32 s91, s26, s41
	s_and_b64 s[40:41], s[4:5], exec
	s_cselect_b32 s40, s91, s93
	s_cselect_b32 s41, s90, s92
	s_add_u32 s10, s10, 0x80080
	s_addc_u32 s11, s11, 0
	s_add_u32 s54, s92, 0x100
	s_addc_u32 s55, s93, 0
	s_mov_b32 s85, -2
	v_add_u32_e32 v177, 0x10000, v194
	s_add_u32 s67, s10, 0xfff80080
	s_addc_u32 s87, s11, -1
	s_add_i32 s96, 0, 0x10000
	s_cmp_eq_u32 s85, 28
	s_cselect_b32 s95, s7, s87
	s_cselect_b32 s94, s9, s67
	s_cselect_b32 s93, s40, s55
	s_cselect_b32 s92, s41, s54
	s_add_i32 s67, 0, 0x14000
	ds_read_b128 v[40:43], v177
	ds_read_b128 v[44:47], v177 offset:1024
	ds_read_b128 v[48:51], v177 offset:2048
	ds_read_b128 v[52:55], v177 offset:3072
	ds_read_b128 v[64:67], v177 offset:16384
	ds_read_b128 v[100:103], v177 offset:17408
	ds_read_b128 v[120:123], v177 offset:18432
	ds_read_b128 v[124:127], v177 offset:19456
	s_add_i32 m0, s57, 0xc000
	ds_read_b128 v[136:139], v195
	ds_read_b128 v[140:143], v195 offset:1024
	ds_read_b128 v[144:147], v195 offset:2048
	ds_read_b128 v[172:175], v195 offset:3072
	ds_read_b128 v[190:193], v195 offset:4096
	ds_read_b128 v[196:199], v195 offset:5120
	ds_read_b128 v[200:203], v195 offset:6144
	ds_read_b128 v[204:207], v195 offset:7168
	global_load_lds_dwordx4 v186, s[10:11]
	s_add_i32 m0, s57, 0xe000
	s_nop 0
	global_load_lds_dwordx4 v188, s[10:11]
	s_waitcnt vmcnt(8)
	s_waitcnt lgkmcnt(0)
	s_barrier
	s_waitcnt lgkmcnt(0)
	v_mfma_f32_16x16x32_bf16 v[168:171], v[40:43], v[136:139], 0
	v_mfma_f32_16x16x32_bf16 v[168:171], v[44:47], v[140:143], v[168:171]
	v_mfma_f32_16x16x32_bf16 v[160:163], v[64:67], v[136:139], 0
	v_mfma_f32_16x16x32_bf16 v[160:163], v[100:103], v[140:143], v[160:163]
	v_mfma_f32_16x16x32_bf16 v[164:167], v[48:51], v[136:139], 0
	v_mfma_f32_16x16x32_bf16 v[164:167], v[52:55], v[140:143], v[164:167]
	v_mfma_f32_16x16x32_bf16 v[132:135], v[64:67], v[144:147], 0
	v_mfma_f32_16x16x32_bf16 v[132:135], v[100:103], v[172:175], v[132:135]
	v_mfma_f32_16x16x32_bf16 v[152:155], v[40:43], v[144:147], 0
	v_mfma_f32_16x16x32_bf16 v[152:155], v[44:47], v[172:175], v[152:155]
	v_mfma_f32_16x16x32_bf16 v[128:131], v[120:123], v[144:147], 0
	v_mfma_f32_16x16x32_bf16 v[128:131], v[124:127], v[172:175], v[128:131]
	v_mfma_f32_16x16x32_bf16 v[148:151], v[48:51], v[144:147], 0
	v_mfma_f32_16x16x32_bf16 v[148:151], v[52:55], v[172:175], v[148:151]
	v_mfma_f32_16x16x32_bf16 v[108:111], v[64:67], v[190:193], 0
	v_mfma_f32_16x16x32_bf16 v[108:111], v[100:103], v[196:199], v[108:111]
	v_mfma_f32_16x16x32_bf16 v[116:119], v[40:43], v[190:193], 0
	v_mfma_f32_16x16x32_bf16 v[116:119], v[44:47], v[196:199], v[116:119]
	v_mfma_f32_16x16x32_bf16 v[104:107], v[120:123], v[190:193], 0
	v_mfma_f32_16x16x32_bf16 v[104:107], v[124:127], v[196:199], v[104:107]
	v_mfma_f32_16x16x32_bf16 v[112:115], v[48:51], v[190:193], 0
	v_mfma_f32_16x16x32_bf16 v[112:115], v[52:55], v[196:199], v[112:115]
	v_mfma_f32_16x16x32_bf16 v[88:91], v[64:67], v[200:203], 0
	v_mfma_f32_16x16x32_bf16 v[88:91], v[100:103], v[204:207], v[88:91]
	v_mfma_f32_16x16x32_bf16 v[96:99], v[40:43], v[200:203], 0
	v_mfma_f32_16x16x32_bf16 v[96:99], v[44:47], v[204:207], v[96:99]
	v_mfma_f32_16x16x32_bf16 v[84:87], v[120:123], v[200:203], 0
	v_mfma_f32_16x16x32_bf16 v[84:87], v[124:127], v[204:207], v[84:87]
	v_mfma_f32_16x16x32_bf16 v[92:95], v[48:51], v[200:203], 0
	v_mfma_f32_16x16x32_bf16 v[92:95], v[52:55], v[204:207], v[92:95]
	v_mfma_f32_16x16x32_bf16 v[136:139], v[120:123], v[136:139], 0
	v_mfma_f32_16x16x32_bf16 v[136:139], v[124:127], v[140:143], v[136:139]
	s_barrier
	s_add_i32 s87, s96, s56
	s_mov_b32 m0, s87
	ds_read_b128 v[140:143], v195 offset:16384
	ds_read_b128 v[144:147], v195 offset:17408
	ds_read_b128 v[156:159], v195 offset:18432
	ds_read_b128 v[172:175], v195 offset:19456
	ds_read_b128 v[190:193], v195 offset:20480
	ds_read_b128 v[196:199], v195 offset:21504
	ds_read_b128 v[200:203], v195 offset:22528
	ds_read_b128 v[204:207], v195 offset:23552
	global_load_lds_dwordx4 v178, s[92:93]
	s_add_i32 m0, s87, 0x2000
	s_add_u32 vcc_lo, s92, 0x80000
	s_addc_u32 vcc_hi, s93, 0
	s_add_i32 s67, s67, s56
	global_load_lds_dwordx4 v182, s[92:93]
	v_lshl_add_u64 v[208:209], vcc, 0, v[178:179]
	s_mov_b32 m0, s67
	s_nop 0
	global_load_lds_dwordx4 v[208:209], off
	v_lshl_add_u64 v[208:209], vcc, 0, v[182:183]
	s_add_i32 m0, s67, 0x2000
	s_nop 0
	global_load_lds_dwordx4 v[208:209], off
	s_mov_b32 m0, s57
	s_nop 0
	global_load_lds_dwordx4 v176, s[94:95]
	s_mov_b32 m0, s61
	s_nop 0
	global_load_lds_dwordx4 v180, s[94:95]
	s_waitcnt vmcnt(8)
	s_waitcnt lgkmcnt(0)
	s_barrier
	s_waitcnt lgkmcnt(0)
	v_mfma_f32_16x16x32_bf16 v[80:83], v[40:43], v[140:143], 0
	v_mfma_f32_16x16x32_bf16 v[80:83], v[44:47], v[144:147], v[80:83]
	v_mfma_f32_16x16x32_bf16 v[36:39], v[64:67], v[156:159], 0
	v_mfma_f32_16x16x32_bf16 v[36:39], v[100:103], v[172:175], v[36:39]
	v_mfma_f32_16x16x32_bf16 v[76:79], v[48:51], v[140:143], 0
	v_mfma_f32_16x16x32_bf16 v[76:79], v[52:55], v[144:147], v[76:79]
	v_mfma_f32_16x16x32_bf16 v[32:35], v[120:123], v[156:159], 0
	v_mfma_f32_16x16x32_bf16 v[32:35], v[124:127], v[172:175], v[32:35]
	v_mfma_f32_16x16x32_bf16 v[60:63], v[40:43], v[156:159], 0
	v_mfma_f32_16x16x32_bf16 v[60:63], v[44:47], v[172:175], v[60:63]
	v_mfma_f32_16x16x32_bf16 v[20:23], v[64:67], v[190:193], 0
	v_mfma_f32_16x16x32_bf16 v[20:23], v[100:103], v[196:199], v[20:23]
	v_mfma_f32_16x16x32_bf16 v[56:59], v[48:51], v[156:159], 0
	v_mfma_f32_16x16x32_bf16 v[56:59], v[52:55], v[172:175], v[56:59]
	v_mfma_f32_16x16x32_bf16 v[16:19], v[120:123], v[190:193], 0
	v_mfma_f32_16x16x32_bf16 v[16:19], v[124:127], v[196:199], v[16:19]
	v_mfma_f32_16x16x32_bf16 v[28:31], v[40:43], v[190:193], 0
	v_mfma_f32_16x16x32_bf16 v[28:31], v[44:47], v[196:199], v[28:31]
	v_mfma_f32_16x16x32_bf16 v[4:7], v[64:67], v[200:203], 0
	v_mfma_f32_16x16x32_bf16 v[4:7], v[100:103], v[204:207], v[4:7]
	v_mfma_f32_16x16x32_bf16 v[24:27], v[48:51], v[190:193], 0
	v_mfma_f32_16x16x32_bf16 v[24:27], v[52:55], v[196:199], v[24:27]
	v_mfma_f32_16x16x32_bf16 v[0:3], v[120:123], v[200:203], 0
	v_mfma_f32_16x16x32_bf16 v[0:3], v[124:127], v[204:207], v[0:3]
	v_mfma_f32_16x16x32_bf16 v[12:15], v[40:43], v[200:203], 0
	v_mfma_f32_16x16x32_bf16 v[12:15], v[44:47], v[204:207], v[12:15]
	v_mfma_f32_16x16x32_bf16 v[40:43], v[64:67], v[140:143], 0
	v_mfma_f32_16x16x32_bf16 v[40:43], v[100:103], v[144:147], v[40:43]
	v_mfma_f32_16x16x32_bf16 v[8:11], v[48:51], v[200:203], 0
	v_mfma_f32_16x16x32_bf16 v[8:11], v[52:55], v[204:207], v[8:11]
	v_mfma_f32_16x16x32_bf16 v[44:47], v[120:123], v[140:143], 0
	v_mfma_f32_16x16x32_bf16 v[44:47], v[124:127], v[144:147], v[44:47]
	s_barrier
	s_add_i32 s67, 0, 0x18000
	s_add_i32 s87, 0, 0x1c000
	ds_read_b128 v[48:51], v177 offset:32768
	ds_read_b128 v[52:55], v177 offset:33792
	ds_read_b128 v[64:67], v177 offset:34816
	ds_read_b128 v[68:71], v177 offset:35840
	ds_read_b128 v[100:103], v177 offset:49152
	ds_read_b128 v[120:123], v177 offset:50176
	ds_read_b128 v[124:127], v177 offset:51200
	ds_read_b128 v[140:143], v177 offset:52224
	s_add_u32 s94, s94, 0x80000
	s_addc_u32 s95, s95, 0
	s_mov_b32 m0, s68
	ds_read_b128 v[72:75], v195 offset:32768
	ds_read_b128 v[144:147], v195 offset:33792
	ds_read_b128 v[172:175], v195 offset:34816
	ds_read_b128 v[190:193], v195 offset:35840
	ds_read_b128 v[196:199], v195 offset:36864
	ds_read_b128 v[200:203], v195 offset:37888
	ds_read_b128 v[204:207], v195 offset:38912
	ds_read_b128 v[208:211], v195 offset:39936
	global_load_lds_dwordx4 v176, s[94:95]
	s_mov_b32 m0, s69
	s_nop 0
	global_load_lds_dwordx4 v180, s[94:95]
	s_waitcnt vmcnt(8)
	s_waitcnt lgkmcnt(0)
	s_barrier
	s_waitcnt lgkmcnt(0)
	v_mfma_f32_16x16x32_bf16 v[156:159], v[48:51], v[72:75], v[168:171]
	v_mfma_f32_16x16x32_bf16 v[168:171], v[52:55], v[144:147], v[156:159]
	v_mfma_f32_16x16x32_bf16 v[156:159], v[64:67], v[72:75], v[164:167]
	v_mfma_f32_16x16x32_bf16 v[164:167], v[68:71], v[144:147], v[156:159]
	v_mfma_f32_16x16x32_bf16 v[152:155], v[48:51], v[172:175], v[152:155]
	v_mfma_f32_16x16x32_bf16 v[152:155], v[52:55], v[190:193], v[152:155]
	v_mfma_f32_16x16x32_bf16 v[148:151], v[64:67], v[172:175], v[148:151]
	v_mfma_f32_16x16x32_bf16 v[148:151], v[68:71], v[190:193], v[148:151]
	v_mfma_f32_16x16x32_bf16 v[116:119], v[48:51], v[196:199], v[116:119]
	v_mfma_f32_16x16x32_bf16 v[116:119], v[52:55], v[200:203], v[116:119]
	v_mfma_f32_16x16x32_bf16 v[112:115], v[64:67], v[196:199], v[112:115]
	v_mfma_f32_16x16x32_bf16 v[112:115], v[68:71], v[200:203], v[112:115]
	v_mfma_f32_16x16x32_bf16 v[96:99], v[48:51], v[204:207], v[96:99]
	v_mfma_f32_16x16x32_bf16 v[96:99], v[52:55], v[208:211], v[96:99]
	v_mfma_f32_16x16x32_bf16 v[92:95], v[64:67], v[204:207], v[92:95]
	v_mfma_f32_16x16x32_bf16 v[92:95], v[68:71], v[208:211], v[92:95]
	v_mfma_f32_16x16x32_bf16 v[156:159], v[100:103], v[72:75], v[160:163]
	v_mfma_f32_16x16x32_bf16 v[160:163], v[120:123], v[144:147], v[156:159]
	v_mfma_f32_16x16x32_bf16 v[72:75], v[124:127], v[72:75], v[136:139]
	v_mfma_f32_16x16x32_bf16 v[156:159], v[140:143], v[144:147], v[72:75]
	v_mfma_f32_16x16x32_bf16 v[72:75], v[100:103], v[172:175], v[132:135]
	v_mfma_f32_16x16x32_bf16 v[132:135], v[120:123], v[190:193], v[72:75]
	v_mfma_f32_16x16x32_bf16 v[72:75], v[124:127], v[172:175], v[128:131]
	v_mfma_f32_16x16x32_bf16 v[128:131], v[140:143], v[190:193], v[72:75]
	v_mfma_f32_16x16x32_bf16 v[72:75], v[100:103], v[196:199], v[108:111]
	v_mfma_f32_16x16x32_bf16 v[108:111], v[120:123], v[200:203], v[72:75]
	v_mfma_f32_16x16x32_bf16 v[72:75], v[124:127], v[196:199], v[104:107]
	v_mfma_f32_16x16x32_bf16 v[104:107], v[140:143], v[200:203], v[72:75]
	v_mfma_f32_16x16x32_bf16 v[72:75], v[100:103], v[204:207], v[88:91]
	v_mfma_f32_16x16x32_bf16 v[88:91], v[120:123], v[208:211], v[72:75]
	v_mfma_f32_16x16x32_bf16 v[72:75], v[124:127], v[204:207], v[84:87]
	v_mfma_f32_16x16x32_bf16 v[84:87], v[140:143], v[208:211], v[72:75]
	s_barrier
	s_add_i32 s67, s67, s56
	s_nop 3
	s_add_u32 s98, s92, 0x80
	s_addc_u32 s99, s93, 0
	s_mov_b32 m0, s67
	ds_read_b128 v[136:139], v195 offset:49152
	ds_read_b128 v[144:147], v195 offset:50176
	ds_read_b128 v[172:175], v195 offset:51200
	ds_read_b128 v[190:193], v195 offset:52224
	ds_read_b128 v[196:199], v195 offset:53248
	ds_read_b128 v[200:203], v195 offset:54272
	ds_read_b128 v[204:207], v195 offset:55296
	ds_read_b128 v[208:211], v195 offset:56320
	global_load_lds_dwordx4 v178, s[98:99]
	s_add_i32 m0, s67, 0x2000
	s_add_u32 s92, s92, 0x80080
	s_addc_u32 s93, s93, 0
	s_add_i32 s67, s87, s56
	global_load_lds_dwordx4 v182, s[98:99]
	s_mov_b32 m0, s67
	s_nop 0
	global_load_lds_dwordx4 v178, s[92:93]
	s_add_i32 m0, s67, 0x2000
	s_nop 0
	global_load_lds_dwordx4 v182, s[92:93]
	s_add_u32 s98, s94, 0xfff80080
	s_addc_u32 s99, s95, -1
	s_mov_b32 m0, s2
	s_nop 0
	global_load_lds_dwordx4 v176, s[98:99]
	s_mov_b32 m0, s28
	s_nop 0
	global_load_lds_dwordx4 v180, s[98:99]
	s_waitcnt vmcnt(8)
	s_waitcnt lgkmcnt(0)
	s_barrier
	s_waitcnt lgkmcnt(0)
	v_mfma_f32_16x16x32_bf16 v[72:75], v[48:51], v[136:139], v[80:83]
	v_mfma_f32_16x16x32_bf16 v[80:83], v[52:55], v[144:147], v[72:75]
	v_mfma_f32_16x16x32_bf16 v[72:75], v[64:67], v[136:139], v[76:79]
	v_mfma_f32_16x16x32_bf16 v[76:79], v[68:71], v[144:147], v[72:75]
	v_mfma_f32_16x16x32_bf16 v[60:63], v[48:51], v[172:175], v[60:63]
	v_mfma_f32_16x16x32_bf16 v[60:63], v[52:55], v[190:193], v[60:63]
	v_mfma_f32_16x16x32_bf16 v[56:59], v[64:67], v[172:175], v[56:59]
	v_mfma_f32_16x16x32_bf16 v[56:59], v[68:71], v[190:193], v[56:59]
	v_mfma_f32_16x16x32_bf16 v[28:31], v[48:51], v[196:199], v[28:31]
	v_mfma_f32_16x16x32_bf16 v[28:31], v[52:55], v[200:203], v[28:31]
	v_mfma_f32_16x16x32_bf16 v[24:27], v[64:67], v[196:199], v[24:27]
	v_mfma_f32_16x16x32_bf16 v[24:27], v[68:71], v[200:203], v[24:27]
	v_mfma_f32_16x16x32_bf16 v[12:15], v[48:51], v[204:207], v[12:15]
	v_mfma_f32_16x16x32_bf16 v[12:15], v[52:55], v[208:211], v[12:15]
	v_mfma_f32_16x16x32_bf16 v[8:11], v[64:67], v[204:207], v[8:11]
	v_mfma_f32_16x16x32_bf16 v[8:11], v[68:71], v[208:211], v[8:11]
	v_mfma_f32_16x16x32_bf16 v[40:43], v[100:103], v[136:139], v[40:43]
	v_mfma_f32_16x16x32_bf16 v[72:75], v[120:123], v[144:147], v[40:43]
	v_mfma_f32_16x16x32_bf16 v[40:43], v[124:127], v[136:139], v[44:47]
	v_mfma_f32_16x16x32_bf16 v[68:71], v[140:143], v[144:147], v[40:43]
	v_mfma_f32_16x16x32_bf16 v[36:39], v[100:103], v[172:175], v[36:39]
	v_mfma_f32_16x16x32_bf16 v[36:39], v[120:123], v[190:193], v[36:39]
	v_mfma_f32_16x16x32_bf16 v[32:35], v[124:127], v[172:175], v[32:35]
	v_mfma_f32_16x16x32_bf16 v[32:35], v[140:143], v[190:193], v[32:35]
	v_mfma_f32_16x16x32_bf16 v[20:23], v[100:103], v[196:199], v[20:23]
	v_mfma_f32_16x16x32_bf16 v[20:23], v[120:123], v[200:203], v[20:23]
	v_mfma_f32_16x16x32_bf16 v[16:19], v[124:127], v[196:199], v[16:19]
	v_mfma_f32_16x16x32_bf16 v[16:19], v[140:143], v[200:203], v[16:19]
	v_mfma_f32_16x16x32_bf16 v[4:7], v[100:103], v[204:207], v[4:7]
	v_mfma_f32_16x16x32_bf16 v[4:7], v[120:123], v[208:211], v[4:7]
	v_mfma_f32_16x16x32_bf16 v[0:3], v[124:127], v[204:207], v[0:3]
	v_mfma_f32_16x16x32_bf16 v[0:3], v[140:143], v[208:211], v[0:3]
	s_barrier
	s_add_i32 s85, s85, 2
	s_add_u32 s10, s10, 0x100
	s_addc_u32 s11, s11, 0
	s_add_u32 s54, s54, 0x100
	s_addc_u32 s55, s55, 0
.LBB0_639:
	s_add_u32 s67, s10, 0xfff80080
	s_addc_u32 s87, s11, -1
	s_add_i32 s96, 0, 0x10000
	s_cmp_eq_u32 s85, 28
	s_cselect_b32 s95, s7, s87
	s_cselect_b32 s94, s9, s67
	s_cselect_b32 s93, s40, s55
	s_cselect_b32 s92, s41, s54
	s_add_i32 s67, 0, 0x14000
	ds_read_b128 v[40:43], v177
	ds_read_b128 v[44:47], v177 offset:1024
	ds_read_b128 v[48:51], v177 offset:2048
	ds_read_b128 v[52:55], v177 offset:3072
	ds_read_b128 v[64:67], v177 offset:16384
	ds_read_b128 v[100:103], v177 offset:17408
	ds_read_b128 v[120:123], v177 offset:18432
	ds_read_b128 v[124:127], v177 offset:19456
	s_add_i32 m0, s57, 0xc000
	ds_read_b128 v[136:139], v195
	ds_read_b128 v[140:143], v195 offset:1024
	ds_read_b128 v[144:147], v195 offset:2048
	ds_read_b128 v[172:175], v195 offset:3072
	ds_read_b128 v[190:193], v195 offset:4096
	ds_read_b128 v[196:199], v195 offset:5120
	ds_read_b128 v[200:203], v195 offset:6144
	ds_read_b128 v[204:207], v195 offset:7168
	global_load_lds_dwordx4 v186, s[10:11]
	s_add_i32 m0, s57, 0xe000
	s_nop 0
	global_load_lds_dwordx4 v188, s[10:11]
	s_waitcnt vmcnt(8)
	s_waitcnt lgkmcnt(0)
	s_barrier
	s_waitcnt lgkmcnt(0)
	v_mfma_f32_16x16x32_bf16 v[168:171], v[40:43], v[136:139], v[168:171]
	v_mfma_f32_16x16x32_bf16 v[168:171], v[44:47], v[140:143], v[168:171]
	v_mfma_f32_16x16x32_bf16 v[160:163], v[64:67], v[136:139], v[160:163]
	v_mfma_f32_16x16x32_bf16 v[160:163], v[100:103], v[140:143], v[160:163]
	v_mfma_f32_16x16x32_bf16 v[164:167], v[48:51], v[136:139], v[164:167]
	v_mfma_f32_16x16x32_bf16 v[164:167], v[52:55], v[140:143], v[164:167]
	v_mfma_f32_16x16x32_bf16 v[132:135], v[64:67], v[144:147], v[132:135]
	v_mfma_f32_16x16x32_bf16 v[132:135], v[100:103], v[172:175], v[132:135]
	v_mfma_f32_16x16x32_bf16 v[152:155], v[40:43], v[144:147], v[152:155]
	v_mfma_f32_16x16x32_bf16 v[152:155], v[44:47], v[172:175], v[152:155]
	v_mfma_f32_16x16x32_bf16 v[128:131], v[120:123], v[144:147], v[128:131]
	v_mfma_f32_16x16x32_bf16 v[128:131], v[124:127], v[172:175], v[128:131]
	v_mfma_f32_16x16x32_bf16 v[148:151], v[48:51], v[144:147], v[148:151]
	v_mfma_f32_16x16x32_bf16 v[148:151], v[52:55], v[172:175], v[148:151]
	v_mfma_f32_16x16x32_bf16 v[108:111], v[64:67], v[190:193], v[108:111]
	v_mfma_f32_16x16x32_bf16 v[108:111], v[100:103], v[196:199], v[108:111]
	v_mfma_f32_16x16x32_bf16 v[116:119], v[40:43], v[190:193], v[116:119]
	v_mfma_f32_16x16x32_bf16 v[116:119], v[44:47], v[196:199], v[116:119]
	v_mfma_f32_16x16x32_bf16 v[104:107], v[120:123], v[190:193], v[104:107]
	v_mfma_f32_16x16x32_bf16 v[104:107], v[124:127], v[196:199], v[104:107]
	v_mfma_f32_16x16x32_bf16 v[112:115], v[48:51], v[190:193], v[112:115]
	v_mfma_f32_16x16x32_bf16 v[112:115], v[52:55], v[196:199], v[112:115]
	v_mfma_f32_16x16x32_bf16 v[88:91], v[64:67], v[200:203], v[88:91]
	v_mfma_f32_16x16x32_bf16 v[88:91], v[100:103], v[204:207], v[88:91]
	v_mfma_f32_16x16x32_bf16 v[96:99], v[40:43], v[200:203], v[96:99]
	v_mfma_f32_16x16x32_bf16 v[96:99], v[44:47], v[204:207], v[96:99]
	v_mfma_f32_16x16x32_bf16 v[84:87], v[120:123], v[200:203], v[84:87]
	v_mfma_f32_16x16x32_bf16 v[84:87], v[124:127], v[204:207], v[84:87]
	v_mfma_f32_16x16x32_bf16 v[92:95], v[48:51], v[200:203], v[92:95]
	v_mfma_f32_16x16x32_bf16 v[92:95], v[52:55], v[204:207], v[92:95]
	v_mfma_f32_16x16x32_bf16 v[136:139], v[120:123], v[136:139], v[156:159]
	v_mfma_f32_16x16x32_bf16 v[136:139], v[124:127], v[140:143], v[136:139]
	s_barrier
	s_add_i32 s87, s96, s56
	s_mov_b32 m0, s87
	ds_read_b128 v[140:143], v195 offset:16384
	ds_read_b128 v[144:147], v195 offset:17408
	ds_read_b128 v[156:159], v195 offset:18432
	ds_read_b128 v[172:175], v195 offset:19456
	ds_read_b128 v[190:193], v195 offset:20480
	ds_read_b128 v[196:199], v195 offset:21504
	ds_read_b128 v[200:203], v195 offset:22528
	ds_read_b128 v[204:207], v195 offset:23552
	global_load_lds_dwordx4 v178, s[92:93]
	s_add_i32 m0, s87, 0x2000
	s_add_u32 vcc_lo, s92, 0x80000
	s_addc_u32 vcc_hi, s93, 0
	s_add_i32 s67, s67, s56
	global_load_lds_dwordx4 v182, s[92:93]
	v_lshl_add_u64 v[208:209], vcc, 0, v[178:179]
	s_mov_b32 m0, s67
	s_nop 0
	global_load_lds_dwordx4 v[208:209], off
	v_lshl_add_u64 v[208:209], vcc, 0, v[182:183]
	s_add_i32 m0, s67, 0x2000
	s_nop 0
	global_load_lds_dwordx4 v[208:209], off
	s_mov_b32 m0, s57
	s_nop 0
	global_load_lds_dwordx4 v176, s[94:95]
	s_mov_b32 m0, s61
	s_nop 0
	global_load_lds_dwordx4 v180, s[94:95]
	s_waitcnt vmcnt(8)
	s_waitcnt lgkmcnt(0)
	s_barrier
	s_waitcnt lgkmcnt(0)
	v_mfma_f32_16x16x32_bf16 v[80:83], v[40:43], v[140:143], v[80:83]
	v_mfma_f32_16x16x32_bf16 v[80:83], v[44:47], v[144:147], v[80:83]
	v_mfma_f32_16x16x32_bf16 v[36:39], v[64:67], v[156:159], v[36:39]
	v_mfma_f32_16x16x32_bf16 v[36:39], v[100:103], v[172:175], v[36:39]
	v_mfma_f32_16x16x32_bf16 v[76:79], v[48:51], v[140:143], v[76:79]
	v_mfma_f32_16x16x32_bf16 v[76:79], v[52:55], v[144:147], v[76:79]
	v_mfma_f32_16x16x32_bf16 v[32:35], v[120:123], v[156:159], v[32:35]
	v_mfma_f32_16x16x32_bf16 v[32:35], v[124:127], v[172:175], v[32:35]
	v_mfma_f32_16x16x32_bf16 v[60:63], v[40:43], v[156:159], v[60:63]
	v_mfma_f32_16x16x32_bf16 v[60:63], v[44:47], v[172:175], v[60:63]
	v_mfma_f32_16x16x32_bf16 v[20:23], v[64:67], v[190:193], v[20:23]
	v_mfma_f32_16x16x32_bf16 v[20:23], v[100:103], v[196:199], v[20:23]
	v_mfma_f32_16x16x32_bf16 v[56:59], v[48:51], v[156:159], v[56:59]
	v_mfma_f32_16x16x32_bf16 v[56:59], v[52:55], v[172:175], v[56:59]
	v_mfma_f32_16x16x32_bf16 v[16:19], v[120:123], v[190:193], v[16:19]
	v_mfma_f32_16x16x32_bf16 v[16:19], v[124:127], v[196:199], v[16:19]
	v_mfma_f32_16x16x32_bf16 v[28:31], v[40:43], v[190:193], v[28:31]
	v_mfma_f32_16x16x32_bf16 v[28:31], v[44:47], v[196:199], v[28:31]
	v_mfma_f32_16x16x32_bf16 v[4:7], v[64:67], v[200:203], v[4:7]
	v_mfma_f32_16x16x32_bf16 v[4:7], v[100:103], v[204:207], v[4:7]
	v_mfma_f32_16x16x32_bf16 v[24:27], v[48:51], v[190:193], v[24:27]
	v_mfma_f32_16x16x32_bf16 v[24:27], v[52:55], v[196:199], v[24:27]
	v_mfma_f32_16x16x32_bf16 v[0:3], v[120:123], v[200:203], v[0:3]
	v_mfma_f32_16x16x32_bf16 v[0:3], v[124:127], v[204:207], v[0:3]
	v_mfma_f32_16x16x32_bf16 v[12:15], v[40:43], v[200:203], v[12:15]
	v_mfma_f32_16x16x32_bf16 v[12:15], v[44:47], v[204:207], v[12:15]
	v_mfma_f32_16x16x32_bf16 v[40:43], v[64:67], v[140:143], v[72:75]
	v_mfma_f32_16x16x32_bf16 v[40:43], v[100:103], v[144:147], v[40:43]
	v_mfma_f32_16x16x32_bf16 v[8:11], v[48:51], v[200:203], v[8:11]
	v_mfma_f32_16x16x32_bf16 v[8:11], v[52:55], v[204:207], v[8:11]
	v_mfma_f32_16x16x32_bf16 v[44:47], v[120:123], v[140:143], v[68:71]
	v_mfma_f32_16x16x32_bf16 v[44:47], v[124:127], v[144:147], v[44:47]
	s_barrier
	s_add_i32 s67, 0, 0x18000
	s_add_i32 s87, 0, 0x1c000
	ds_read_b128 v[48:51], v177 offset:32768
	ds_read_b128 v[52:55], v177 offset:33792
	ds_read_b128 v[64:67], v177 offset:34816
	ds_read_b128 v[68:71], v177 offset:35840
	ds_read_b128 v[100:103], v177 offset:49152
	ds_read_b128 v[120:123], v177 offset:50176
	ds_read_b128 v[124:127], v177 offset:51200
	ds_read_b128 v[140:143], v177 offset:52224
	s_add_u32 s94, s94, 0x80000
	s_addc_u32 s95, s95, 0
	s_mov_b32 m0, s68
	ds_read_b128 v[72:75], v195 offset:32768
	ds_read_b128 v[144:147], v195 offset:33792
	ds_read_b128 v[172:175], v195 offset:34816
	ds_read_b128 v[190:193], v195 offset:35840
	ds_read_b128 v[196:199], v195 offset:36864
	ds_read_b128 v[200:203], v195 offset:37888
	ds_read_b128 v[204:207], v195 offset:38912
	ds_read_b128 v[208:211], v195 offset:39936
	global_load_lds_dwordx4 v176, s[94:95]
	s_mov_b32 m0, s69
	s_nop 0
	global_load_lds_dwordx4 v180, s[94:95]
	s_waitcnt vmcnt(8)
	s_waitcnt lgkmcnt(0)
	s_barrier
	s_waitcnt lgkmcnt(0)
	v_mfma_f32_16x16x32_bf16 v[156:159], v[48:51], v[72:75], v[168:171]
	v_mfma_f32_16x16x32_bf16 v[168:171], v[52:55], v[144:147], v[156:159]
	v_mfma_f32_16x16x32_bf16 v[156:159], v[64:67], v[72:75], v[164:167]
	v_mfma_f32_16x16x32_bf16 v[164:167], v[68:71], v[144:147], v[156:159]
	v_mfma_f32_16x16x32_bf16 v[152:155], v[48:51], v[172:175], v[152:155]
	v_mfma_f32_16x16x32_bf16 v[152:155], v[52:55], v[190:193], v[152:155]
	v_mfma_f32_16x16x32_bf16 v[148:151], v[64:67], v[172:175], v[148:151]
	v_mfma_f32_16x16x32_bf16 v[148:151], v[68:71], v[190:193], v[148:151]
	v_mfma_f32_16x16x32_bf16 v[116:119], v[48:51], v[196:199], v[116:119]
	v_mfma_f32_16x16x32_bf16 v[116:119], v[52:55], v[200:203], v[116:119]
	v_mfma_f32_16x16x32_bf16 v[112:115], v[64:67], v[196:199], v[112:115]
	v_mfma_f32_16x16x32_bf16 v[112:115], v[68:71], v[200:203], v[112:115]
	v_mfma_f32_16x16x32_bf16 v[96:99], v[48:51], v[204:207], v[96:99]
	v_mfma_f32_16x16x32_bf16 v[96:99], v[52:55], v[208:211], v[96:99]
	v_mfma_f32_16x16x32_bf16 v[92:95], v[64:67], v[204:207], v[92:95]
	v_mfma_f32_16x16x32_bf16 v[92:95], v[68:71], v[208:211], v[92:95]
	v_mfma_f32_16x16x32_bf16 v[156:159], v[100:103], v[72:75], v[160:163]
	v_mfma_f32_16x16x32_bf16 v[160:163], v[120:123], v[144:147], v[156:159]
	v_mfma_f32_16x16x32_bf16 v[72:75], v[124:127], v[72:75], v[136:139]
	v_mfma_f32_16x16x32_bf16 v[156:159], v[140:143], v[144:147], v[72:75]
	v_mfma_f32_16x16x32_bf16 v[72:75], v[100:103], v[172:175], v[132:135]
	v_mfma_f32_16x16x32_bf16 v[132:135], v[120:123], v[190:193], v[72:75]
	v_mfma_f32_16x16x32_bf16 v[72:75], v[124:127], v[172:175], v[128:131]
	v_mfma_f32_16x16x32_bf16 v[128:131], v[140:143], v[190:193], v[72:75]
	v_mfma_f32_16x16x32_bf16 v[72:75], v[100:103], v[196:199], v[108:111]
	v_mfma_f32_16x16x32_bf16 v[108:111], v[120:123], v[200:203], v[72:75]
	v_mfma_f32_16x16x32_bf16 v[72:75], v[124:127], v[196:199], v[104:107]
	v_mfma_f32_16x16x32_bf16 v[104:107], v[140:143], v[200:203], v[72:75]
	v_mfma_f32_16x16x32_bf16 v[72:75], v[100:103], v[204:207], v[88:91]
	v_mfma_f32_16x16x32_bf16 v[88:91], v[120:123], v[208:211], v[72:75]
	v_mfma_f32_16x16x32_bf16 v[72:75], v[124:127], v[204:207], v[84:87]
	v_mfma_f32_16x16x32_bf16 v[84:87], v[140:143], v[208:211], v[72:75]
	s_barrier
	s_add_i32 s67, s67, s56
	s_nop 3
	s_add_u32 s98, s92, 0x80
	s_addc_u32 s99, s93, 0
	s_mov_b32 m0, s67
	ds_read_b128 v[136:139], v195 offset:49152
	ds_read_b128 v[144:147], v195 offset:50176
	ds_read_b128 v[172:175], v195 offset:51200
	ds_read_b128 v[190:193], v195 offset:52224
	ds_read_b128 v[196:199], v195 offset:53248
	ds_read_b128 v[200:203], v195 offset:54272
	ds_read_b128 v[204:207], v195 offset:55296
	ds_read_b128 v[208:211], v195 offset:56320
	global_load_lds_dwordx4 v178, s[98:99]
	s_add_i32 m0, s67, 0x2000
	s_add_u32 s92, s92, 0x80080
	s_addc_u32 s93, s93, 0
	s_add_i32 s67, s87, s56
	global_load_lds_dwordx4 v182, s[98:99]
	s_mov_b32 m0, s67
	s_nop 0
	global_load_lds_dwordx4 v178, s[92:93]
	s_add_i32 m0, s67, 0x2000
	s_nop 0
	global_load_lds_dwordx4 v182, s[92:93]
	s_add_u32 s98, s94, 0xfff80080
	s_addc_u32 s99, s95, -1
	s_mov_b32 m0, s2
	s_nop 0
	global_load_lds_dwordx4 v176, s[98:99]
	s_mov_b32 m0, s28
	s_nop 0
	global_load_lds_dwordx4 v180, s[98:99]
	s_waitcnt vmcnt(8)
	s_waitcnt lgkmcnt(0)
	s_barrier
	s_waitcnt lgkmcnt(0)
	v_mfma_f32_16x16x32_bf16 v[72:75], v[48:51], v[136:139], v[80:83]
	v_mfma_f32_16x16x32_bf16 v[80:83], v[52:55], v[144:147], v[72:75]
	v_mfma_f32_16x16x32_bf16 v[72:75], v[64:67], v[136:139], v[76:79]
	v_mfma_f32_16x16x32_bf16 v[76:79], v[68:71], v[144:147], v[72:75]
	v_mfma_f32_16x16x32_bf16 v[60:63], v[48:51], v[172:175], v[60:63]
	v_mfma_f32_16x16x32_bf16 v[60:63], v[52:55], v[190:193], v[60:63]
	v_mfma_f32_16x16x32_bf16 v[56:59], v[64:67], v[172:175], v[56:59]
	v_mfma_f32_16x16x32_bf16 v[56:59], v[68:71], v[190:193], v[56:59]
	v_mfma_f32_16x16x32_bf16 v[28:31], v[48:51], v[196:199], v[28:31]
	v_mfma_f32_16x16x32_bf16 v[28:31], v[52:55], v[200:203], v[28:31]
	v_mfma_f32_16x16x32_bf16 v[24:27], v[64:67], v[196:199], v[24:27]
	v_mfma_f32_16x16x32_bf16 v[24:27], v[68:71], v[200:203], v[24:27]
	v_mfma_f32_16x16x32_bf16 v[12:15], v[48:51], v[204:207], v[12:15]
	v_mfma_f32_16x16x32_bf16 v[12:15], v[52:55], v[208:211], v[12:15]
	v_mfma_f32_16x16x32_bf16 v[8:11], v[64:67], v[204:207], v[8:11]
	v_mfma_f32_16x16x32_bf16 v[8:11], v[68:71], v[208:211], v[8:11]
	v_mfma_f32_16x16x32_bf16 v[40:43], v[100:103], v[136:139], v[40:43]
	v_mfma_f32_16x16x32_bf16 v[72:75], v[120:123], v[144:147], v[40:43]
	v_mfma_f32_16x16x32_bf16 v[40:43], v[124:127], v[136:139], v[44:47]
	v_mfma_f32_16x16x32_bf16 v[68:71], v[140:143], v[144:147], v[40:43]
	v_mfma_f32_16x16x32_bf16 v[36:39], v[100:103], v[172:175], v[36:39]
	v_mfma_f32_16x16x32_bf16 v[36:39], v[120:123], v[190:193], v[36:39]
	v_mfma_f32_16x16x32_bf16 v[32:35], v[124:127], v[172:175], v[32:35]
	v_mfma_f32_16x16x32_bf16 v[32:35], v[140:143], v[190:193], v[32:35]
	v_mfma_f32_16x16x32_bf16 v[20:23], v[100:103], v[196:199], v[20:23]
	v_mfma_f32_16x16x32_bf16 v[20:23], v[120:123], v[200:203], v[20:23]
	v_mfma_f32_16x16x32_bf16 v[16:19], v[124:127], v[196:199], v[16:19]
	v_mfma_f32_16x16x32_bf16 v[16:19], v[140:143], v[200:203], v[16:19]
	v_mfma_f32_16x16x32_bf16 v[4:7], v[100:103], v[204:207], v[4:7]
	v_mfma_f32_16x16x32_bf16 v[4:7], v[120:123], v[208:211], v[4:7]
	v_mfma_f32_16x16x32_bf16 v[0:3], v[124:127], v[204:207], v[0:3]
	v_mfma_f32_16x16x32_bf16 v[0:3], v[140:143], v[208:211], v[0:3]
	s_barrier
	s_add_i32 s85, s85, 2
	s_add_u32 s10, s10, 0x100
	s_addc_u32 s11, s11, 0
	s_add_u32 s54, s54, 0x100
	s_addc_u32 s55, s55, 0
	s_cmp_gt_u32 s85, 29
	s_cbranch_scc0 .LBB0_639
	s_and_b64 vcc, exec, s[80:81]
	s_cbranch_vccz .LBB0_642
	s_barrier

.LBB0_964:
	s_ashr_i32 s79, s78, 31
	s_lshl_b64 s[82:83], s[78:79], 20
	s_add_u32 s82, s14, s82
	s_addc_u32 s83, s15, s83
	s_and_b64 s[84:85], s[80:81], exec
	s_cselect_b32 s79, s83, s93
	s_cselect_b32 s96, s82, s92
	s_ashr_i32 s77, s76, 31
	s_lshl_b64 s[84:85], s[76:77], 20
	s_add_u32 s84, s24, s84
	s_addc_u32 s85, s26, s85
	s_and_b64 vcc, s[80:81], exec
	s_cselect_b32 s77, s85, s91
	s_cselect_b32 vcc_lo, s84, s90
	s_lshl_b32 s86, s86, 8
	s_ashr_i32 s87, s86, 31
	s_lshl_b64 s[74:75], s[86:87], 2
	s_add_u32 s74, s88, s74
	s_addc_u32 s75, s89, s75
	s_add_i32 m0, s71, s40
	s_add_u32 s88, s92, 0x80080
	global_load_lds_dwordx4 v239, s[74:75]
	s_addc_u32 s89, s93, 0
	s_add_u32 s87, s90, 0x100
	s_addc_u32 vcc_hi, s91, 0
	s_mov_b32 s71, -2
	s_waitcnt vmcnt(0)
	v_add_u32_e32 v192, 0x10000, v238
	s_add_u32 s67, s88, 0xfff80080
	s_addc_u32 s74, s89, -1
	s_add_i32 s75, 0, 0x10000
	s_cmp_eq_u32 s71, 28
	s_cselect_b32 s93, s79, s74
	s_cselect_b32 s92, s96, s67
	s_cselect_b32 s91, s77, vcc_hi
	s_cselect_b32 s90, vcc_lo, s87
	s_add_i32 s67, 0, 0x14000
	ds_read_b128 v[64:67], v192
	ds_read_b128 v[72:75], v192 offset:1024
	ds_read_b128 v[88:91], v192 offset:2048
	ds_read_b128 v[96:99], v192 offset:3072
	ds_read_b128 v[108:111], v192 offset:16384
	ds_read_b128 v[116:119], v192 offset:17408
	ds_read_b128 v[128:131], v192 offset:18432
	ds_read_b128 v[140:143], v192 offset:19456
	s_add_i32 m0, s28, 0xc000
	ds_read_b128 v[152:155], v240
	ds_read_b128 v[156:159], v240 offset:1024
	ds_read_b128 v[160:163], v240 offset:2048
	ds_read_b128 v[164:167], v240 offset:3072
	ds_read_b128 v[168:171], v240 offset:4096
	ds_read_b128 v[180:183], v240 offset:5120
	ds_read_b128 v[184:187], v240 offset:6144
	ds_read_b128 v[188:191], v240 offset:7168
	global_load_lds_dwordx4 v230, s[88:89]
	s_add_i32 m0, s28, 0xe000
	s_nop 0
	global_load_lds_dwordx4 v232, s[88:89]
	s_cmp_lg_u32 s94, 1
	s_cbranch_scc1 .Lds4_0
	s_waitcnt vmcnt(8)

.Lds4_1:
	s_waitcnt lgkmcnt(0)
	s_barrier
	s_waitcnt lgkmcnt(0)
	v_mfma_f32_16x16x32_bf16 v[60:63], v[64:67], v[152:155], 0
	v_mfma_f32_16x16x32_bf16 v[60:63], v[72:75], v[156:159], v[60:63]
	v_mfma_f32_16x16x32_bf16 v[52:55], v[108:111], v[152:155], 0
	v_mfma_f32_16x16x32_bf16 v[52:55], v[116:119], v[156:159], v[52:55]
	v_mfma_f32_16x16x32_bf16 v[56:59], v[88:91], v[152:155], 0
	v_mfma_f32_16x16x32_bf16 v[56:59], v[96:99], v[156:159], v[56:59]
	v_mfma_f32_16x16x32_bf16 v[48:51], v[128:131], v[152:155], 0
	v_mfma_f32_16x16x32_bf16 v[48:51], v[140:143], v[156:159], v[48:51]
	v_mfma_f32_16x16x32_bf16 v[44:47], v[64:67], v[160:163], 0
	v_mfma_f32_16x16x32_bf16 v[44:47], v[72:75], v[164:167], v[44:47]
	v_mfma_f32_16x16x32_bf16 v[36:39], v[108:111], v[160:163], 0
	v_mfma_f32_16x16x32_bf16 v[36:39], v[116:119], v[164:167], v[36:39]
	v_mfma_f32_16x16x32_bf16 v[40:43], v[88:91], v[160:163], 0
	v_mfma_f32_16x16x32_bf16 v[40:43], v[96:99], v[164:167], v[40:43]
	v_mfma_f32_16x16x32_bf16 v[32:35], v[128:131], v[160:163], 0
	v_mfma_f32_16x16x32_bf16 v[32:35], v[140:143], v[164:167], v[32:35]
	v_mfma_f32_16x16x32_bf16 v[28:31], v[64:67], v[168:171], 0
	v_mfma_f32_16x16x32_bf16 v[28:31], v[72:75], v[180:183], v[28:31]
	v_mfma_f32_16x16x32_bf16 v[20:23], v[108:111], v[168:171], 0
	v_mfma_f32_16x16x32_bf16 v[20:23], v[116:119], v[180:183], v[20:23]
	v_mfma_f32_16x16x32_bf16 v[24:27], v[88:91], v[168:171], 0
	v_mfma_f32_16x16x32_bf16 v[24:27], v[96:99], v[180:183], v[24:27]
	v_mfma_f32_16x16x32_bf16 v[16:19], v[128:131], v[168:171], 0
	v_mfma_f32_16x16x32_bf16 v[16:19], v[140:143], v[180:183], v[16:19]
	v_mfma_f32_16x16x32_bf16 v[12:15], v[64:67], v[184:187], 0
	v_mfma_f32_16x16x32_bf16 v[12:15], v[72:75], v[188:191], v[12:15]
	v_mfma_f32_16x16x32_bf16 v[4:7], v[108:111], v[184:187], 0
	v_mfma_f32_16x16x32_bf16 v[4:7], v[116:119], v[188:191], v[4:7]
	v_mfma_f32_16x16x32_bf16 v[8:11], v[88:91], v[184:187], 0
	v_mfma_f32_16x16x32_bf16 v[8:11], v[96:99], v[188:191], v[8:11]
	v_mfma_f32_16x16x32_bf16 v[0:3], v[128:131], v[184:187], 0
	v_mfma_f32_16x16x32_bf16 v[0:3], v[140:143], v[188:191], v[0:3]
	s_barrier
	s_add_i32 s67, 0, 0x18000
	s_add_i32 s3, 0, 0x1c000
	ds_read_b128 v[64:67], v192 offset:32768
	ds_read_b128 v[72:75], v192 offset:33792
	ds_read_b128 v[88:91], v192 offset:34816
	ds_read_b128 v[96:99], v192 offset:35840
	ds_read_b128 v[108:111], v192 offset:49152
	ds_read_b128 v[116:119], v192 offset:50176
	ds_read_b128 v[128:131], v192 offset:51200
	ds_read_b128 v[140:143], v192 offset:52224
	s_add_u32 s74, s92, 0x80000
	s_addc_u32 s75, s93, 0
	s_mov_b32 m0, s34
	ds_read_b128 v[152:155], v240 offset:32768
	ds_read_b128 v[156:159], v240 offset:33792
	ds_read_b128 v[160:163], v240 offset:34816
	ds_read_b128 v[164:167], v240 offset:35840
	ds_read_b128 v[168:171], v240 offset:36864
	ds_read_b128 v[180:183], v240 offset:37888
	ds_read_b128 v[184:187], v240 offset:38912
	ds_read_b128 v[188:191], v240 offset:39936
	global_load_lds_dwordx4 v224, s[74:75]
	s_mov_b32 m0, s35
	s_nop 0
	global_load_lds_dwordx4 v226, s[74:75]
	s_waitcnt vmcnt(8)
	s_waitcnt lgkmcnt(0)
	s_barrier
	s_waitcnt lgkmcnt(0)
	v_mfma_f32_16x16x32_bf16 v[176:179], v[64:67], v[152:155], v[176:179]
	v_mfma_f32_16x16x32_bf16 v[176:179], v[72:75], v[156:159], v[176:179]
	v_mfma_f32_16x16x32_bf16 v[148:151], v[108:111], v[152:155], v[148:151]
	v_mfma_f32_16x16x32_bf16 v[148:151], v[116:119], v[156:159], v[148:151]
	v_mfma_f32_16x16x32_bf16 v[172:175], v[88:91], v[152:155], v[172:175]
	v_mfma_f32_16x16x32_bf16 v[172:175], v[96:99], v[156:159], v[172:175]
	v_mfma_f32_16x16x32_bf16 v[144:147], v[128:131], v[152:155], v[144:147]
	v_mfma_f32_16x16x32_bf16 v[144:147], v[140:143], v[156:159], v[144:147]
	v_mfma_f32_16x16x32_bf16 v[136:139], v[64:67], v[160:163], v[136:139]
	v_mfma_f32_16x16x32_bf16 v[136:139], v[72:75], v[164:167], v[136:139]
	v_mfma_f32_16x16x32_bf16 v[124:127], v[108:111], v[160:163], v[124:127]
	v_mfma_f32_16x16x32_bf16 v[124:127], v[116:119], v[164:167], v[124:127]
	v_mfma_f32_16x16x32_bf16 v[132:135], v[88:91], v[160:163], v[132:135]
	v_mfma_f32_16x16x32_bf16 v[132:135], v[96:99], v[164:167], v[132:135]
	v_mfma_f32_16x16x32_bf16 v[120:123], v[128:131], v[160:163], v[120:123]
	v_mfma_f32_16x16x32_bf16 v[120:123], v[140:143], v[164:167], v[120:123]
	v_mfma_f32_16x16x32_bf16 v[112:115], v[64:67], v[168:171], v[112:115]
	v_mfma_f32_16x16x32_bf16 v[112:115], v[72:75], v[180:183], v[112:115]
	v_mfma_f32_16x16x32_bf16 v[100:103], v[108:111], v[168:171], v[100:103]
	v_mfma_f32_16x16x32_bf16 v[100:103], v[116:119], v[180:183], v[100:103]
	v_mfma_f32_16x16x32_bf16 v[104:107], v[88:91], v[168:171], v[104:107]
	v_mfma_f32_16x16x32_bf16 v[104:107], v[96:99], v[180:183], v[104:107]
	v_mfma_f32_16x16x32_bf16 v[92:95], v[128:131], v[168:171], v[92:95]
	v_mfma_f32_16x16x32_bf16 v[92:95], v[140:143], v[180:183], v[92:95]
	v_mfma_f32_16x16x32_bf16 v[84:87], v[64:67], v[184:187], v[84:87]
	v_mfma_f32_16x16x32_bf16 v[84:87], v[72:75], v[188:191], v[84:87]
	v_mfma_f32_16x16x32_bf16 v[76:79], v[108:111], v[184:187], v[76:79]
	v_mfma_f32_16x16x32_bf16 v[76:79], v[116:119], v[188:191], v[76:79]
	v_mfma_f32_16x16x32_bf16 v[80:83], v[88:91], v[184:187], v[80:83]
	v_mfma_f32_16x16x32_bf16 v[80:83], v[96:99], v[188:191], v[80:83]
	v_mfma_f32_16x16x32_bf16 v[68:71], v[128:131], v[184:187], v[68:71]
	v_mfma_f32_16x16x32_bf16 v[68:71], v[140:143], v[188:191], v[68:71]
	s_barrier
	s_add_i32 s67, s67, s2
	s_add_u32 s98, s90, 0x80
	s_addc_u32 s99, s91, 0
	s_mov_b32 m0, s67
	ds_read_b128 v[152:155], v240 offset:49152
	ds_read_b128 v[156:159], v240 offset:50176
	ds_read_b128 v[160:163], v240 offset:51200
	ds_read_b128 v[164:167], v240 offset:52224
	ds_read_b128 v[168:171], v240 offset:53248
	ds_read_b128 v[180:183], v240 offset:54272
	ds_read_b128 v[184:187], v240 offset:55296
	ds_read_b128 v[188:191], v240 offset:56320
	global_load_lds_dwordx4 v216, s[98:99]
	s_add_i32 m0, s67, 0x2000
	s_add_u32 s74, s90, 0x80080
	s_addc_u32 s75, s91, 0
	s_add_i32 s3, s3, s2
	global_load_lds_dwordx4 v228, s[98:99]
	s_mov_b32 m0, s3
	s_nop 0
	global_load_lds_dwordx4 v216, s[74:75]
	s_add_i32 m0, s3, 0x2000
	s_nop 0
	global_load_lds_dwordx4 v228, s[74:75]
	s_add_u32 s98, s92, 0x80
	s_addc_u32 s99, s93, 0
	s_mov_b32 m0, s60
	s_nop 0
	global_load_lds_dwordx4 v224, s[98:99]
	s_mov_b32 m0, s61
	s_nop 0
	global_load_lds_dwordx4 v226, s[98:99]
	s_waitcnt vmcnt(8)
	s_waitcnt lgkmcnt(0)
	s_barrier
	s_waitcnt lgkmcnt(0)
	v_mfma_f32_16x16x32_bf16 v[60:63], v[64:67], v[152:155], v[60:63]
	v_mfma_f32_16x16x32_bf16 v[60:63], v[72:75], v[156:159], v[60:63]
	v_mfma_f32_16x16x32_bf16 v[52:55], v[108:111], v[152:155], v[52:55]
	v_mfma_f32_16x16x32_bf16 v[52:55], v[116:119], v[156:159], v[52:55]
	v_mfma_f32_16x16x32_bf16 v[56:59], v[88:91], v[152:155], v[56:59]
	v_mfma_f32_16x16x32_bf16 v[56:59], v[96:99], v[156:159], v[56:59]
	v_mfma_f32_16x16x32_bf16 v[48:51], v[128:131], v[152:155], v[48:51]
	v_mfma_f32_16x16x32_bf16 v[48:51], v[140:143], v[156:159], v[48:51]
	v_mfma_f32_16x16x32_bf16 v[44:47], v[64:67], v[160:163], v[44:47]
	v_mfma_f32_16x16x32_bf16 v[44:47], v[72:75], v[164:167], v[44:47]
	v_mfma_f32_16x16x32_bf16 v[36:39], v[108:111], v[160:163], v[36:39]
	v_mfma_f32_16x16x32_bf16 v[36:39], v[116:119], v[164:167], v[36:39]
	v_mfma_f32_16x16x32_bf16 v[40:43], v[88:91], v[160:163], v[40:43]
	v_mfma_f32_16x16x32_bf16 v[40:43], v[96:99], v[164:167], v[40:43]
	v_mfma_f32_16x16x32_bf16 v[32:35], v[128:131], v[160:163], v[32:35]
	v_mfma_f32_16x16x32_bf16 v[32:35], v[140:143], v[164:167], v[32:35]
	v_mfma_f32_16x16x32_bf16 v[28:31], v[64:67], v[168:171], v[28:31]
	v_mfma_f32_16x16x32_bf16 v[28:31], v[72:75], v[180:183], v[28:31]
	v_mfma_f32_16x16x32_bf16 v[20:23], v[108:111], v[168:171], v[20:23]
	v_mfma_f32_16x16x32_bf16 v[20:23], v[116:119], v[180:183], v[20:23]
	v_mfma_f32_16x16x32_bf16 v[24:27], v[88:91], v[168:171], v[24:27]
	v_mfma_f32_16x16x32_bf16 v[24:27], v[96:99], v[180:183], v[24:27]
	v_mfma_f32_16x16x32_bf16 v[16:19], v[128:131], v[168:171], v[16:19]
	v_mfma_f32_16x16x32_bf16 v[16:19], v[140:143], v[180:183], v[16:19]
	v_mfma_f32_16x16x32_bf16 v[12:15], v[64:67], v[184:187], v[12:15]
	v_mfma_f32_16x16x32_bf16 v[12:15], v[72:75], v[188:191], v[12:15]
	v_mfma_f32_16x16x32_bf16 v[4:7], v[108:111], v[184:187], v[4:7]
	v_mfma_f32_16x16x32_bf16 v[4:7], v[116:119], v[188:191], v[4:7]
	v_mfma_f32_16x16x32_bf16 v[8:11], v[88:91], v[184:187], v[8:11]
	v_mfma_f32_16x16x32_bf16 v[8:11], v[96:99], v[188:191], v[8:11]
	v_mfma_f32_16x16x32_bf16 v[0:3], v[128:131], v[184:187], v[0:3]
	v_mfma_f32_16x16x32_bf16 v[0:3], v[140:143], v[188:191], v[0:3]
	s_barrier
	s_add_i32 s71, s71, 2
	s_add_u32 s88, s88, 0x100
	s_addc_u32 s89, s89, 0
	s_add_u32 s87, s87, 0x100
	s_addc_u32 vcc_hi, vcc_hi, 0
.LBB0_965:
	s_add_u32 s67, s88, 0xfff80080
	s_addc_u32 s74, s89, -1
	s_add_i32 s75, 0, 0x10000
	s_cmp_eq_u32 s71, 28
	s_cselect_b32 s93, s79, s74
	s_cselect_b32 s92, s96, s67
	s_cselect_b32 s91, s77, vcc_hi
	s_cselect_b32 s90, vcc_lo, s87
	s_add_i32 s67, 0, 0x14000
	ds_read_b128 v[64:67], v192
	ds_read_b128 v[72:75], v192 offset:1024
	ds_read_b128 v[88:91], v192 offset:2048
	ds_read_b128 v[96:99], v192 offset:3072
	ds_read_b128 v[108:111], v192 offset:16384
	ds_read_b128 v[116:119], v192 offset:17408
	ds_read_b128 v[128:131], v192 offset:18432
	ds_read_b128 v[140:143], v192 offset:19456
	s_add_i32 m0, s28, 0xc000
	ds_read_b128 v[152:155], v240
	ds_read_b128 v[156:159], v240 offset:1024
	ds_read_b128 v[160:163], v240 offset:2048
	ds_read_b128 v[164:167], v240 offset:3072
	ds_read_b128 v[168:171], v240 offset:4096
	ds_read_b128 v[180:183], v240 offset:5120
	ds_read_b128 v[184:187], v240 offset:6144
	ds_read_b128 v[188:191], v240 offset:7168
	global_load_lds_dwordx4 v230, s[88:89]
	s_add_i32 m0, s28, 0xe000
	s_nop 0
	global_load_lds_dwordx4 v232, s[88:89]
	s_waitcnt vmcnt(8)
	s_waitcnt lgkmcnt(0)
	s_barrier
	s_waitcnt lgkmcnt(0)
	v_mfma_f32_16x16x32_bf16 v[176:179], v[64:67], v[152:155], v[176:179]
	v_mfma_f32_16x16x32_bf16 v[176:179], v[72:75], v[156:159], v[176:179]
	v_mfma_f32_16x16x32_bf16 v[148:151], v[108:111], v[152:155], v[148:151]
	v_mfma_f32_16x16x32_bf16 v[148:151], v[116:119], v[156:159], v[148:151]
	v_mfma_f32_16x16x32_bf16 v[172:175], v[88:91], v[152:155], v[172:175]
	v_mfma_f32_16x16x32_bf16 v[172:175], v[96:99], v[156:159], v[172:175]
	v_mfma_f32_16x16x32_bf16 v[144:147], v[128:131], v[152:155], v[144:147]
	v_mfma_f32_16x16x32_bf16 v[144:147], v[140:143], v[156:159], v[144:147]
	v_mfma_f32_16x16x32_bf16 v[136:139], v[64:67], v[160:163], v[136:139]
	v_mfma_f32_16x16x32_bf16 v[136:139], v[72:75], v[164:167], v[136:139]
	v_mfma_f32_16x16x32_bf16 v[124:127], v[108:111], v[160:163], v[124:127]
	v_mfma_f32_16x16x32_bf16 v[124:127], v[116:119], v[164:167], v[124:127]
	v_mfma_f32_16x16x32_bf16 v[132:135], v[88:91], v[160:163], v[132:135]
	v_mfma_f32_16x16x32_bf16 v[132:135], v[96:99], v[164:167], v[132:135]
	v_mfma_f32_16x16x32_bf16 v[120:123], v[128:131], v[160:163], v[120:123]
	v_mfma_f32_16x16x32_bf16 v[120:123], v[140:143], v[164:167], v[120:123]
	v_mfma_f32_16x16x32_bf16 v[112:115], v[64:67], v[168:171], v[112:115]
	v_mfma_f32_16x16x32_bf16 v[112:115], v[72:75], v[180:183], v[112:115]
	v_mfma_f32_16x16x32_bf16 v[100:103], v[108:111], v[168:171], v[100:103]
	v_mfma_f32_16x16x32_bf16 v[100:103], v[116:119], v[180:183], v[100:103]
	v_mfma_f32_16x16x32_bf16 v[104:107], v[88:91], v[168:171], v[104:107]
	v_mfma_f32_16x16x32_bf16 v[104:107], v[96:99], v[180:183], v[104:107]
	v_mfma_f32_16x16x32_bf16 v[92:95], v[128:131], v[168:171], v[92:95]
	v_mfma_f32_16x16x32_bf16 v[92:95], v[140:143], v[180:183], v[92:95]
	v_mfma_f32_16x16x32_bf16 v[84:87], v[64:67], v[184:187], v[84:87]
	v_mfma_f32_16x16x32_bf16 v[84:87], v[72:75], v[188:191], v[84:87]
	v_mfma_f32_16x16x32_bf16 v[76:79], v[108:111], v[184:187], v[76:79]
	v_mfma_f32_16x16x32_bf16 v[76:79], v[116:119], v[188:191], v[76:79]
	v_mfma_f32_16x16x32_bf16 v[80:83], v[88:91], v[184:187], v[80:83]
	v_mfma_f32_16x16x32_bf16 v[80:83], v[96:99], v[188:191], v[80:83]
	v_mfma_f32_16x16x32_bf16 v[68:71], v[128:131], v[184:187], v[68:71]
	v_mfma_f32_16x16x32_bf16 v[68:71], v[140:143], v[188:191], v[68:71]
	s_barrier
	s_add_i32 s74, s75, s2
	s_mov_b32 m0, s74
	ds_read_b128 v[152:155], v240 offset:16384
	ds_read_b128 v[156:159], v240 offset:17408
	ds_read_b128 v[160:163], v240 offset:18432
	ds_read_b128 v[164:167], v240 offset:19456
	ds_read_b128 v[168:171], v240 offset:20480
	ds_read_b128 v[180:183], v240 offset:21504
	ds_read_b128 v[184:187], v240 offset:22528
	ds_read_b128 v[188:191], v240 offset:23552
	global_load_lds_dwordx4 v216, s[90:91]
	s_add_i32 m0, s74, 0x2000
	s_add_u32 s74, s90, 0x80000
	s_addc_u32 s75, s91, 0
	s_add_i32 s67, s67, s2
	global_load_lds_dwordx4 v228, s[90:91]
	s_mov_b32 m0, s67
	s_nop 0
	global_load_lds_dwordx4 v216, s[74:75]
	s_add_i32 m0, s67, 0x2000
	s_nop 0
	global_load_lds_dwordx4 v228, s[74:75]
	s_mov_b32 m0, s28
	s_nop 0
	global_load_lds_dwordx4 v224, s[92:93]
	s_mov_b32 m0, s29
	s_nop 0
	global_load_lds_dwordx4 v226, s[92:93]
	s_waitcnt vmcnt(8)
	s_waitcnt lgkmcnt(0)
	s_barrier
	s_waitcnt lgkmcnt(0)
	v_mfma_f32_16x16x32_bf16 v[60:63], v[64:67], v[152:155], v[60:63]
	v_mfma_f32_16x16x32_bf16 v[60:63], v[72:75], v[156:159], v[60:63]
	v_mfma_f32_16x16x32_bf16 v[52:55], v[108:111], v[152:155], v[52:55]
	v_mfma_f32_16x16x32_bf16 v[52:55], v[116:119], v[156:159], v[52:55]
	v_mfma_f32_16x16x32_bf16 v[56:59], v[88:91], v[152:155], v[56:59]
	v_mfma_f32_16x16x32_bf16 v[56:59], v[96:99], v[156:159], v[56:59]
	v_mfma_f32_16x16x32_bf16 v[48:51], v[128:131], v[152:155], v[48:51]
	v_mfma_f32_16x16x32_bf16 v[48:51], v[140:143], v[156:159], v[48:51]
	v_mfma_f32_16x16x32_bf16 v[44:47], v[64:67], v[160:163], v[44:47]
	v_mfma_f32_16x16x32_bf16 v[44:47], v[72:75], v[164:167], v[44:47]
	v_mfma_f32_16x16x32_bf16 v[36:39], v[108:111], v[160:163], v[36:39]
	v_mfma_f32_16x16x32_bf16 v[36:39], v[116:119], v[164:167], v[36:39]
	v_mfma_f32_16x16x32_bf16 v[40:43], v[88:91], v[160:163], v[40:43]
	v_mfma_f32_16x16x32_bf16 v[40:43], v[96:99], v[164:167], v[40:43]
	v_mfma_f32_16x16x32_bf16 v[32:35], v[128:131], v[160:163], v[32:35]
	v_mfma_f32_16x16x32_bf16 v[32:35], v[140:143], v[164:167], v[32:35]
	v_mfma_f32_16x16x32_bf16 v[28:31], v[64:67], v[168:171], v[28:31]
	v_mfma_f32_16x16x32_bf16 v[28:31], v[72:75], v[180:183], v[28:31]
	v_mfma_f32_16x16x32_bf16 v[20:23], v[108:111], v[168:171], v[20:23]
	v_mfma_f32_16x16x32_bf16 v[20:23], v[116:119], v[180:183], v[20:23]
	v_mfma_f32_16x16x32_bf16 v[24:27], v[88:91], v[168:171], v[24:27]
	v_mfma_f32_16x16x32_bf16 v[24:27], v[96:99], v[180:183], v[24:27]
	v_mfma_f32_16x16x32_bf16 v[16:19], v[128:131], v[168:171], v[16:19]
	v_mfma_f32_16x16x32_bf16 v[16:19], v[140:143], v[180:183], v[16:19]
	v_mfma_f32_16x16x32_bf16 v[12:15], v[64:67], v[184:187], v[12:15]
	v_mfma_f32_16x16x32_bf16 v[12:15], v[72:75], v[188:191], v[12:15]
	v_mfma_f32_16x16x32_bf16 v[4:7], v[108:111], v[184:187], v[4:7]
	v_mfma_f32_16x16x32_bf16 v[4:7], v[116:119], v[188:191], v[4:7]
	v_mfma_f32_16x16x32_bf16 v[8:11], v[88:91], v[184:187], v[8:11]
	v_mfma_f32_16x16x32_bf16 v[8:11], v[96:99], v[188:191], v[8:11]
	v_mfma_f32_16x16x32_bf16 v[0:3], v[128:131], v[184:187], v[0:3]
	v_mfma_f32_16x16x32_bf16 v[0:3], v[140:143], v[188:191], v[0:3]
	s_barrier
	s_add_i32 s67, 0, 0x18000
	s_add_i32 s3, 0, 0x1c000
	ds_read_b128 v[64:67], v192 offset:32768
	ds_read_b128 v[72:75], v192 offset:33792
	ds_read_b128 v[88:91], v192 offset:34816
	ds_read_b128 v[96:99], v192 offset:35840
	ds_read_b128 v[108:111], v192 offset:49152
	ds_read_b128 v[116:119], v192 offset:50176
	ds_read_b128 v[128:131], v192 offset:51200
	ds_read_b128 v[140:143], v192 offset:52224
	s_add_u32 s74, s92, 0x80000
	s_addc_u32 s75, s93, 0
	s_mov_b32 m0, s34
	ds_read_b128 v[152:155], v240 offset:32768
	ds_read_b128 v[156:159], v240 offset:33792
	ds_read_b128 v[160:163], v240 offset:34816
	ds_read_b128 v[164:167], v240 offset:35840
	ds_read_b128 v[168:171], v240 offset:36864
	ds_read_b128 v[180:183], v240 offset:37888
	ds_read_b128 v[184:187], v240 offset:38912
	ds_read_b128 v[188:191], v240 offset:39936
	global_load_lds_dwordx4 v224, s[74:75]
	s_mov_b32 m0, s35
	s_nop 0
	global_load_lds_dwordx4 v226, s[74:75]
	s_waitcnt vmcnt(8)
	s_waitcnt lgkmcnt(0)
	s_barrier
	s_waitcnt lgkmcnt(0)
	v_mfma_f32_16x16x32_bf16 v[176:179], v[64:67], v[152:155], v[176:179]
	v_mfma_f32_16x16x32_bf16 v[176:179], v[72:75], v[156:159], v[176:179]
	v_mfma_f32_16x16x32_bf16 v[148:151], v[108:111], v[152:155], v[148:151]
	v_mfma_f32_16x16x32_bf16 v[148:151], v[116:119], v[156:159], v[148:151]
	v_mfma_f32_16x16x32_bf16 v[172:175], v[88:91], v[152:155], v[172:175]
	v_mfma_f32_16x16x32_bf16 v[172:175], v[96:99], v[156:159], v[172:175]
	v_mfma_f32_16x16x32_bf16 v[144:147], v[128:131], v[152:155], v[144:147]
	v_mfma_f32_16x16x32_bf16 v[144:147], v[140:143], v[156:159], v[144:147]
	v_mfma_f32_16x16x32_bf16 v[136:139], v[64:67], v[160:163], v[136:139]
	v_mfma_f32_16x16x32_bf16 v[136:139], v[72:75], v[164:167], v[136:139]
	v_mfma_f32_16x16x32_bf16 v[124:127], v[108:111], v[160:163], v[124:127]
	v_mfma_f32_16x16x32_bf16 v[124:127], v[116:119], v[164:167], v[124:127]
	v_mfma_f32_16x16x32_bf16 v[132:135], v[88:91], v[160:163], v[132:135]
	v_mfma_f32_16x16x32_bf16 v[132:135], v[96:99], v[164:167], v[132:135]
	v_mfma_f32_16x16x32_bf16 v[120:123], v[128:131], v[160:163], v[120:123]
	v_mfma_f32_16x16x32_bf16 v[120:123], v[140:143], v[164:167], v[120:123]
	v_mfma_f32_16x16x32_bf16 v[112:115], v[64:67], v[168:171], v[112:115]
	v_mfma_f32_16x16x32_bf16 v[112:115], v[72:75], v[180:183], v[112:115]
	v_mfma_f32_16x16x32_bf16 v[100:103], v[108:111], v[168:171], v[100:103]
	v_mfma_f32_16x16x32_bf16 v[100:103], v[116:119], v[180:183], v[100:103]
	v_mfma_f32_16x16x32_bf16 v[104:107], v[88:91], v[168:171], v[104:107]
	v_mfma_f32_16x16x32_bf16 v[104:107], v[96:99], v[180:183], v[104:107]
	v_mfma_f32_16x16x32_bf16 v[92:95], v[128:131], v[168:171], v[92:95]
	v_mfma_f32_16x16x32_bf16 v[92:95], v[140:143], v[180:183], v[92:95]
	v_mfma_f32_16x16x32_bf16 v[84:87], v[64:67], v[184:187], v[84:87]
	v_mfma_f32_16x16x32_bf16 v[84:87], v[72:75], v[188:191], v[84:87]
	v_mfma_f32_16x16x32_bf16 v[76:79], v[108:111], v[184:187], v[76:79]
	v_mfma_f32_16x16x32_bf16 v[76:79], v[116:119], v[188:191], v[76:79]
	v_mfma_f32_16x16x32_bf16 v[80:83], v[88:91], v[184:187], v[80:83]
	v_mfma_f32_16x16x32_bf16 v[80:83], v[96:99], v[188:191], v[80:83]
	v_mfma_f32_16x16x32_bf16 v[68:71], v[128:131], v[184:187], v[68:71]
	v_mfma_f32_16x16x32_bf16 v[68:71], v[140:143], v[188:191], v[68:71]
	s_barrier
	s_add_i32 s67, s67, s2
	s_add_u32 s98, s90, 0x80
	s_addc_u32 s99, s91, 0
	s_mov_b32 m0, s67
	ds_read_b128 v[152:155], v240 offset:49152
	ds_read_b128 v[156:159], v240 offset:50176
	ds_read_b128 v[160:163], v240 offset:51200
	ds_read_b128 v[164:167], v240 offset:52224
	ds_read_b128 v[168:171], v240 offset:53248
	ds_read_b128 v[180:183], v240 offset:54272
	ds_read_b128 v[184:187], v240 offset:55296
	ds_read_b128 v[188:191], v240 offset:56320
	global_load_lds_dwordx4 v216, s[98:99]
	s_add_i32 m0, s67, 0x2000
	s_add_u32 s74, s90, 0x80080
	s_addc_u32 s75, s91, 0
	s_add_i32 s3, s3, s2
	global_load_lds_dwordx4 v228, s[98:99]
	s_mov_b32 m0, s3
	s_nop 0
	global_load_lds_dwordx4 v216, s[74:75]
	s_add_i32 m0, s3, 0x2000
	s_nop 0
	global_load_lds_dwordx4 v228, s[74:75]
	s_add_u32 s98, s92, 0x80
	s_addc_u32 s99, s93, 0
	s_mov_b32 m0, s60
	s_nop 0
	global_load_lds_dwordx4 v224, s[98:99]
	s_mov_b32 m0, s61
	s_nop 0
	global_load_lds_dwordx4 v226, s[98:99]
	s_waitcnt vmcnt(8)
	s_waitcnt lgkmcnt(0)
	s_barrier
	s_waitcnt lgkmcnt(0)
	v_mfma_f32_16x16x32_bf16 v[60:63], v[64:67], v[152:155], v[60:63]
	v_mfma_f32_16x16x32_bf16 v[60:63], v[72:75], v[156:159], v[60:63]
	v_mfma_f32_16x16x32_bf16 v[52:55], v[108:111], v[152:155], v[52:55]
	v_mfma_f32_16x16x32_bf16 v[52:55], v[116:119], v[156:159], v[52:55]
	v_mfma_f32_16x16x32_bf16 v[56:59], v[88:91], v[152:155], v[56:59]
	v_mfma_f32_16x16x32_bf16 v[56:59], v[96:99], v[156:159], v[56:59]
	v_mfma_f32_16x16x32_bf16 v[48:51], v[128:131], v[152:155], v[48:51]
	v_mfma_f32_16x16x32_bf16 v[48:51], v[140:143], v[156:159], v[48:51]
	v_mfma_f32_16x16x32_bf16 v[44:47], v[64:67], v[160:163], v[44:47]
	v_mfma_f32_16x16x32_bf16 v[44:47], v[72:75], v[164:167], v[44:47]
	v_mfma_f32_16x16x32_bf16 v[36:39], v[108:111], v[160:163], v[36:39]
	v_mfma_f32_16x16x32_bf16 v[36:39], v[116:119], v[164:167], v[36:39]
	v_mfma_f32_16x16x32_bf16 v[40:43], v[88:91], v[160:163], v[40:43]
	v_mfma_f32_16x16x32_bf16 v[40:43], v[96:99], v[164:167], v[40:43]
	v_mfma_f32_16x16x32_bf16 v[32:35], v[128:131], v[160:163], v[32:35]
	v_mfma_f32_16x16x32_bf16 v[32:35], v[140:143], v[164:167], v[32:35]
	v_mfma_f32_16x16x32_bf16 v[28:31], v[64:67], v[168:171], v[28:31]
	v_mfma_f32_16x16x32_bf16 v[28:31], v[72:75], v[180:183], v[28:31]
	v_mfma_f32_16x16x32_bf16 v[20:23], v[108:111], v[168:171], v[20:23]
	v_mfma_f32_16x16x32_bf16 v[20:23], v[116:119], v[180:183], v[20:23]
	v_mfma_f32_16x16x32_bf16 v[24:27], v[88:91], v[168:171], v[24:27]
	v_mfma_f32_16x16x32_bf16 v[24:27], v[96:99], v[180:183], v[24:27]
	v_mfma_f32_16x16x32_bf16 v[16:19], v[128:131], v[168:171], v[16:19]
	v_mfma_f32_16x16x32_bf16 v[16:19], v[140:143], v[180:183], v[16:19]
	v_mfma_f32_16x16x32_bf16 v[12:15], v[64:67], v[184:187], v[12:15]
	v_mfma_f32_16x16x32_bf16 v[12:15], v[72:75], v[188:191], v[12:15]
	v_mfma_f32_16x16x32_bf16 v[4:7], v[108:111], v[184:187], v[4:7]
	v_mfma_f32_16x16x32_bf16 v[4:7], v[116:119], v[188:191], v[4:7]
	v_mfma_f32_16x16x32_bf16 v[8:11], v[88:91], v[184:187], v[8:11]
	v_mfma_f32_16x16x32_bf16 v[8:11], v[96:99], v[188:191], v[8:11]
	v_mfma_f32_16x16x32_bf16 v[0:3], v[128:131], v[184:187], v[0:3]
	v_mfma_f32_16x16x32_bf16 v[0:3], v[140:143], v[188:191], v[0:3]
	s_barrier
	s_add_i32 s71, s71, 2
	s_add_u32 s88, s88, 0x100
	s_addc_u32 s89, s89, 0
	s_add_u32 s87, s87, 0x100
	s_addc_u32 vcc_hi, vcc_hi, 0
	s_cmp_gt_u32 s71, 29
	s_cbranch_scc0 .LBB0_965
	s_and_b64 vcc, exec, s[22:23]
	s_cbranch_vccz .LBB0_968
	s_barrier

.LBB0_1189:
	s_ashr_i32 s75, s74, 31
	s_lshl_b64 s[72:73], s[74:75], 20
	s_add_u32 s76, s2, s72
	s_addc_u32 s77, s3, s73
	s_and_b64 s[72:73], s[4:5], exec
	s_cselect_b32 s71, s77, s83
	s_cselect_b32 s72, s76, s82
	s_ashr_i32 s23, s22, 31
	s_lshl_b64 s[78:79], s[22:23], 20
	s_add_u32 s78, s14, s78
	s_addc_u32 s79, s15, s79
	s_and_b64 s[86:87], s[4:5], exec
	s_cselect_b32 s23, s79, s85
	s_cselect_b32 s73, s78, s84
	s_add_u32 s82, s82, 0x80080
	s_addc_u32 s83, s83, 0
	s_add_u32 s75, s84, 0x100
	s_addc_u32 s81, s85, 0
	s_mov_b32 s88, -2
	v_add_u32_e32 v177, 0x10000, v192
	s_add_u32 s67, s82, 0xfff80080
	s_addc_u32 s84, s83, -1
	s_add_i32 s89, 0, 0x10000
	s_cmp_eq_u32 s88, 28
	s_cselect_b32 s87, s71, s84
	s_cselect_b32 s86, s72, s67
	s_cselect_b32 s85, s23, s81
	s_cselect_b32 s84, s73, s75
	s_add_i32 s67, 0, 0x14000
	ds_read_b128 v[64:67], v177
	ds_read_b128 v[68:71], v177 offset:1024
	ds_read_b128 v[72:75], v177 offset:2048
	ds_read_b128 v[76:79], v177 offset:3072
	ds_read_b128 v[80:83], v177 offset:16384
	ds_read_b128 v[116:119], v177 offset:17408
	ds_read_b128 v[152:155], v177 offset:18432
	ds_read_b128 v[156:159], v177 offset:19456
	s_add_i32 m0, s28, 0xc000
	ds_read_b128 v[160:163], v193
	ds_read_b128 v[164:167], v193 offset:1024
	ds_read_b128 v[168:171], v193 offset:2048
	ds_read_b128 v[172:175], v193 offset:3072
	ds_read_b128 v[194:197], v193 offset:4096
	ds_read_b128 v[198:201], v193 offset:5120
	ds_read_b128 v[202:205], v193 offset:6144
	ds_read_b128 v[206:209], v193 offset:7168
	global_load_lds_dwordx4 v186, s[82:83]
	s_add_i32 m0, s28, 0xe000
	s_nop 0
	global_load_lds_dwordx4 v188, s[82:83]
	s_waitcnt vmcnt(8)
	s_waitcnt lgkmcnt(0)
	s_barrier
	s_waitcnt lgkmcnt(0)
	v_mfma_f32_16x16x32_bf16 v[148:151], v[64:67], v[160:163], 0
	v_mfma_f32_16x16x32_bf16 v[148:151], v[68:71], v[164:167], v[148:151]
	v_mfma_f32_16x16x32_bf16 v[140:143], v[80:83], v[160:163], 0
	v_mfma_f32_16x16x32_bf16 v[140:143], v[116:119], v[164:167], v[140:143]
	v_mfma_f32_16x16x32_bf16 v[144:147], v[72:75], v[160:163], 0
	v_mfma_f32_16x16x32_bf16 v[144:147], v[76:79], v[164:167], v[144:147]
	v_mfma_f32_16x16x32_bf16 v[136:139], v[152:155], v[160:163], 0
	v_mfma_f32_16x16x32_bf16 v[136:139], v[156:159], v[164:167], v[136:139]
	v_mfma_f32_16x16x32_bf16 v[132:135], v[64:67], v[168:171], 0
	v_mfma_f32_16x16x32_bf16 v[132:135], v[68:71], v[172:175], v[132:135]
	v_mfma_f32_16x16x32_bf16 v[124:127], v[80:83], v[168:171], 0
	v_mfma_f32_16x16x32_bf16 v[124:127], v[116:119], v[172:175], v[124:127]
	v_mfma_f32_16x16x32_bf16 v[128:131], v[72:75], v[168:171], 0
	v_mfma_f32_16x16x32_bf16 v[128:131], v[76:79], v[172:175], v[128:131]
	v_mfma_f32_16x16x32_bf16 v[120:123], v[152:155], v[168:171], 0
	v_mfma_f32_16x16x32_bf16 v[120:123], v[156:159], v[172:175], v[120:123]
	v_mfma_f32_16x16x32_bf16 v[112:115], v[64:67], v[194:197], 0
	v_mfma_f32_16x16x32_bf16 v[112:115], v[68:71], v[198:201], v[112:115]
	v_mfma_f32_16x16x32_bf16 v[104:107], v[80:83], v[194:197], 0
	v_mfma_f32_16x16x32_bf16 v[104:107], v[116:119], v[198:201], v[104:107]
	v_mfma_f32_16x16x32_bf16 v[108:111], v[72:75], v[194:197], 0
	v_mfma_f32_16x16x32_bf16 v[108:111], v[76:79], v[198:201], v[108:111]
	v_mfma_f32_16x16x32_bf16 v[100:103], v[152:155], v[194:197], 0
	v_mfma_f32_16x16x32_bf16 v[100:103], v[156:159], v[198:201], v[100:103]
	v_mfma_f32_16x16x32_bf16 v[96:99], v[64:67], v[202:205], 0
	v_mfma_f32_16x16x32_bf16 v[96:99], v[68:71], v[206:209], v[96:99]
	v_mfma_f32_16x16x32_bf16 v[88:91], v[80:83], v[202:205], 0
	v_mfma_f32_16x16x32_bf16 v[88:91], v[116:119], v[206:209], v[88:91]
	v_mfma_f32_16x16x32_bf16 v[92:95], v[72:75], v[202:205], 0
	v_mfma_f32_16x16x32_bf16 v[92:95], v[76:79], v[206:209], v[92:95]
	v_mfma_f32_16x16x32_bf16 v[84:87], v[152:155], v[202:205], 0
	v_mfma_f32_16x16x32_bf16 v[84:87], v[156:159], v[206:209], v[84:87]
	s_barrier
	s_add_i32 s89, s89, s24
	s_mov_b32 m0, s89
	ds_read_b128 v[160:163], v193 offset:16384
	ds_read_b128 v[164:167], v193 offset:17408
	ds_read_b128 v[168:171], v193 offset:18432
	ds_read_b128 v[172:175], v193 offset:19456
	ds_read_b128 v[194:197], v193 offset:20480
	ds_read_b128 v[198:201], v193 offset:21504
	ds_read_b128 v[202:205], v193 offset:22528
	ds_read_b128 v[206:209], v193 offset:23552
	global_load_lds_dwordx4 v180, s[84:85]
	s_add_i32 m0, s89, 0x2000
	s_add_u32 s90, s84, 0x80000
	s_addc_u32 s91, s85, 0
	s_add_i32 s67, s67, s24
	global_load_lds_dwordx4 v176, s[84:85]
	s_mov_b32 m0, s67
	s_nop 0
	global_load_lds_dwordx4 v180, s[90:91]
	s_add_i32 m0, s67, 0x2000
	s_nop 0
	global_load_lds_dwordx4 v176, s[90:91]
	s_mov_b32 m0, s28
	s_nop 0
	global_load_lds_dwordx4 v182, s[86:87]
	s_mov_b32 m0, s29
	s_nop 0
	global_load_lds_dwordx4 v178, s[86:87]
	s_waitcnt vmcnt(8)
	s_waitcnt lgkmcnt(0)
	s_barrier
	s_waitcnt lgkmcnt(0)
	v_mfma_f32_16x16x32_bf16 v[60:63], v[64:67], v[160:163], 0
	v_mfma_f32_16x16x32_bf16 v[60:63], v[68:71], v[164:167], v[60:63]
	v_mfma_f32_16x16x32_bf16 v[52:55], v[80:83], v[160:163], 0
	v_mfma_f32_16x16x32_bf16 v[52:55], v[116:119], v[164:167], v[52:55]
	v_mfma_f32_16x16x32_bf16 v[56:59], v[72:75], v[160:163], 0
	v_mfma_f32_16x16x32_bf16 v[56:59], v[76:79], v[164:167], v[56:59]
	v_mfma_f32_16x16x32_bf16 v[48:51], v[152:155], v[160:163], 0
	v_mfma_f32_16x16x32_bf16 v[48:51], v[156:159], v[164:167], v[48:51]
	v_mfma_f32_16x16x32_bf16 v[44:47], v[64:67], v[168:171], 0
	v_mfma_f32_16x16x32_bf16 v[44:47], v[68:71], v[172:175], v[44:47]
	v_mfma_f32_16x16x32_bf16 v[36:39], v[80:83], v[168:171], 0
	v_mfma_f32_16x16x32_bf16 v[36:39], v[116:119], v[172:175], v[36:39]
	v_mfma_f32_16x16x32_bf16 v[40:43], v[72:75], v[168:171], 0
	v_mfma_f32_16x16x32_bf16 v[40:43], v[76:79], v[172:175], v[40:43]
	v_mfma_f32_16x16x32_bf16 v[32:35], v[152:155], v[168:171], 0
	v_mfma_f32_16x16x32_bf16 v[32:35], v[156:159], v[172:175], v[32:35]
	v_mfma_f32_16x16x32_bf16 v[28:31], v[64:67], v[194:197], 0
	v_mfma_f32_16x16x32_bf16 v[28:31], v[68:71], v[198:201], v[28:31]
	v_mfma_f32_16x16x32_bf16 v[20:23], v[80:83], v[194:197], 0
	v_mfma_f32_16x16x32_bf16 v[20:23], v[116:119], v[198:201], v[20:23]
	v_mfma_f32_16x16x32_bf16 v[24:27], v[72:75], v[194:197], 0
	v_mfma_f32_16x16x32_bf16 v[24:27], v[76:79], v[198:201], v[24:27]
	v_mfma_f32_16x16x32_bf16 v[16:19], v[152:155], v[194:197], 0
	v_mfma_f32_16x16x32_bf16 v[16:19], v[156:159], v[198:201], v[16:19]
	v_mfma_f32_16x16x32_bf16 v[12:15], v[64:67], v[202:205], 0
	v_mfma_f32_16x16x32_bf16 v[12:15], v[68:71], v[206:209], v[12:15]
	v_mfma_f32_16x16x32_bf16 v[4:7], v[80:83], v[202:205], 0
	v_mfma_f32_16x16x32_bf16 v[4:7], v[116:119], v[206:209], v[4:7]
	v_mfma_f32_16x16x32_bf16 v[8:11], v[72:75], v[202:205], 0
	v_mfma_f32_16x16x32_bf16 v[8:11], v[76:79], v[206:209], v[8:11]
	v_mfma_f32_16x16x32_bf16 v[0:3], v[152:155], v[202:205], 0
	v_mfma_f32_16x16x32_bf16 v[0:3], v[156:159], v[206:209], v[0:3]
	s_barrier
	s_add_i32 s67, 0, 0x18000
	s_add_i32 s89, 0, 0x1c000
	ds_read_b128 v[64:67], v177 offset:32768
	ds_read_b128 v[68:71], v177 offset:33792
	ds_read_b128 v[72:75], v177 offset:34816
	ds_read_b128 v[76:79], v177 offset:35840
	ds_read_b128 v[80:83], v177 offset:49152
	ds_read_b128 v[116:119], v177 offset:50176
	ds_read_b128 v[152:155], v177 offset:51200
	ds_read_b128 v[156:159], v177 offset:52224
	s_add_u32 s86, s86, 0x80000
	s_addc_u32 s87, s87, 0
	s_mov_b32 m0, s34
	ds_read_b128 v[160:163], v193 offset:32768
	ds_read_b128 v[164:167], v193 offset:33792
	ds_read_b128 v[168:171], v193 offset:34816
	ds_read_b128 v[172:175], v193 offset:35840
	ds_read_b128 v[194:197], v193 offset:36864
	ds_read_b128 v[198:201], v193 offset:37888
	ds_read_b128 v[202:205], v193 offset:38912
	ds_read_b128 v[206:209], v193 offset:39936
	global_load_lds_dwordx4 v182, s[86:87]
	s_mov_b32 m0, s35
	s_nop 0
	global_load_lds_dwordx4 v178, s[86:87]
	s_waitcnt vmcnt(8)
	s_waitcnt lgkmcnt(0)
	s_barrier
	s_waitcnt lgkmcnt(0)
	v_mfma_f32_16x16x32_bf16 v[148:151], v[64:67], v[160:163], v[148:151]
	v_mfma_f32_16x16x32_bf16 v[148:151], v[68:71], v[164:167], v[148:151]
	v_mfma_f32_16x16x32_bf16 v[140:143], v[80:83], v[160:163], v[140:143]
	v_mfma_f32_16x16x32_bf16 v[140:143], v[116:119], v[164:167], v[140:143]
	v_mfma_f32_16x16x32_bf16 v[144:147], v[72:75], v[160:163], v[144:147]
	v_mfma_f32_16x16x32_bf16 v[144:147], v[76:79], v[164:167], v[144:147]
	v_mfma_f32_16x16x32_bf16 v[136:139], v[152:155], v[160:163], v[136:139]
	v_mfma_f32_16x16x32_bf16 v[136:139], v[156:159], v[164:167], v[136:139]
	v_mfma_f32_16x16x32_bf16 v[132:135], v[64:67], v[168:171], v[132:135]
	v_mfma_f32_16x16x32_bf16 v[132:135], v[68:71], v[172:175], v[132:135]
	v_mfma_f32_16x16x32_bf16 v[124:127], v[80:83], v[168:171], v[124:127]
	v_mfma_f32_16x16x32_bf16 v[124:127], v[116:119], v[172:175], v[124:127]
	v_mfma_f32_16x16x32_bf16 v[128:131], v[72:75], v[168:171], v[128:131]
	v_mfma_f32_16x16x32_bf16 v[128:131], v[76:79], v[172:175], v[128:131]
	v_mfma_f32_16x16x32_bf16 v[120:123], v[152:155], v[168:171], v[120:123]
	v_mfma_f32_16x16x32_bf16 v[120:123], v[156:159], v[172:175], v[120:123]
	v_mfma_f32_16x16x32_bf16 v[112:115], v[64:67], v[194:197], v[112:115]
	v_mfma_f32_16x16x32_bf16 v[112:115], v[68:71], v[198:201], v[112:115]
	v_mfma_f32_16x16x32_bf16 v[104:107], v[80:83], v[194:197], v[104:107]
	v_mfma_f32_16x16x32_bf16 v[104:107], v[116:119], v[198:201], v[104:107]
	v_mfma_f32_16x16x32_bf16 v[108:111], v[72:75], v[194:197], v[108:111]
	v_mfma_f32_16x16x32_bf16 v[108:111], v[76:79], v[198:201], v[108:111]
	v_mfma_f32_16x16x32_bf16 v[100:103], v[152:155], v[194:197], v[100:103]
	v_mfma_f32_16x16x32_bf16 v[100:103], v[156:159], v[198:201], v[100:103]
	v_mfma_f32_16x16x32_bf16 v[96:99], v[64:67], v[202:205], v[96:99]
	v_mfma_f32_16x16x32_bf16 v[96:99], v[68:71], v[206:209], v[96:99]
	v_mfma_f32_16x16x32_bf16 v[88:91], v[80:83], v[202:205], v[88:91]
	v_mfma_f32_16x16x32_bf16 v[88:91], v[116:119], v[206:209], v[88:91]
	v_mfma_f32_16x16x32_bf16 v[92:95], v[72:75], v[202:205], v[92:95]
	v_mfma_f32_16x16x32_bf16 v[92:95], v[76:79], v[206:209], v[92:95]
	v_mfma_f32_16x16x32_bf16 v[84:87], v[152:155], v[202:205], v[84:87]
	v_mfma_f32_16x16x32_bf16 v[84:87], v[156:159], v[206:209], v[84:87]
	s_barrier
	s_add_i32 s67, s67, s24
	s_add_u32 s98, s84, 0x80
	s_addc_u32 s99, s85, 0
	s_mov_b32 m0, s67
	ds_read_b128 v[160:163], v193 offset:49152
	ds_read_b128 v[164:167], v193 offset:50176
	ds_read_b128 v[168:171], v193 offset:51200
	ds_read_b128 v[172:175], v193 offset:52224
	ds_read_b128 v[194:197], v193 offset:53248
	ds_read_b128 v[198:201], v193 offset:54272
	ds_read_b128 v[202:205], v193 offset:55296
	ds_read_b128 v[206:209], v193 offset:56320
	global_load_lds_dwordx4 v180, s[98:99]
	s_add_i32 m0, s67, 0x2000
	s_add_u32 s84, s84, 0x80080
	s_addc_u32 s85, s85, 0
	s_add_i32 s67, s89, s24
	global_load_lds_dwordx4 v176, s[98:99]
	s_mov_b32 m0, s67
	s_nop 0
	global_load_lds_dwordx4 v180, s[84:85]
	s_add_i32 m0, s67, 0x2000
	s_nop 0
	global_load_lds_dwordx4 v176, s[84:85]
	s_add_u32 s98, s86, 0xfff80080
	s_addc_u32 s99, s87, -1
	s_mov_b32 m0, s53
	s_nop 0
	global_load_lds_dwordx4 v182, s[98:99]
	s_mov_b32 m0, s54
	s_nop 0
	global_load_lds_dwordx4 v178, s[98:99]
	s_waitcnt vmcnt(8)
	s_waitcnt lgkmcnt(0)
	s_barrier
	s_waitcnt lgkmcnt(0)
	v_mfma_f32_16x16x32_bf16 v[60:63], v[64:67], v[160:163], v[60:63]
	v_mfma_f32_16x16x32_bf16 v[60:63], v[68:71], v[164:167], v[60:63]
	v_mfma_f32_16x16x32_bf16 v[52:55], v[80:83], v[160:163], v[52:55]
	v_mfma_f32_16x16x32_bf16 v[52:55], v[116:119], v[164:167], v[52:55]
	v_mfma_f32_16x16x32_bf16 v[56:59], v[72:75], v[160:163], v[56:59]
	v_mfma_f32_16x16x32_bf16 v[56:59], v[76:79], v[164:167], v[56:59]
	v_mfma_f32_16x16x32_bf16 v[48:51], v[152:155], v[160:163], v[48:51]
	v_mfma_f32_16x16x32_bf16 v[48:51], v[156:159], v[164:167], v[48:51]
	v_mfma_f32_16x16x32_bf16 v[44:47], v[64:67], v[168:171], v[44:47]
	v_mfma_f32_16x16x32_bf16 v[44:47], v[68:71], v[172:175], v[44:47]
	v_mfma_f32_16x16x32_bf16 v[36:39], v[80:83], v[168:171], v[36:39]
	v_mfma_f32_16x16x32_bf16 v[36:39], v[116:119], v[172:175], v[36:39]
	v_mfma_f32_16x16x32_bf16 v[40:43], v[72:75], v[168:171], v[40:43]
	v_mfma_f32_16x16x32_bf16 v[40:43], v[76:79], v[172:175], v[40:43]
	v_mfma_f32_16x16x32_bf16 v[32:35], v[152:155], v[168:171], v[32:35]
	v_mfma_f32_16x16x32_bf16 v[32:35], v[156:159], v[172:175], v[32:35]
	v_mfma_f32_16x16x32_bf16 v[28:31], v[64:67], v[194:197], v[28:31]
	v_mfma_f32_16x16x32_bf16 v[28:31], v[68:71], v[198:201], v[28:31]
	v_mfma_f32_16x16x32_bf16 v[20:23], v[80:83], v[194:197], v[20:23]
	v_mfma_f32_16x16x32_bf16 v[20:23], v[116:119], v[198:201], v[20:23]
	v_mfma_f32_16x16x32_bf16 v[24:27], v[72:75], v[194:197], v[24:27]
	v_mfma_f32_16x16x32_bf16 v[24:27], v[76:79], v[198:201], v[24:27]
	v_mfma_f32_16x16x32_bf16 v[16:19], v[152:155], v[194:197], v[16:19]
	v_mfma_f32_16x16x32_bf16 v[16:19], v[156:159], v[198:201], v[16:19]
	v_mfma_f32_16x16x32_bf16 v[12:15], v[64:67], v[202:205], v[12:15]
	v_mfma_f32_16x16x32_bf16 v[12:15], v[68:71], v[206:209], v[12:15]
	v_mfma_f32_16x16x32_bf16 v[4:7], v[80:83], v[202:205], v[4:7]
	v_mfma_f32_16x16x32_bf16 v[4:7], v[116:119], v[206:209], v[4:7]
	v_mfma_f32_16x16x32_bf16 v[8:11], v[72:75], v[202:205], v[8:11]
	v_mfma_f32_16x16x32_bf16 v[8:11], v[76:79], v[206:209], v[8:11]
	v_mfma_f32_16x16x32_bf16 v[0:3], v[152:155], v[202:205], v[0:3]
	v_mfma_f32_16x16x32_bf16 v[0:3], v[156:159], v[206:209], v[0:3]
	s_barrier
	s_add_i32 s88, s88, 2
	s_add_u32 s82, s82, 0x100
	s_addc_u32 s83, s83, 0
	s_add_u32 s75, s75, 0x100
	s_addc_u32 s81, s81, 0
.LBB0_1190:
	s_add_u32 s67, s82, 0xfff80080
	s_addc_u32 s84, s83, -1
	s_add_i32 s89, 0, 0x10000
	s_cmp_eq_u32 s88, 28
	s_cselect_b32 s87, s71, s84
	s_cselect_b32 s86, s72, s67
	s_cselect_b32 s85, s23, s81
	s_cselect_b32 s84, s73, s75
	s_add_i32 s67, 0, 0x14000
	ds_read_b128 v[64:67], v177
	ds_read_b128 v[68:71], v177 offset:1024
	ds_read_b128 v[72:75], v177 offset:2048
	ds_read_b128 v[76:79], v177 offset:3072
	ds_read_b128 v[80:83], v177 offset:16384
	ds_read_b128 v[116:119], v177 offset:17408
	ds_read_b128 v[152:155], v177 offset:18432
	ds_read_b128 v[156:159], v177 offset:19456
	s_add_i32 m0, s28, 0xc000
	ds_read_b128 v[160:163], v193
	ds_read_b128 v[164:167], v193 offset:1024
	ds_read_b128 v[168:171], v193 offset:2048
	ds_read_b128 v[172:175], v193 offset:3072
	ds_read_b128 v[194:197], v193 offset:4096
	ds_read_b128 v[198:201], v193 offset:5120
	ds_read_b128 v[202:205], v193 offset:6144
	ds_read_b128 v[206:209], v193 offset:7168
	global_load_lds_dwordx4 v186, s[82:83]
	s_add_i32 m0, s28, 0xe000
	s_nop 0
	global_load_lds_dwordx4 v188, s[82:83]
	s_waitcnt vmcnt(8)
	s_waitcnt lgkmcnt(0)
	s_barrier
	s_waitcnt lgkmcnt(0)
	v_mfma_f32_16x16x32_bf16 v[148:151], v[64:67], v[160:163], v[148:151]
	v_mfma_f32_16x16x32_bf16 v[148:151], v[68:71], v[164:167], v[148:151]
	v_mfma_f32_16x16x32_bf16 v[140:143], v[80:83], v[160:163], v[140:143]
	v_mfma_f32_16x16x32_bf16 v[140:143], v[116:119], v[164:167], v[140:143]
	v_mfma_f32_16x16x32_bf16 v[144:147], v[72:75], v[160:163], v[144:147]
	v_mfma_f32_16x16x32_bf16 v[144:147], v[76:79], v[164:167], v[144:147]
	v_mfma_f32_16x16x32_bf16 v[136:139], v[152:155], v[160:163], v[136:139]
	v_mfma_f32_16x16x32_bf16 v[136:139], v[156:159], v[164:167], v[136:139]
	v_mfma_f32_16x16x32_bf16 v[132:135], v[64:67], v[168:171], v[132:135]
	v_mfma_f32_16x16x32_bf16 v[132:135], v[68:71], v[172:175], v[132:135]
	v_mfma_f32_16x16x32_bf16 v[124:127], v[80:83], v[168:171], v[124:127]
	v_mfma_f32_16x16x32_bf16 v[124:127], v[116:119], v[172:175], v[124:127]
	v_mfma_f32_16x16x32_bf16 v[128:131], v[72:75], v[168:171], v[128:131]
	v_mfma_f32_16x16x32_bf16 v[128:131], v[76:79], v[172:175], v[128:131]
	v_mfma_f32_16x16x32_bf16 v[120:123], v[152:155], v[168:171], v[120:123]
	v_mfma_f32_16x16x32_bf16 v[120:123], v[156:159], v[172:175], v[120:123]
	v_mfma_f32_16x16x32_bf16 v[112:115], v[64:67], v[194:197], v[112:115]
	v_mfma_f32_16x16x32_bf16 v[112:115], v[68:71], v[198:201], v[112:115]
	v_mfma_f32_16x16x32_bf16 v[104:107], v[80:83], v[194:197], v[104:107]
	v_mfma_f32_16x16x32_bf16 v[104:107], v[116:119], v[198:201], v[104:107]
	v_mfma_f32_16x16x32_bf16 v[108:111], v[72:75], v[194:197], v[108:111]
	v_mfma_f32_16x16x32_bf16 v[108:111], v[76:79], v[198:201], v[108:111]
	v_mfma_f32_16x16x32_bf16 v[100:103], v[152:155], v[194:197], v[100:103]
	v_mfma_f32_16x16x32_bf16 v[100:103], v[156:159], v[198:201], v[100:103]
	v_mfma_f32_16x16x32_bf16 v[96:99], v[64:67], v[202:205], v[96:99]
	v_mfma_f32_16x16x32_bf16 v[96:99], v[68:71], v[206:209], v[96:99]
	v_mfma_f32_16x16x32_bf16 v[88:91], v[80:83], v[202:205], v[88:91]
	v_mfma_f32_16x16x32_bf16 v[88:91], v[116:119], v[206:209], v[88:91]
	v_mfma_f32_16x16x32_bf16 v[92:95], v[72:75], v[202:205], v[92:95]
	v_mfma_f32_16x16x32_bf16 v[92:95], v[76:79], v[206:209], v[92:95]
	v_mfma_f32_16x16x32_bf16 v[84:87], v[152:155], v[202:205], v[84:87]
	v_mfma_f32_16x16x32_bf16 v[84:87], v[156:159], v[206:209], v[84:87]
	s_barrier
	s_add_i32 s89, s89, s24
	s_mov_b32 m0, s89
	ds_read_b128 v[160:163], v193 offset:16384
	ds_read_b128 v[164:167], v193 offset:17408
	ds_read_b128 v[168:171], v193 offset:18432
	ds_read_b128 v[172:175], v193 offset:19456
	ds_read_b128 v[194:197], v193 offset:20480
	ds_read_b128 v[198:201], v193 offset:21504
	ds_read_b128 v[202:205], v193 offset:22528
	ds_read_b128 v[206:209], v193 offset:23552
	global_load_lds_dwordx4 v180, s[84:85]
	s_add_i32 m0, s89, 0x2000
	s_add_u32 s90, s84, 0x80000
	s_addc_u32 s91, s85, 0
	s_add_i32 s67, s67, s24
	global_load_lds_dwordx4 v176, s[84:85]
	s_mov_b32 m0, s67
	s_nop 0
	global_load_lds_dwordx4 v180, s[90:91]
	s_add_i32 m0, s67, 0x2000
	s_nop 0
	global_load_lds_dwordx4 v176, s[90:91]
	s_mov_b32 m0, s28
	s_nop 0
	global_load_lds_dwordx4 v182, s[86:87]
	s_mov_b32 m0, s29
	s_nop 0
	global_load_lds_dwordx4 v178, s[86:87]
	s_waitcnt vmcnt(8)
	s_waitcnt lgkmcnt(0)
	s_barrier
	s_waitcnt lgkmcnt(0)
	v_mfma_f32_16x16x32_bf16 v[60:63], v[64:67], v[160:163], v[60:63]
	v_mfma_f32_16x16x32_bf16 v[60:63], v[68:71], v[164:167], v[60:63]
	v_mfma_f32_16x16x32_bf16 v[52:55], v[80:83], v[160:163], v[52:55]
	v_mfma_f32_16x16x32_bf16 v[52:55], v[116:119], v[164:167], v[52:55]
	v_mfma_f32_16x16x32_bf16 v[56:59], v[72:75], v[160:163], v[56:59]
	v_mfma_f32_16x16x32_bf16 v[56:59], v[76:79], v[164:167], v[56:59]
	v_mfma_f32_16x16x32_bf16 v[48:51], v[152:155], v[160:163], v[48:51]
	v_mfma_f32_16x16x32_bf16 v[48:51], v[156:159], v[164:167], v[48:51]
	v_mfma_f32_16x16x32_bf16 v[44:47], v[64:67], v[168:171], v[44:47]
	v_mfma_f32_16x16x32_bf16 v[44:47], v[68:71], v[172:175], v[44:47]
	v_mfma_f32_16x16x32_bf16 v[36:39], v[80:83], v[168:171], v[36:39]
	v_mfma_f32_16x16x32_bf16 v[36:39], v[116:119], v[172:175], v[36:39]
	v_mfma_f32_16x16x32_bf16 v[40:43], v[72:75], v[168:171], v[40:43]
	v_mfma_f32_16x16x32_bf16 v[40:43], v[76:79], v[172:175], v[40:43]
	v_mfma_f32_16x16x32_bf16 v[32:35], v[152:155], v[168:171], v[32:35]
	v_mfma_f32_16x16x32_bf16 v[32:35], v[156:159], v[172:175], v[32:35]
	v_mfma_f32_16x16x32_bf16 v[28:31], v[64:67], v[194:197], v[28:31]
	v_mfma_f32_16x16x32_bf16 v[28:31], v[68:71], v[198:201], v[28:31]
	v_mfma_f32_16x16x32_bf16 v[20:23], v[80:83], v[194:197], v[20:23]
	v_mfma_f32_16x16x32_bf16 v[20:23], v[116:119], v[198:201], v[20:23]
	v_mfma_f32_16x16x32_bf16 v[24:27], v[72:75], v[194:197], v[24:27]
	v_mfma_f32_16x16x32_bf16 v[24:27], v[76:79], v[198:201], v[24:27]
	v_mfma_f32_16x16x32_bf16 v[16:19], v[152:155], v[194:197], v[16:19]
	v_mfma_f32_16x16x32_bf16 v[16:19], v[156:159], v[198:201], v[16:19]
	v_mfma_f32_16x16x32_bf16 v[12:15], v[64:67], v[202:205], v[12:15]
	v_mfma_f32_16x16x32_bf16 v[12:15], v[68:71], v[206:209], v[12:15]
	v_mfma_f32_16x16x32_bf16 v[4:7], v[80:83], v[202:205], v[4:7]
	v_mfma_f32_16x16x32_bf16 v[4:7], v[116:119], v[206:209], v[4:7]
	v_mfma_f32_16x16x32_bf16 v[8:11], v[72:75], v[202:205], v[8:11]
	v_mfma_f32_16x16x32_bf16 v[8:11], v[76:79], v[206:209], v[8:11]
	v_mfma_f32_16x16x32_bf16 v[0:3], v[152:155], v[202:205], v[0:3]
	v_mfma_f32_16x16x32_bf16 v[0:3], v[156:159], v[206:209], v[0:3]
	s_barrier
	s_add_i32 s67, 0, 0x18000
	s_add_i32 s89, 0, 0x1c000
	ds_read_b128 v[64:67], v177 offset:32768
	ds_read_b128 v[68:71], v177 offset:33792
	ds_read_b128 v[72:75], v177 offset:34816
	ds_read_b128 v[76:79], v177 offset:35840
	ds_read_b128 v[80:83], v177 offset:49152
	ds_read_b128 v[116:119], v177 offset:50176
	ds_read_b128 v[152:155], v177 offset:51200
	ds_read_b128 v[156:159], v177 offset:52224
	s_add_u32 s86, s86, 0x80000
	s_addc_u32 s87, s87, 0
	s_mov_b32 m0, s34
	ds_read_b128 v[160:163], v193 offset:32768
	ds_read_b128 v[164:167], v193 offset:33792
	ds_read_b128 v[168:171], v193 offset:34816
	ds_read_b128 v[172:175], v193 offset:35840
	ds_read_b128 v[194:197], v193 offset:36864
	ds_read_b128 v[198:201], v193 offset:37888
	ds_read_b128 v[202:205], v193 offset:38912
	ds_read_b128 v[206:209], v193 offset:39936
	global_load_lds_dwordx4 v182, s[86:87]
	s_mov_b32 m0, s35
	s_nop 0
	global_load_lds_dwordx4 v178, s[86:87]
	s_waitcnt vmcnt(8)
	s_waitcnt lgkmcnt(0)
	s_barrier
	s_waitcnt lgkmcnt(0)
	v_mfma_f32_16x16x32_bf16 v[148:151], v[64:67], v[160:163], v[148:151]
	v_mfma_f32_16x16x32_bf16 v[148:151], v[68:71], v[164:167], v[148:151]
	v_mfma_f32_16x16x32_bf16 v[140:143], v[80:83], v[160:163], v[140:143]
	v_mfma_f32_16x16x32_bf16 v[140:143], v[116:119], v[164:167], v[140:143]
	v_mfma_f32_16x16x32_bf16 v[144:147], v[72:75], v[160:163], v[144:147]
	v_mfma_f32_16x16x32_bf16 v[144:147], v[76:79], v[164:167], v[144:147]
	v_mfma_f32_16x16x32_bf16 v[136:139], v[152:155], v[160:163], v[136:139]
	v_mfma_f32_16x16x32_bf16 v[136:139], v[156:159], v[164:167], v[136:139]
	v_mfma_f32_16x16x32_bf16 v[132:135], v[64:67], v[168:171], v[132:135]
	v_mfma_f32_16x16x32_bf16 v[132:135], v[68:71], v[172:175], v[132:135]
	v_mfma_f32_16x16x32_bf16 v[124:127], v[80:83], v[168:171], v[124:127]
	v_mfma_f32_16x16x32_bf16 v[124:127], v[116:119], v[172:175], v[124:127]
	v_mfma_f32_16x16x32_bf16 v[128:131], v[72:75], v[168:171], v[128:131]
	v_mfma_f32_16x16x32_bf16 v[128:131], v[76:79], v[172:175], v[128:131]
	v_mfma_f32_16x16x32_bf16 v[120:123], v[152:155], v[168:171], v[120:123]
	v_mfma_f32_16x16x32_bf16 v[120:123], v[156:159], v[172:175], v[120:123]
	v_mfma_f32_16x16x32_bf16 v[112:115], v[64:67], v[194:197], v[112:115]
	v_mfma_f32_16x16x32_bf16 v[112:115], v[68:71], v[198:201], v[112:115]
	v_mfma_f32_16x16x32_bf16 v[104:107], v[80:83], v[194:197], v[104:107]
	v_mfma_f32_16x16x32_bf16 v[104:107], v[116:119], v[198:201], v[104:107]
	v_mfma_f32_16x16x32_bf16 v[108:111], v[72:75], v[194:197], v[108:111]
	v_mfma_f32_16x16x32_bf16 v[108:111], v[76:79], v[198:201], v[108:111]
	v_mfma_f32_16x16x32_bf16 v[100:103], v[152:155], v[194:197], v[100:103]
	v_mfma_f32_16x16x32_bf16 v[100:103], v[156:159], v[198:201], v[100:103]
	v_mfma_f32_16x16x32_bf16 v[96:99], v[64:67], v[202:205], v[96:99]
	v_mfma_f32_16x16x32_bf16 v[96:99], v[68:71], v[206:209], v[96:99]
	v_mfma_f32_16x16x32_bf16 v[88:91], v[80:83], v[202:205], v[88:91]
	v_mfma_f32_16x16x32_bf16 v[88:91], v[116:119], v[206:209], v[88:91]
	v_mfma_f32_16x16x32_bf16 v[92:95], v[72:75], v[202:205], v[92:95]
	v_mfma_f32_16x16x32_bf16 v[92:95], v[76:79], v[206:209], v[92:95]
	v_mfma_f32_16x16x32_bf16 v[84:87], v[152:155], v[202:205], v[84:87]
	v_mfma_f32_16x16x32_bf16 v[84:87], v[156:159], v[206:209], v[84:87]
	s_barrier
	s_add_i32 s67, s67, s24
	s_add_u32 s98, s84, 0x80
	s_addc_u32 s99, s85, 0
	s_mov_b32 m0, s67
	ds_read_b128 v[160:163], v193 offset:49152
	ds_read_b128 v[164:167], v193 offset:50176
	ds_read_b128 v[168:171], v193 offset:51200
	ds_read_b128 v[172:175], v193 offset:52224
	ds_read_b128 v[194:197], v193 offset:53248
	ds_read_b128 v[198:201], v193 offset:54272
	ds_read_b128 v[202:205], v193 offset:55296
	ds_read_b128 v[206:209], v193 offset:56320
	global_load_lds_dwordx4 v180, s[98:99]
	s_add_i32 m0, s67, 0x2000
	s_add_u32 s84, s84, 0x80080
	s_addc_u32 s85, s85, 0
	s_add_i32 s67, s89, s24
	global_load_lds_dwordx4 v176, s[98:99]
	s_mov_b32 m0, s67
	s_nop 0
	global_load_lds_dwordx4 v180, s[84:85]
	s_add_i32 m0, s67, 0x2000
	s_nop 0
	global_load_lds_dwordx4 v176, s[84:85]
	s_add_u32 s98, s86, 0xfff80080
	s_addc_u32 s99, s87, -1
	s_mov_b32 m0, s53
	s_nop 0
	global_load_lds_dwordx4 v182, s[98:99]
	s_mov_b32 m0, s54
	s_nop 0
	global_load_lds_dwordx4 v178, s[98:99]
	s_waitcnt vmcnt(8)
	s_waitcnt lgkmcnt(0)
	s_barrier
	s_waitcnt lgkmcnt(0)
	v_mfma_f32_16x16x32_bf16 v[60:63], v[64:67], v[160:163], v[60:63]
	v_mfma_f32_16x16x32_bf16 v[60:63], v[68:71], v[164:167], v[60:63]
	v_mfma_f32_16x16x32_bf16 v[52:55], v[80:83], v[160:163], v[52:55]
	v_mfma_f32_16x16x32_bf16 v[52:55], v[116:119], v[164:167], v[52:55]
	v_mfma_f32_16x16x32_bf16 v[56:59], v[72:75], v[160:163], v[56:59]
	v_mfma_f32_16x16x32_bf16 v[56:59], v[76:79], v[164:167], v[56:59]
	v_mfma_f32_16x16x32_bf16 v[48:51], v[152:155], v[160:163], v[48:51]
	v_mfma_f32_16x16x32_bf16 v[48:51], v[156:159], v[164:167], v[48:51]
	v_mfma_f32_16x16x32_bf16 v[44:47], v[64:67], v[168:171], v[44:47]
	v_mfma_f32_16x16x32_bf16 v[44:47], v[68:71], v[172:175], v[44:47]
	v_mfma_f32_16x16x32_bf16 v[36:39], v[80:83], v[168:171], v[36:39]
	v_mfma_f32_16x16x32_bf16 v[36:39], v[116:119], v[172:175], v[36:39]
	v_mfma_f32_16x16x32_bf16 v[40:43], v[72:75], v[168:171], v[40:43]
	v_mfma_f32_16x16x32_bf16 v[40:43], v[76:79], v[172:175], v[40:43]
	v_mfma_f32_16x16x32_bf16 v[32:35], v[152:155], v[168:171], v[32:35]
	v_mfma_f32_16x16x32_bf16 v[32:35], v[156:159], v[172:175], v[32:35]
	v_mfma_f32_16x16x32_bf16 v[28:31], v[64:67], v[194:197], v[28:31]
	v_mfma_f32_16x16x32_bf16 v[28:31], v[68:71], v[198:201], v[28:31]
	v_mfma_f32_16x16x32_bf16 v[20:23], v[80:83], v[194:197], v[20:23]
	v_mfma_f32_16x16x32_bf16 v[20:23], v[116:119], v[198:201], v[20:23]
	v_mfma_f32_16x16x32_bf16 v[24:27], v[72:75], v[194:197], v[24:27]
	v_mfma_f32_16x16x32_bf16 v[24:27], v[76:79], v[198:201], v[24:27]
	v_mfma_f32_16x16x32_bf16 v[16:19], v[152:155], v[194:197], v[16:19]
	v_mfma_f32_16x16x32_bf16 v[16:19], v[156:159], v[198:201], v[16:19]
	v_mfma_f32_16x16x32_bf16 v[12:15], v[64:67], v[202:205], v[12:15]
	v_mfma_f32_16x16x32_bf16 v[12:15], v[68:71], v[206:209], v[12:15]
	v_mfma_f32_16x16x32_bf16 v[4:7], v[80:83], v[202:205], v[4:7]
	v_mfma_f32_16x16x32_bf16 v[4:7], v[116:119], v[206:209], v[4:7]
	v_mfma_f32_16x16x32_bf16 v[8:11], v[72:75], v[202:205], v[8:11]
	v_mfma_f32_16x16x32_bf16 v[8:11], v[76:79], v[206:209], v[8:11]
	v_mfma_f32_16x16x32_bf16 v[0:3], v[152:155], v[202:205], v[0:3]
	v_mfma_f32_16x16x32_bf16 v[0:3], v[156:159], v[206:209], v[0:3]
	s_barrier
	s_add_i32 s88, s88, 2
	s_add_u32 s82, s82, 0x100
	s_addc_u32 s83, s83, 0
	s_add_u32 s75, s75, 0x100
	s_addc_u32 s81, s81, 0
	s_cmp_gt_u32 s88, 29
	s_cbranch_scc0 .LBB0_1190
	s_and_b64 vcc, exec, s[18:19]
	s_cbranch_vccz .LBB0_1193
	s_barrier

.LBB0_1289:
	s_lshl_b32 s80, s96, 8
	s_ashr_i32 s81, s80, 31
	s_lshl_b64 s[86:87], s[80:81], 2
	s_add_u32 s84, s84, s86
	s_addc_u32 s85, s85, s87
	s_add_i32 m0, s94, s41
	s_add_u32 s81, s82, 0x100
	global_load_lds_dwordx4 v239, s[84:85]
	s_addc_u32 s96, s83, 0
	s_cmp_eq_u32 s54, 5
	s_cselect_b32 vcc_lo, 66, -2
	s_bfe_u32 s86, s1, 0x20003
	s_cmp_eq_u32 s86, 3
	s_cselect_b32 s86, -8, 0
	s_cmp_eq_u32 s54, 5
	s_cselect_b32 s86, s86, 0
	s_add_i32 vcc_lo, vcc_lo, s86
	v_add_u32_e32 v192, 0x10000, v238
	s_add_u32 s82, s78, 0x100
	s_addc_u32 s83, s79, 0
	s_add_i32 s94, 0, 0x10000
	s_cmpk_eq_i32 vcc_lo, 0x54
	s_cselect_b32 s87, s75, s83
	s_cselect_b32 s86, s74, s82
	s_cselect_b32 s85, s77, s96
	s_cselect_b32 s84, s76, s81
	s_add_i32 vcc_hi, 0, 0x14000
	ds_read_b128 v[64:67], v192
	ds_read_b128 v[72:75], v192 offset:1024
	ds_read_b128 v[88:91], v192 offset:2048
	ds_read_b128 v[96:99], v192 offset:3072
	ds_read_b128 v[108:111], v192 offset:16384
	ds_read_b128 v[116:119], v192 offset:17408
	ds_read_b128 v[128:131], v192 offset:18432
	ds_read_b128 v[140:143], v192 offset:19456
	s_add_i32 m0, s29, 0xc000
	ds_read_b128 v[152:155], v240
	ds_read_b128 v[156:159], v240 offset:1024
	ds_read_b128 v[160:163], v240 offset:2048
	ds_read_b128 v[164:167], v240 offset:3072
	ds_read_b128 v[168:171], v240 offset:4096
	ds_read_b128 v[180:183], v240 offset:5120
	ds_read_b128 v[184:187], v240 offset:6144
	ds_read_b128 v[188:191], v240 offset:7168
	global_load_lds_dwordx4 v230, s[78:79]
	s_add_i32 m0, s29, 0xe000
	s_nop 0
	global_load_lds_dwordx4 v232, s[78:79]
	s_cmp_lg_u32 s54, 1
	s_cbranch_scc1 .Lds6_0
	s_waitcnt vmcnt(8)

.Lds6_1:
	s_waitcnt lgkmcnt(0)
	s_barrier
	s_waitcnt lgkmcnt(0)
	v_mfma_f32_16x16x32_bf16 v[60:63], v[64:67], v[152:155], 0
	v_mfma_f32_16x16x32_bf16 v[60:63], v[72:75], v[156:159], v[60:63]
	v_mfma_f32_16x16x32_bf16 v[52:55], v[108:111], v[152:155], 0
	v_mfma_f32_16x16x32_bf16 v[52:55], v[116:119], v[156:159], v[52:55]
	v_mfma_f32_16x16x32_bf16 v[56:59], v[88:91], v[152:155], 0
	v_mfma_f32_16x16x32_bf16 v[56:59], v[96:99], v[156:159], v[56:59]
	v_mfma_f32_16x16x32_bf16 v[48:51], v[128:131], v[152:155], 0
	v_mfma_f32_16x16x32_bf16 v[48:51], v[140:143], v[156:159], v[48:51]
	v_mfma_f32_16x16x32_bf16 v[44:47], v[64:67], v[160:163], 0
	v_mfma_f32_16x16x32_bf16 v[44:47], v[72:75], v[164:167], v[44:47]
	v_mfma_f32_16x16x32_bf16 v[36:39], v[108:111], v[160:163], 0
	v_mfma_f32_16x16x32_bf16 v[36:39], v[116:119], v[164:167], v[36:39]
	v_mfma_f32_16x16x32_bf16 v[40:43], v[88:91], v[160:163], 0
	v_mfma_f32_16x16x32_bf16 v[40:43], v[96:99], v[164:167], v[40:43]
	v_mfma_f32_16x16x32_bf16 v[32:35], v[128:131], v[160:163], 0
	v_mfma_f32_16x16x32_bf16 v[32:35], v[140:143], v[164:167], v[32:35]
	v_mfma_f32_16x16x32_bf16 v[28:31], v[64:67], v[168:171], 0
	v_mfma_f32_16x16x32_bf16 v[28:31], v[72:75], v[180:183], v[28:31]
	v_mfma_f32_16x16x32_bf16 v[20:23], v[108:111], v[168:171], 0
	v_mfma_f32_16x16x32_bf16 v[20:23], v[116:119], v[180:183], v[20:23]
	v_mfma_f32_16x16x32_bf16 v[24:27], v[88:91], v[168:171], 0
	v_mfma_f32_16x16x32_bf16 v[24:27], v[96:99], v[180:183], v[24:27]
	v_mfma_f32_16x16x32_bf16 v[16:19], v[128:131], v[168:171], 0
	v_mfma_f32_16x16x32_bf16 v[16:19], v[140:143], v[180:183], v[16:19]
	v_mfma_f32_16x16x32_bf16 v[12:15], v[64:67], v[184:187], 0
	v_mfma_f32_16x16x32_bf16 v[12:15], v[72:75], v[188:191], v[12:15]
	v_mfma_f32_16x16x32_bf16 v[4:7], v[108:111], v[184:187], 0
	v_mfma_f32_16x16x32_bf16 v[4:7], v[116:119], v[188:191], v[4:7]
	v_mfma_f32_16x16x32_bf16 v[8:11], v[88:91], v[184:187], 0
	v_mfma_f32_16x16x32_bf16 v[8:11], v[96:99], v[188:191], v[8:11]
	v_mfma_f32_16x16x32_bf16 v[0:3], v[128:131], v[184:187], 0
	v_mfma_f32_16x16x32_bf16 v[0:3], v[140:143], v[188:191], v[0:3]
	s_barrier
	s_add_i32 s94, 0, 0x18000
	s_add_i32 vcc_hi, 0, 0x1c000
	ds_read_b128 v[64:67], v192 offset:32768
	ds_read_b128 v[72:75], v192 offset:33792
	ds_read_b128 v[88:91], v192 offset:34816
	ds_read_b128 v[96:99], v192 offset:35840
	ds_read_b128 v[108:111], v192 offset:49152
	ds_read_b128 v[116:119], v192 offset:50176
	ds_read_b128 v[128:131], v192 offset:51200
	ds_read_b128 v[140:143], v192 offset:52224
	s_add_u32 s78, s86, 0x160000
	s_addc_u32 s79, s87, 0
	s_mov_b32 m0, s35
	ds_read_b128 v[152:155], v240 offset:32768
	ds_read_b128 v[156:159], v240 offset:33792
	ds_read_b128 v[160:163], v240 offset:34816
	ds_read_b128 v[164:167], v240 offset:35840
	ds_read_b128 v[168:171], v240 offset:36864
	ds_read_b128 v[180:183], v240 offset:37888
	ds_read_b128 v[184:187], v240 offset:38912
	ds_read_b128 v[188:191], v240 offset:39936
	global_load_lds_dwordx4 v224, s[78:79]
	s_mov_b32 m0, s38
	s_nop 0
	global_load_lds_dwordx4 v226, s[78:79]
	s_waitcnt vmcnt(8)
	s_waitcnt lgkmcnt(0)
	s_barrier
	s_waitcnt lgkmcnt(0)
	v_mfma_f32_16x16x32_bf16 v[176:179], v[64:67], v[152:155], v[176:179]
	v_mfma_f32_16x16x32_bf16 v[176:179], v[72:75], v[156:159], v[176:179]
	v_mfma_f32_16x16x32_bf16 v[148:151], v[108:111], v[152:155], v[148:151]
	v_mfma_f32_16x16x32_bf16 v[148:151], v[116:119], v[156:159], v[148:151]
	v_mfma_f32_16x16x32_bf16 v[172:175], v[88:91], v[152:155], v[172:175]
	v_mfma_f32_16x16x32_bf16 v[172:175], v[96:99], v[156:159], v[172:175]
	v_mfma_f32_16x16x32_bf16 v[144:147], v[128:131], v[152:155], v[144:147]
	v_mfma_f32_16x16x32_bf16 v[144:147], v[140:143], v[156:159], v[144:147]
	v_mfma_f32_16x16x32_bf16 v[136:139], v[64:67], v[160:163], v[136:139]
	v_mfma_f32_16x16x32_bf16 v[136:139], v[72:75], v[164:167], v[136:139]
	v_mfma_f32_16x16x32_bf16 v[124:127], v[108:111], v[160:163], v[124:127]
	v_mfma_f32_16x16x32_bf16 v[124:127], v[116:119], v[164:167], v[124:127]
	v_mfma_f32_16x16x32_bf16 v[132:135], v[88:91], v[160:163], v[132:135]
	v_mfma_f32_16x16x32_bf16 v[132:135], v[96:99], v[164:167], v[132:135]
	v_mfma_f32_16x16x32_bf16 v[120:123], v[128:131], v[160:163], v[120:123]
	v_mfma_f32_16x16x32_bf16 v[120:123], v[140:143], v[164:167], v[120:123]
	v_mfma_f32_16x16x32_bf16 v[112:115], v[64:67], v[168:171], v[112:115]
	v_mfma_f32_16x16x32_bf16 v[112:115], v[72:75], v[180:183], v[112:115]
	v_mfma_f32_16x16x32_bf16 v[100:103], v[108:111], v[168:171], v[100:103]
	v_mfma_f32_16x16x32_bf16 v[100:103], v[116:119], v[180:183], v[100:103]
	v_mfma_f32_16x16x32_bf16 v[104:107], v[88:91], v[168:171], v[104:107]
	v_mfma_f32_16x16x32_bf16 v[104:107], v[96:99], v[180:183], v[104:107]
	v_mfma_f32_16x16x32_bf16 v[92:95], v[128:131], v[168:171], v[92:95]
	v_mfma_f32_16x16x32_bf16 v[92:95], v[140:143], v[180:183], v[92:95]
	v_mfma_f32_16x16x32_bf16 v[84:87], v[64:67], v[184:187], v[84:87]
	v_mfma_f32_16x16x32_bf16 v[84:87], v[72:75], v[188:191], v[84:87]
	v_mfma_f32_16x16x32_bf16 v[76:79], v[108:111], v[184:187], v[76:79]
	v_mfma_f32_16x16x32_bf16 v[76:79], v[116:119], v[188:191], v[76:79]
	v_mfma_f32_16x16x32_bf16 v[80:83], v[88:91], v[184:187], v[80:83]
	v_mfma_f32_16x16x32_bf16 v[80:83], v[96:99], v[188:191], v[80:83]
	v_mfma_f32_16x16x32_bf16 v[68:71], v[128:131], v[184:187], v[68:71]
	v_mfma_f32_16x16x32_bf16 v[68:71], v[140:143], v[188:191], v[68:71]
	s_barrier
	s_add_i32 s78, s94, s2
	s_add_u32 s98, s84, 0x80
	s_addc_u32 s99, s85, 0
	s_mov_b32 m0, s78
	ds_read_b128 v[152:155], v240 offset:49152
	ds_read_b128 v[156:159], v240 offset:50176
	ds_read_b128 v[160:163], v240 offset:51200
	ds_read_b128 v[164:167], v240 offset:52224
	ds_read_b128 v[168:171], v240 offset:53248
	ds_read_b128 v[180:183], v240 offset:54272
	ds_read_b128 v[184:187], v240 offset:55296
	ds_read_b128 v[188:191], v240 offset:56320
	global_load_lds_dwordx4 v216, s[98:99]
	s_add_i32 m0, s78, 0x2000
	s_add_u32 s78, s84, 0x160080
	s_addc_u32 s79, s85, 0
	s_add_i32 s84, vcc_hi, s2
	global_load_lds_dwordx4 v228, s[98:99]
	s_mov_b32 m0, s84
	s_nop 0
	global_load_lds_dwordx4 v216, s[78:79]
	s_add_i32 m0, s84, 0x2000
	s_nop 0
	global_load_lds_dwordx4 v228, s[78:79]
	s_add_u32 s98, s86, 0x80
	s_addc_u32 s99, s87, 0
	s_mov_b32 m0, s60
	s_nop 0
	global_load_lds_dwordx4 v224, s[98:99]
	s_mov_b32 m0, s61
	s_nop 0
	global_load_lds_dwordx4 v226, s[98:99]
	s_waitcnt vmcnt(8)
	s_waitcnt lgkmcnt(0)
	s_barrier
	s_waitcnt lgkmcnt(0)
	v_mfma_f32_16x16x32_bf16 v[60:63], v[64:67], v[152:155], v[60:63]
	v_mfma_f32_16x16x32_bf16 v[60:63], v[72:75], v[156:159], v[60:63]
	v_mfma_f32_16x16x32_bf16 v[52:55], v[108:111], v[152:155], v[52:55]
	v_mfma_f32_16x16x32_bf16 v[52:55], v[116:119], v[156:159], v[52:55]
	v_mfma_f32_16x16x32_bf16 v[56:59], v[88:91], v[152:155], v[56:59]
	v_mfma_f32_16x16x32_bf16 v[56:59], v[96:99], v[156:159], v[56:59]
	v_mfma_f32_16x16x32_bf16 v[48:51], v[128:131], v[152:155], v[48:51]
	v_mfma_f32_16x16x32_bf16 v[48:51], v[140:143], v[156:159], v[48:51]
	v_mfma_f32_16x16x32_bf16 v[44:47], v[64:67], v[160:163], v[44:47]
	v_mfma_f32_16x16x32_bf16 v[44:47], v[72:75], v[164:167], v[44:47]
	v_mfma_f32_16x16x32_bf16 v[36:39], v[108:111], v[160:163], v[36:39]
	v_mfma_f32_16x16x32_bf16 v[36:39], v[116:119], v[164:167], v[36:39]
	v_mfma_f32_16x16x32_bf16 v[40:43], v[88:91], v[160:163], v[40:43]
	v_mfma_f32_16x16x32_bf16 v[40:43], v[96:99], v[164:167], v[40:43]
	v_mfma_f32_16x16x32_bf16 v[32:35], v[128:131], v[160:163], v[32:35]
	v_mfma_f32_16x16x32_bf16 v[32:35], v[140:143], v[164:167], v[32:35]
	v_mfma_f32_16x16x32_bf16 v[28:31], v[64:67], v[168:171], v[28:31]
	v_mfma_f32_16x16x32_bf16 v[28:31], v[72:75], v[180:183], v[28:31]
	v_mfma_f32_16x16x32_bf16 v[20:23], v[108:111], v[168:171], v[20:23]
	v_mfma_f32_16x16x32_bf16 v[20:23], v[116:119], v[180:183], v[20:23]
	v_mfma_f32_16x16x32_bf16 v[24:27], v[88:91], v[168:171], v[24:27]
	v_mfma_f32_16x16x32_bf16 v[24:27], v[96:99], v[180:183], v[24:27]
	v_mfma_f32_16x16x32_bf16 v[16:19], v[128:131], v[168:171], v[16:19]
	v_mfma_f32_16x16x32_bf16 v[16:19], v[140:143], v[180:183], v[16:19]
	v_mfma_f32_16x16x32_bf16 v[12:15], v[64:67], v[184:187], v[12:15]
	v_mfma_f32_16x16x32_bf16 v[12:15], v[72:75], v[188:191], v[12:15]
	v_mfma_f32_16x16x32_bf16 v[4:7], v[108:111], v[184:187], v[4:7]
	v_mfma_f32_16x16x32_bf16 v[4:7], v[116:119], v[188:191], v[4:7]
	v_mfma_f32_16x16x32_bf16 v[8:11], v[88:91], v[184:187], v[8:11]
	v_mfma_f32_16x16x32_bf16 v[8:11], v[96:99], v[188:191], v[8:11]
	v_mfma_f32_16x16x32_bf16 v[0:3], v[128:131], v[184:187], v[0:3]
	v_mfma_f32_16x16x32_bf16 v[0:3], v[140:143], v[188:191], v[0:3]
	s_barrier
	s_add_i32 vcc_lo, vcc_lo, 2
	s_add_u32 s81, s81, 0x100
	s_addc_u32 s96, s96, 0
	s_mov_b64 s[78:79], s[82:83]
.LBB0_1290:
	s_add_u32 s82, s78, 0x100
	s_addc_u32 s83, s79, 0
	s_add_i32 s94, 0, 0x10000
	s_cmpk_eq_i32 vcc_lo, 0x54
	s_cselect_b32 s87, s75, s83
	s_cselect_b32 s86, s74, s82
	s_cselect_b32 s85, s77, s96
	s_cselect_b32 s84, s76, s81
	s_add_i32 vcc_hi, 0, 0x14000
	ds_read_b128 v[64:67], v192
	ds_read_b128 v[72:75], v192 offset:1024
	ds_read_b128 v[88:91], v192 offset:2048
	ds_read_b128 v[96:99], v192 offset:3072
	ds_read_b128 v[108:111], v192 offset:16384
	ds_read_b128 v[116:119], v192 offset:17408
	ds_read_b128 v[128:131], v192 offset:18432
	ds_read_b128 v[140:143], v192 offset:19456
	s_add_i32 m0, s29, 0xc000
	ds_read_b128 v[152:155], v240
	ds_read_b128 v[156:159], v240 offset:1024
	ds_read_b128 v[160:163], v240 offset:2048
	ds_read_b128 v[164:167], v240 offset:3072
	ds_read_b128 v[168:171], v240 offset:4096
	ds_read_b128 v[180:183], v240 offset:5120
	ds_read_b128 v[184:187], v240 offset:6144
	ds_read_b128 v[188:191], v240 offset:7168
	global_load_lds_dwordx4 v230, s[78:79]
	s_add_i32 m0, s29, 0xe000
	s_nop 0
	global_load_lds_dwordx4 v232, s[78:79]
	s_waitcnt vmcnt(8)
	s_waitcnt lgkmcnt(0)
	s_barrier
	s_waitcnt lgkmcnt(0)
	v_mfma_f32_16x16x32_bf16 v[176:179], v[64:67], v[152:155], v[176:179]
	v_mfma_f32_16x16x32_bf16 v[176:179], v[72:75], v[156:159], v[176:179]
	v_mfma_f32_16x16x32_bf16 v[148:151], v[108:111], v[152:155], v[148:151]
	v_mfma_f32_16x16x32_bf16 v[148:151], v[116:119], v[156:159], v[148:151]
	v_mfma_f32_16x16x32_bf16 v[172:175], v[88:91], v[152:155], v[172:175]
	v_mfma_f32_16x16x32_bf16 v[172:175], v[96:99], v[156:159], v[172:175]
	v_mfma_f32_16x16x32_bf16 v[144:147], v[128:131], v[152:155], v[144:147]
	v_mfma_f32_16x16x32_bf16 v[144:147], v[140:143], v[156:159], v[144:147]
	v_mfma_f32_16x16x32_bf16 v[136:139], v[64:67], v[160:163], v[136:139]
	v_mfma_f32_16x16x32_bf16 v[136:139], v[72:75], v[164:167], v[136:139]
	v_mfma_f32_16x16x32_bf16 v[124:127], v[108:111], v[160:163], v[124:127]
	v_mfma_f32_16x16x32_bf16 v[124:127], v[116:119], v[164:167], v[124:127]
	v_mfma_f32_16x16x32_bf16 v[132:135], v[88:91], v[160:163], v[132:135]
	v_mfma_f32_16x16x32_bf16 v[132:135], v[96:99], v[164:167], v[132:135]
	v_mfma_f32_16x16x32_bf16 v[120:123], v[128:131], v[160:163], v[120:123]
	v_mfma_f32_16x16x32_bf16 v[120:123], v[140:143], v[164:167], v[120:123]
	v_mfma_f32_16x16x32_bf16 v[112:115], v[64:67], v[168:171], v[112:115]
	v_mfma_f32_16x16x32_bf16 v[112:115], v[72:75], v[180:183], v[112:115]
	v_mfma_f32_16x16x32_bf16 v[100:103], v[108:111], v[168:171], v[100:103]
	v_mfma_f32_16x16x32_bf16 v[100:103], v[116:119], v[180:183], v[100:103]
	v_mfma_f32_16x16x32_bf16 v[104:107], v[88:91], v[168:171], v[104:107]
	v_mfma_f32_16x16x32_bf16 v[104:107], v[96:99], v[180:183], v[104:107]
	v_mfma_f32_16x16x32_bf16 v[92:95], v[128:131], v[168:171], v[92:95]
	v_mfma_f32_16x16x32_bf16 v[92:95], v[140:143], v[180:183], v[92:95]
	v_mfma_f32_16x16x32_bf16 v[84:87], v[64:67], v[184:187], v[84:87]
	v_mfma_f32_16x16x32_bf16 v[84:87], v[72:75], v[188:191], v[84:87]
	v_mfma_f32_16x16x32_bf16 v[76:79], v[108:111], v[184:187], v[76:79]
	v_mfma_f32_16x16x32_bf16 v[76:79], v[116:119], v[188:191], v[76:79]
	v_mfma_f32_16x16x32_bf16 v[80:83], v[88:91], v[184:187], v[80:83]
	v_mfma_f32_16x16x32_bf16 v[80:83], v[96:99], v[188:191], v[80:83]
	v_mfma_f32_16x16x32_bf16 v[68:71], v[128:131], v[184:187], v[68:71]
	v_mfma_f32_16x16x32_bf16 v[68:71], v[140:143], v[188:191], v[68:71]
	s_barrier
	s_add_i32 s78, s94, s2
	s_mov_b32 m0, s78
	ds_read_b128 v[152:155], v240 offset:16384
	ds_read_b128 v[156:159], v240 offset:17408
	ds_read_b128 v[160:163], v240 offset:18432
	ds_read_b128 v[164:167], v240 offset:19456
	ds_read_b128 v[168:171], v240 offset:20480
	ds_read_b128 v[180:183], v240 offset:21504
	ds_read_b128 v[184:187], v240 offset:22528
	ds_read_b128 v[188:191], v240 offset:23552
	global_load_lds_dwordx4 v216, s[84:85]
	s_add_i32 m0, s78, 0x2000
	s_add_u32 s78, s84, 0x160000
	s_addc_u32 s79, s85, 0
	s_add_i32 s94, vcc_hi, s2
	global_load_lds_dwordx4 v228, s[84:85]
	s_mov_b32 m0, s94
	s_nop 0
	global_load_lds_dwordx4 v216, s[78:79]
	s_add_i32 m0, s94, 0x2000
	s_nop 0
	global_load_lds_dwordx4 v228, s[78:79]
	s_mov_b32 m0, s29
	s_nop 0
	global_load_lds_dwordx4 v224, s[86:87]
	s_mov_b32 m0, s34
	s_nop 0
	global_load_lds_dwordx4 v226, s[86:87]
	s_waitcnt vmcnt(8)
	s_waitcnt lgkmcnt(0)
	s_barrier
	s_waitcnt lgkmcnt(0)
	v_mfma_f32_16x16x32_bf16 v[60:63], v[64:67], v[152:155], v[60:63]
	v_mfma_f32_16x16x32_bf16 v[60:63], v[72:75], v[156:159], v[60:63]
	v_mfma_f32_16x16x32_bf16 v[52:55], v[108:111], v[152:155], v[52:55]
	v_mfma_f32_16x16x32_bf16 v[52:55], v[116:119], v[156:159], v[52:55]
	v_mfma_f32_16x16x32_bf16 v[56:59], v[88:91], v[152:155], v[56:59]
	v_mfma_f32_16x16x32_bf16 v[56:59], v[96:99], v[156:159], v[56:59]
	v_mfma_f32_16x16x32_bf16 v[48:51], v[128:131], v[152:155], v[48:51]
	v_mfma_f32_16x16x32_bf16 v[48:51], v[140:143], v[156:159], v[48:51]
	v_mfma_f32_16x16x32_bf16 v[44:47], v[64:67], v[160:163], v[44:47]
	v_mfma_f32_16x16x32_bf16 v[44:47], v[72:75], v[164:167], v[44:47]
	v_mfma_f32_16x16x32_bf16 v[36:39], v[108:111], v[160:163], v[36:39]
	v_mfma_f32_16x16x32_bf16 v[36:39], v[116:119], v[164:167], v[36:39]
	v_mfma_f32_16x16x32_bf16 v[40:43], v[88:91], v[160:163], v[40:43]
	v_mfma_f32_16x16x32_bf16 v[40:43], v[96:99], v[164:167], v[40:43]
	v_mfma_f32_16x16x32_bf16 v[32:35], v[128:131], v[160:163], v[32:35]
	v_mfma_f32_16x16x32_bf16 v[32:35], v[140:143], v[164:167], v[32:35]
	v_mfma_f32_16x16x32_bf16 v[28:31], v[64:67], v[168:171], v[28:31]
	v_mfma_f32_16x16x32_bf16 v[28:31], v[72:75], v[180:183], v[28:31]
	v_mfma_f32_16x16x32_bf16 v[20:23], v[108:111], v[168:171], v[20:23]
	v_mfma_f32_16x16x32_bf16 v[20:23], v[116:119], v[180:183], v[20:23]
	v_mfma_f32_16x16x32_bf16 v[24:27], v[88:91], v[168:171], v[24:27]
	v_mfma_f32_16x16x32_bf16 v[24:27], v[96:99], v[180:183], v[24:27]
	v_mfma_f32_16x16x32_bf16 v[16:19], v[128:131], v[168:171], v[16:19]
	v_mfma_f32_16x16x32_bf16 v[16:19], v[140:143], v[180:183], v[16:19]
	v_mfma_f32_16x16x32_bf16 v[12:15], v[64:67], v[184:187], v[12:15]
	v_mfma_f32_16x16x32_bf16 v[12:15], v[72:75], v[188:191], v[12:15]
	v_mfma_f32_16x16x32_bf16 v[4:7], v[108:111], v[184:187], v[4:7]
	v_mfma_f32_16x16x32_bf16 v[4:7], v[116:119], v[188:191], v[4:7]
	v_mfma_f32_16x16x32_bf16 v[8:11], v[88:91], v[184:187], v[8:11]
	v_mfma_f32_16x16x32_bf16 v[8:11], v[96:99], v[188:191], v[8:11]
	v_mfma_f32_16x16x32_bf16 v[0:3], v[128:131], v[184:187], v[0:3]
	v_mfma_f32_16x16x32_bf16 v[0:3], v[140:143], v[188:191], v[0:3]
	s_barrier
	s_add_i32 s94, 0, 0x18000
	s_add_i32 vcc_hi, 0, 0x1c000
	ds_read_b128 v[64:67], v192 offset:32768
	ds_read_b128 v[72:75], v192 offset:33792
	ds_read_b128 v[88:91], v192 offset:34816
	ds_read_b128 v[96:99], v192 offset:35840
	ds_read_b128 v[108:111], v192 offset:49152
	ds_read_b128 v[116:119], v192 offset:50176
	ds_read_b128 v[128:131], v192 offset:51200
	ds_read_b128 v[140:143], v192 offset:52224
	s_add_u32 s78, s86, 0x160000
	s_addc_u32 s79, s87, 0
	s_mov_b32 m0, s35
	ds_read_b128 v[152:155], v240 offset:32768
	ds_read_b128 v[156:159], v240 offset:33792
	ds_read_b128 v[160:163], v240 offset:34816
	ds_read_b128 v[164:167], v240 offset:35840
	ds_read_b128 v[168:171], v240 offset:36864
	ds_read_b128 v[180:183], v240 offset:37888
	ds_read_b128 v[184:187], v240 offset:38912
	ds_read_b128 v[188:191], v240 offset:39936
	global_load_lds_dwordx4 v224, s[78:79]
	s_mov_b32 m0, s38
	s_nop 0
	global_load_lds_dwordx4 v226, s[78:79]
	s_waitcnt vmcnt(8)
	s_waitcnt lgkmcnt(0)
	s_barrier
	s_waitcnt lgkmcnt(0)
	v_mfma_f32_16x16x32_bf16 v[176:179], v[64:67], v[152:155], v[176:179]
	v_mfma_f32_16x16x32_bf16 v[176:179], v[72:75], v[156:159], v[176:179]
	v_mfma_f32_16x16x32_bf16 v[148:151], v[108:111], v[152:155], v[148:151]
	v_mfma_f32_16x16x32_bf16 v[148:151], v[116:119], v[156:159], v[148:151]
	v_mfma_f32_16x16x32_bf16 v[172:175], v[88:91], v[152:155], v[172:175]
	v_mfma_f32_16x16x32_bf16 v[172:175], v[96:99], v[156:159], v[172:175]
	v_mfma_f32_16x16x32_bf16 v[144:147], v[128:131], v[152:155], v[144:147]
	v_mfma_f32_16x16x32_bf16 v[144:147], v[140:143], v[156:159], v[144:147]
	v_mfma_f32_16x16x32_bf16 v[136:139], v[64:67], v[160:163], v[136:139]
	v_mfma_f32_16x16x32_bf16 v[136:139], v[72:75], v[164:167], v[136:139]
	v_mfma_f32_16x16x32_bf16 v[124:127], v[108:111], v[160:163], v[124:127]
	v_mfma_f32_16x16x32_bf16 v[124:127], v[116:119], v[164:167], v[124:127]
	v_mfma_f32_16x16x32_bf16 v[132:135], v[88:91], v[160:163], v[132:135]
	v_mfma_f32_16x16x32_bf16 v[132:135], v[96:99], v[164:167], v[132:135]
	v_mfma_f32_16x16x32_bf16 v[120:123], v[128:131], v[160:163], v[120:123]
	v_mfma_f32_16x16x32_bf16 v[120:123], v[140:143], v[164:167], v[120:123]
	v_mfma_f32_16x16x32_bf16 v[112:115], v[64:67], v[168:171], v[112:115]
	v_mfma_f32_16x16x32_bf16 v[112:115], v[72:75], v[180:183], v[112:115]
	v_mfma_f32_16x16x32_bf16 v[100:103], v[108:111], v[168:171], v[100:103]
	v_mfma_f32_16x16x32_bf16 v[100:103], v[116:119], v[180:183], v[100:103]
	v_mfma_f32_16x16x32_bf16 v[104:107], v[88:91], v[168:171], v[104:107]
	v_mfma_f32_16x16x32_bf16 v[104:107], v[96:99], v[180:183], v[104:107]
	v_mfma_f32_16x16x32_bf16 v[92:95], v[128:131], v[168:171], v[92:95]
	v_mfma_f32_16x16x32_bf16 v[92:95], v[140:143], v[180:183], v[92:95]
	v_mfma_f32_16x16x32_bf16 v[84:87], v[64:67], v[184:187], v[84:87]
	v_mfma_f32_16x16x32_bf16 v[84:87], v[72:75], v[188:191], v[84:87]
	v_mfma_f32_16x16x32_bf16 v[76:79], v[108:111], v[184:187], v[76:79]
	v_mfma_f32_16x16x32_bf16 v[76:79], v[116:119], v[188:191], v[76:79]
	v_mfma_f32_16x16x32_bf16 v[80:83], v[88:91], v[184:187], v[80:83]
	v_mfma_f32_16x16x32_bf16 v[80:83], v[96:99], v[188:191], v[80:83]
	v_mfma_f32_16x16x32_bf16 v[68:71], v[128:131], v[184:187], v[68:71]
	v_mfma_f32_16x16x32_bf16 v[68:71], v[140:143], v[188:191], v[68:71]
	s_barrier
	s_add_i32 s78, s94, s2
	s_add_u32 s98, s84, 0x80
	s_addc_u32 s99, s85, 0
	s_mov_b32 m0, s78
	ds_read_b128 v[152:155], v240 offset:49152
	ds_read_b128 v[156:159], v240 offset:50176
	ds_read_b128 v[160:163], v240 offset:51200
	ds_read_b128 v[164:167], v240 offset:52224
	ds_read_b128 v[168:171], v240 offset:53248
	ds_read_b128 v[180:183], v240 offset:54272
	ds_read_b128 v[184:187], v240 offset:55296
	ds_read_b128 v[188:191], v240 offset:56320
	global_load_lds_dwordx4 v216, s[98:99]
	s_add_i32 m0, s78, 0x2000
	s_add_u32 s78, s84, 0x160080
	s_addc_u32 s79, s85, 0
	s_add_i32 s84, vcc_hi, s2
	global_load_lds_dwordx4 v228, s[98:99]
	s_mov_b32 m0, s84
	s_nop 0
	global_load_lds_dwordx4 v216, s[78:79]
	s_add_i32 m0, s84, 0x2000
	s_nop 0
	global_load_lds_dwordx4 v228, s[78:79]
	s_add_u32 s98, s86, 0x80
	s_addc_u32 s99, s87, 0
	s_mov_b32 m0, s60
	s_nop 0
	global_load_lds_dwordx4 v224, s[98:99]
	s_mov_b32 m0, s61
	s_nop 0
	global_load_lds_dwordx4 v226, s[98:99]
	s_waitcnt vmcnt(8)
	s_waitcnt lgkmcnt(0)
	s_barrier
	s_waitcnt lgkmcnt(0)
	v_mfma_f32_16x16x32_bf16 v[60:63], v[64:67], v[152:155], v[60:63]
	v_mfma_f32_16x16x32_bf16 v[60:63], v[72:75], v[156:159], v[60:63]
	v_mfma_f32_16x16x32_bf16 v[52:55], v[108:111], v[152:155], v[52:55]
	v_mfma_f32_16x16x32_bf16 v[52:55], v[116:119], v[156:159], v[52:55]
	v_mfma_f32_16x16x32_bf16 v[56:59], v[88:91], v[152:155], v[56:59]
	v_mfma_f32_16x16x32_bf16 v[56:59], v[96:99], v[156:159], v[56:59]
	v_mfma_f32_16x16x32_bf16 v[48:51], v[128:131], v[152:155], v[48:51]
	v_mfma_f32_16x16x32_bf16 v[48:51], v[140:143], v[156:159], v[48:51]
	v_mfma_f32_16x16x32_bf16 v[44:47], v[64:67], v[160:163], v[44:47]
	v_mfma_f32_16x16x32_bf16 v[44:47], v[72:75], v[164:167], v[44:47]
	v_mfma_f32_16x16x32_bf16 v[36:39], v[108:111], v[160:163], v[36:39]
	v_mfma_f32_16x16x32_bf16 v[36:39], v[116:119], v[164:167], v[36:39]
	v_mfma_f32_16x16x32_bf16 v[40:43], v[88:91], v[160:163], v[40:43]
	v_mfma_f32_16x16x32_bf16 v[40:43], v[96:99], v[164:167], v[40:43]
	v_mfma_f32_16x16x32_bf16 v[32:35], v[128:131], v[160:163], v[32:35]
	v_mfma_f32_16x16x32_bf16 v[32:35], v[140:143], v[164:167], v[32:35]
	v_mfma_f32_16x16x32_bf16 v[28:31], v[64:67], v[168:171], v[28:31]
	v_mfma_f32_16x16x32_bf16 v[28:31], v[72:75], v[180:183], v[28:31]
	v_mfma_f32_16x16x32_bf16 v[20:23], v[108:111], v[168:171], v[20:23]
	v_mfma_f32_16x16x32_bf16 v[20:23], v[116:119], v[180:183], v[20:23]
	v_mfma_f32_16x16x32_bf16 v[24:27], v[88:91], v[168:171], v[24:27]
	v_mfma_f32_16x16x32_bf16 v[24:27], v[96:99], v[180:183], v[24:27]
	v_mfma_f32_16x16x32_bf16 v[16:19], v[128:131], v[168:171], v[16:19]
	v_mfma_f32_16x16x32_bf16 v[16:19], v[140:143], v[180:183], v[16:19]
	v_mfma_f32_16x16x32_bf16 v[12:15], v[64:67], v[184:187], v[12:15]
	v_mfma_f32_16x16x32_bf16 v[12:15], v[72:75], v[188:191], v[12:15]
	v_mfma_f32_16x16x32_bf16 v[4:7], v[108:111], v[184:187], v[4:7]
	v_mfma_f32_16x16x32_bf16 v[4:7], v[116:119], v[188:191], v[4:7]
	v_mfma_f32_16x16x32_bf16 v[8:11], v[88:91], v[184:187], v[8:11]
	v_mfma_f32_16x16x32_bf16 v[8:11], v[96:99], v[188:191], v[8:11]
	v_mfma_f32_16x16x32_bf16 v[0:3], v[128:131], v[184:187], v[0:3]
	v_mfma_f32_16x16x32_bf16 v[0:3], v[140:143], v[188:191], v[0:3]
	s_barrier
	s_add_i32 vcc_lo, vcc_lo, 2
	s_add_u32 s81, s81, 0x100
	s_addc_u32 s96, s96, 0
	s_cmpk_gt_u32 vcc_lo, 0x55
	s_mov_b64 s[78:79], s[82:83]
	s_cbranch_scc0 .LBB0_1290
	s_and_b64 vcc, exec, s[70:71]
	s_cbranch_vccz .LBB0_1293
	s_barrier
